# c1 + attention row-max cross-half exchange via v_permlane32_swap instead of ds_bpermute; gelu -log2e factor folded into its two constants
# speedup vs baseline: 1.0079x; 1.0046x over previous
; #define LAS __attribute__((address_space(3)))
; DI float fexp2(float x) { return __builtin_amdgcn_exp2f(x); }
; DI float shx(float v, int o) { int l = (int)__builtin_amdgcn_mbcnt_hi(~0u, __builtin_amdgcn_mbcnt_lo(~0u, 0u)); asm volatile("" : "+v"(l)); return __int_as_float(__builtin_amdgcn_ds_bpermute((l ^ o) << 2, __float_as_int(v))); }
; DI f32x16 mfma32(bf16x8 a, bf16x8 b, f32x16 c) { return __builtin_amdgcn_mfma_f32_32x32x16_bf16(a, b, c, 0, 0, 0); }
;     DI void loadk(int t, bf16x8 (&kn)[4]) const { attn_load_k(P, tokbase, EIN, kcol, 1, 0, SEQ, (rsA + t) * 64 + c0, lane, kn); }
;     DI void loadv(int t, bf16x8 (&vn)[4]) const { attn_load_v(P, tokbase, EIN, vcol, 1, 0, SEQ, (rsA + t) * 64 + c0, lane, vn); }
;     DI void rest(int t, const f32x16& S, LAS unsigned char* LV, int ln, f32x16& O0, f32x16& O1, float& m_run, float& l_run) const { attn_rest(S, LV, ln, O0, O1, m_run, l_run, mask(t)); }
; DI f32x16 attn_scores(LAS unsigned char* LQ, int lane, const bf16x8 (&kf)[4]) {
;     f32x16 S;
; #pragma unroll
;     for (int i = 0; i < 16; ++i) S[i] = 0.f;
; #pragma unroll
;     for (int c = 0; c < 4; ++c) S = mfma32(kf[c], lds_r128(LQ, c * 1024 + lane * 16), S);
;     return S;
; }
; template <class MaskF>
; DI void attn_rest(const f32x16& S, LAS unsigned char* LV, int lane, f32x16& O0, f32x16& O1, float& m_run, float& l_run, const MaskF& maskf) {
;     const int h = lane >> 5;
;     float sv[16]; float mx = -1e30f;
; #pragma unroll
;     for (int r = 0; r < 16; ++r) { sv[r] = maskf((r & 3) + 8 * (r >> 2), S[r]); mx = fmaxf(mx, sv[r]); }
;     mx = fmaxf(mx, shx(mx, 32));
;     if (__builtin_amdgcn_ballot_w64(mx > m_run) != 0ull) {
;         const float mn = fmaxf(m_run, mx);
;         const float alpha = fexp2(m_run - mn);
;         m_run = mn; l_run *= alpha;
; #pragma unroll
;         for (int i = 0; i < 16; ++i) { O0[i] *= alpha; O1[i] *= alpha; }
;     }
; template <class Desc>
; DI void attn_loop(const Desc& d, int ntiles, const bf16x8 (&qf)[4], LAS unsigned char* LV, int lane, bf16_t* orow) {
;     ...
;     for (int t = 0; t + 1 < ntiles; t += 2) {
;         const f32x16 Sa = attn_scores(LQ, lane, kA);
;         d.loadk(t + 2 < tl ? t + 2 : tl, kA);
;         attn_store_v(LV, lane, vN);
;         d.loadv(t + 1, vN);
;         d.rest(t, Sa, LV, lane, O0, O1, m_run, l_run);
.LBB0_315:
	s_cmp_lt_u32 s44, 26
	s_cselect_b32 s38, 2, 4
	s_cselect_b32 s39, s48, 0xffffffe4
	s_cmp_lt_u32 s44, 18
	s_waitcnt vmcnt(11) lgkmcnt(0)
	v_mfma_f32_32x32x16_bf16 v[2:17], v[34:37], v[236:239], 0
	s_cselect_b32 s46, 0, s38
	s_cselect_b32 s38, 0, s39
	s_add_i32 s38, s38, s44
	v_lshrrev_b32_e32 v0, s46, v151
	s_lshl_b32 s38, s38, 5
	v_add3_u32 v0, s38, 64, v0
	s_waitcnt vmcnt(10) lgkmcnt(0)
	v_mfma_f32_32x32x16_bf16 v[2:17], v[26:29], v[240:243], v[2:17]
	s_lshr_b32 s47, 0x1000, s46
	v_subrev_u32_e32 v163, 64, v0
	v_add_u32_e32 v0, v163, v121
	s_add_i32 s47, s47, -1
	v_cmp_lt_i32_e32 vcc, -1, v0
	v_bfe_u32 v162, v137, 0, s46
	s_waitcnt vmcnt(9) lgkmcnt(0)
	v_mfma_f32_32x32x16_bf16 v[2:17], v[22:25], v[244:247], v[2:17]
	s_cmp_lt_u32 s44, 28
	v_add_u32_e32 v143, v125, v127
	s_waitcnt vmcnt(8) lgkmcnt(0)
	v_mfma_f32_32x32x16_bf16 v[2:17], v[18:21], v[248:251], v[2:17]
	v_min_u32_e32 v18, s47, v0
	v_cndmask_b32_e32 v0, 0, v18, vcc
	v_lshl_add_u32 v0, v0, s46, v162
	v_lshl_add_u64 v[18:19], v[46:47], 0, v[0:1]
	v_mad_u64_u32 v[20:21], s[38:39], v18, s90, v[140:141]
	s_cselect_b32 s38, 2, 4
	s_cselect_b32 s39, s48, 0xffffffe4
	s_cmp_lt_u32 s44, 20
	s_cselect_b32 s49, 0, s38
	s_cselect_b32 s38, 0, s39
	v_mad_u32_u24 v21, v19, s90, v21
	s_add_i32 s38, s38, s44
	global_load_dwordx4 v[34:37], v[20:21], off
	global_load_dwordx4 v[26:29], v[20:21], off offset:32
	global_load_dwordx4 v[22:25], v[20:21], off offset:64
	s_nop 0
	global_load_dwordx4 v[18:21], v[20:21], off offset:96
	s_waitcnt vmcnt(7)
	ds_write_b128 v143, v[96:99] offset:16384
	s_waitcnt vmcnt(6)
	ds_write_b128 v143, v[100:103] offset:17920
	s_waitcnt vmcnt(5)
	ds_write_b128 v143, v[104:107] offset:19456
	s_waitcnt vmcnt(4)
	ds_write_b128 v143, v[108:111] offset:20992
	v_lshrrev_b32_e32 v100, s49, v151
	s_lshl_b32 s52, s38, 5
	v_add3_u32 v159, s52, 32, v100
	s_lshr_b32 s45, 0x1000, s49
	v_subrev_u32_e32 v161, 64, v159
	v_or_b32_e32 v97, v161, v123
	s_add_i32 s53, s45, -1
	v_cmp_gt_i32_e64 s[38:39], 0, v161
	v_min_u32_e32 v0, s53, v97
	v_bfe_u32 v96, v137, 0, s49
	v_cndmask_b32_e64 v0, v0, 0, s[38:39]
	v_lshl_add_u32 v0, v0, s49, v96
	v_lshl_add_u64 v[84:85], v[46:47], 0, v[0:1]
	v_add_u32_e32 v0, 8, v97
	v_min_u32_e32 v88, s53, v0
	v_cmp_lt_i32_e32 vcc, -1, v0
	v_mad_u64_u32 v[86:87], s[40:41], v84, s90, v[138:139]
	s_nop 0
	v_cndmask_b32_e32 v0, 0, v88, vcc
	v_lshl_add_u32 v0, v0, s49, v96
	v_lshl_add_u64 v[88:89], v[46:47], 0, v[0:1]
	v_add_u32_e32 v0, 16, v97
	v_min_u32_e32 v92, s53, v0
	v_cmp_lt_i32_e32 vcc, -1, v0
	v_mad_u64_u32 v[90:91], s[40:41], v88, s90, v[138:139]
	s_nop 0
	v_cndmask_b32_e32 v0, 0, v92, vcc
	v_lshl_add_u32 v0, v0, s49, v96
	v_lshl_add_u64 v[92:93], v[46:47], 0, v[0:1]
	v_add_u32_e32 v0, 24, v97
	v_min_u32_e32 v97, s53, v0
	v_cmp_lt_i32_e32 vcc, -1, v0
	v_mad_u64_u32 v[94:95], s[40:41], v92, s90, v[138:139]
	s_nop 0
	v_cndmask_b32_e32 v0, 0, v97, vcc
	v_lshl_add_u32 v0, v0, s49, v96
	v_lshl_add_u64 v[96:97], v[46:47], 0, v[0:1]
	v_mad_u64_u32 v[98:99], s[40:41], v96, s90, v[138:139]
	v_mad_u32_u24 v87, v85, s90, v87
	v_mad_u32_u24 v91, v89, s90, v91
	v_mad_u32_u24 v95, v93, s90, v95
	v_mad_u32_u24 v99, v97, s90, v99
	global_load_dwordx4 v[84:87], v[86:87], off
	v_add_u32_e32 v0, s52, v100
	global_load_dwordx4 v[88:91], v[90:91], off
	v_subrev_u32_e32 v100, 64, v0
	global_load_dwordx4 v[92:95], v[94:95], off
	v_subrev_u32_e32 v101, 32, v0
	global_load_dwordx4 v[96:99], v[98:99], off
	v_cmp_lt_i32_e32 vcc, -1, v100
	v_cmp_ge_i32_e64 s[40:41], s45, v101
	s_and_b64 s[40:41], vcc, s[40:41]
	v_lshrrev_b32_e32 v164, s49, v142
	s_and_saveexec_b64 s[52:53], s[40:41]
	s_xor_b64 s[40:41], exec, s[52:53]
	s_cbranch_execz .LBB0_319
	v_sub_u32_e32 v0, v0, v164
	v_add_u32_e32 v107, v0, v114
	v_cmp_gt_u32_e32 vcc, s82, v107
	v_add_u32_e32 v0, 1, v107
	s_nop 0
	v_cndmask_b32_e32 v106, v229, v2, vcc
	v_cmp_gt_u32_e32 vcc, s82, v0
	v_add_u32_e32 v2, 2, v107
	s_nop 0
	v_cndmask_b32_e32 v105, v229, v3, vcc
	v_cmp_gt_u32_e32 vcc, s82, v2
	v_add_u32_e32 v2, 3, v107
	v_max3_f32 v0, v106, s83, v105
	v_cndmask_b32_e32 v104, v229, v4, vcc
	v_cmp_gt_u32_e32 vcc, s82, v2
	v_add_u32_e32 v2, 8, v107
	v_add_u32_e32 v3, 25, v107
	v_cndmask_b32_e32 v103, v229, v5, vcc
	v_cmp_gt_u32_e32 vcc, s82, v2
	v_add_u32_e32 v2, 9, v107
	v_max3_f32 v0, v0, v104, v103
	v_cndmask_b32_e32 v102, v229, v6, vcc
	v_cmp_gt_u32_e32 vcc, s82, v2
	v_add_u32_e32 v2, 10, v107
	v_add_u32_e32 v5, 27, v107
	v_cndmask_b32_e32 v101, v229, v7, vcc
	v_cmp_gt_u32_e32 vcc, s82, v2
	v_add_u32_e32 v2, 11, v107
	v_max3_f32 v0, v0, v102, v101
	v_cndmask_b32_e32 v100, v229, v8, vcc
	v_cmp_gt_u32_e32 vcc, s82, v2
	v_add_u32_e32 v2, 16, v107
	s_nop 0
	v_cndmask_b32_e32 v9, v229, v9, vcc
	v_cmp_gt_u32_e32 vcc, s82, v2
	v_add_u32_e32 v2, 17, v107
	v_max3_f32 v0, v0, v100, v9
	v_cndmask_b32_e32 v8, v229, v10, vcc
	v_cmp_gt_u32_e32 vcc, s82, v2
	s_nop 1
	v_cndmask_b32_e32 v7, v229, v11, vcc
	v_max3_f32 v2, v0, v8, v7
	v_add_u32_e32 v0, 18, v107
	v_cmp_gt_u32_e32 vcc, s82, v0
	v_add_u32_e32 v0, 19, v107
	v_cndmask_b32_e32 v6, v229, v12, vcc
	v_cmp_gt_u32_e32 vcc, s82, v0
	s_nop 0
	v_cndmask_b32_e32 v0, v229, v13, vcc
	v_max3_f32 v4, v2, v6, v0
	v_add_u32_e32 v2, 24, v107
	v_cmp_gt_u32_e32 vcc, s82, v2
	s_nop 0
	v_cndmask_b32_e32 v2, v229, v14, vcc
	v_cmp_gt_u32_e32 vcc, s82, v3
	s_nop 1
	v_cndmask_b32_e32 v3, v229, v15, vcc
	v_max3_f32 v10, v4, v2, v3
	v_add_u32_e32 v4, 26, v107
	v_cmp_gt_u32_e32 vcc, s82, v4
	s_nop 1
	v_cndmask_b32_e32 v4, v229, v16, vcc
	v_cmp_gt_u32_e32 vcc, s82, v5
	s_nop 1
	v_cndmask_b32_e32 v5, v229, v17, vcc
	v_max3_f32 v10, v10, v4, v5
	v_mov_b32_e32 v11, v10
	s_nop 1
	v_permlane32_swap_b32_e32 v11, v10
	s_waitcnt lgkmcnt(0)
	v_max_f32_e32 v11, v11, v11
	v_max_f32_e32 v10, v10, v11
	v_cmp_gt_f32_e32 vcc, v10, v133
	s_cbranch_vccz .LBB0_318
	v_max_f32_e32 v10, v10, v10
	v_max_f32_e32 v11, v133, v133
	v_max_f32_e32 v11, v11, v10
	v_sub_f32_e32 v10, v133, v11
	v_exp_f32_e32 v10, v10
	v_mov_b32_e32 v133, v11
	v_mul_f32_e32 v160, v160, v10
	v_pk_mul_f32 v[62:63], v[62:63], v[10:11] op_sel_hi:[1,0]
	v_pk_mul_f32 v[60:61], v[60:61], v[10:11] op_sel_hi:[1,0]
	v_pk_mul_f32 v[58:59], v[58:59], v[10:11] op_sel_hi:[1,0]
	v_pk_mul_f32 v[56:57], v[56:57], v[10:11] op_sel_hi:[1,0]
	v_pk_mul_f32 v[54:55], v[54:55], v[10:11] op_sel_hi:[1,0]
	v_pk_mul_f32 v[52:53], v[52:53], v[10:11] op_sel_hi:[1,0]
	v_pk_mul_f32 v[50:51], v[50:51], v[10:11] op_sel_hi:[1,0]
	v_pk_mul_f32 v[48:49], v[48:49], v[10:11] op_sel_hi:[1,0]
	v_pk_mul_f32 v[78:79], v[78:79], v[10:11] op_sel_hi:[1,0]
	v_pk_mul_f32 v[76:77], v[76:77], v[10:11] op_sel_hi:[1,0]
	v_pk_mul_f32 v[74:75], v[74:75], v[10:11] op_sel_hi:[1,0]
	v_pk_mul_f32 v[72:73], v[72:73], v[10:11] op_sel_hi:[1,0]
	v_pk_mul_f32 v[70:71], v[70:71], v[10:11] op_sel_hi:[1,0]
	v_pk_mul_f32 v[68:69], v[68:69], v[10:11] op_sel_hi:[1,0]
	v_pk_mul_f32 v[66:67], v[66:67], v[10:11] op_sel_hi:[1,0]
	v_pk_mul_f32 v[64:65], v[64:65], v[10:11] op_sel_hi:[1,0]

; #define LAS __attribute__((address_space(3)))
; DI float fexp2(float x) { return __builtin_amdgcn_exp2f(x); }
; DI float shx(float v, int o) { int l = (int)__builtin_amdgcn_mbcnt_hi(~0u, __builtin_amdgcn_mbcnt_lo(~0u, 0u)); asm volatile("" : "+v"(l)); return __int_as_float(__builtin_amdgcn_ds_bpermute((l ^ o) << 2, __float_as_int(v))); }
; template <class MaskF>
; DI void attn_rest(const f32x16& S, LAS unsigned char* LV, int lane, f32x16& O0, f32x16& O1, float& m_run, float& l_run, const MaskF& maskf) {
;     const int h = lane >> 5;
;     float sv[16]; float mx = -1e30f;
; #pragma unroll
;     for (int r = 0; r < 16; ++r) { sv[r] = maskf((r & 3) + 8 * (r >> 2), S[r]); mx = fmaxf(mx, sv[r]); }
;     mx = fmaxf(mx, shx(mx, 32));
;     if (__builtin_amdgcn_ballot_w64(mx > m_run) != 0ull) {
;         const float mn = fmaxf(m_run, mx);
;         const float alpha = fexp2(m_run - mn);
;         m_run = mn; l_run *= alpha;
; #pragma unroll
;         for (int i = 0; i < 16; ++i) { O0[i] *= alpha; O1[i] *= alpha; }
;     }
.LBB0_319:
	s_andn2_saveexec_b64 s[58:59], s[40:41]
	s_cbranch_execz .LBB0_323
	v_or_b32_e32 v0, v0, v114
	v_sub_u32_e32 v106, v0, v164
	v_or_b32_e32 v107, v100, v114
	v_cmp_gt_u32_e32 vcc, s82, v106
	v_cmp_gt_u32_e64 s[40:41], s45, v107
	s_and_b64 vcc, vcc, s[40:41]
	v_add_u32_e32 v0, 1, v106
	v_cndmask_b32_e32 v105, v229, v2, vcc
	v_cmp_gt_u32_e32 vcc, s82, v0
	v_or_b32_e32 v0, 1, v107
	v_cmp_gt_u32_e64 s[40:41], s45, v0
	s_and_b64 vcc, vcc, s[40:41]
	v_add_u32_e32 v2, 2, v106
	v_cndmask_b32_e32 v103, v229, v3, vcc
	v_cmp_gt_u32_e32 vcc, s82, v2
	v_or_b32_e32 v2, 2, v107
	v_cmp_gt_u32_e64 s[40:41], s45, v2
	s_and_b64 vcc, vcc, s[40:41]
	v_add_u32_e32 v2, 3, v106
	v_cndmask_b32_e32 v104, v229, v4, vcc
	v_cmp_gt_u32_e32 vcc, s82, v2
	v_or_b32_e32 v2, 3, v107
	v_cmp_gt_u32_e64 s[40:41], s45, v2
	s_and_b64 vcc, vcc, s[40:41]
	v_add_u32_e32 v2, 8, v106
	v_cndmask_b32_e32 v101, v229, v5, vcc
	v_cmp_gt_u32_e32 vcc, s82, v2
	v_add_u32_e32 v2, 8, v107
	v_cmp_gt_u32_e64 s[40:41], s45, v2
	s_and_b64 vcc, vcc, s[40:41]
	v_add_u32_e32 v2, 9, v106
	v_cndmask_b32_e32 v102, v229, v6, vcc
	v_cmp_gt_u32_e32 vcc, s82, v2
	v_add_u32_e32 v2, 9, v107
	v_cmp_gt_u32_e64 s[40:41], s45, v2
	s_and_b64 vcc, vcc, s[40:41]
	v_add_u32_e32 v2, 10, v106
	v_cndmask_b32_e32 v100, v229, v7, vcc
	v_cmp_gt_u32_e32 vcc, s82, v2
	v_add_u32_e32 v2, 10, v107
	v_cmp_gt_u32_e64 s[40:41], s45, v2
	s_and_b64 vcc, vcc, s[40:41]
	v_add_u32_e32 v2, 11, v106
	v_cndmask_b32_e32 v8, v229, v8, vcc
	v_cmp_gt_u32_e32 vcc, s82, v2
	v_add_u32_e32 v2, 11, v107
	v_cmp_gt_u32_e64 s[40:41], s45, v2
	s_and_b64 vcc, vcc, s[40:41]
	v_add_u32_e32 v2, 16, v106
	v_cndmask_b32_e32 v6, v229, v9, vcc
	v_cmp_gt_u32_e32 vcc, s82, v2
	v_add_u32_e32 v2, 16, v107
	v_cmp_gt_u32_e64 s[40:41], s45, v2
	s_and_b64 vcc, vcc, s[40:41]
	v_add_u32_e32 v2, 17, v106
	v_max3_f32 v0, v105, s83, v103
	v_cndmask_b32_e32 v7, v229, v10, vcc
	v_cmp_gt_u32_e32 vcc, s82, v2
	v_add_u32_e32 v2, 17, v107
	v_max3_f32 v0, v0, v104, v101
	v_cmp_gt_u32_e64 s[40:41], s45, v2
	v_max3_f32 v0, v0, v102, v100
	s_and_b64 vcc, vcc, s[40:41]
	v_max3_f32 v0, v0, v8, v6
	v_cndmask_b32_e32 v5, v229, v11, vcc
	v_max3_f32 v3, v0, v7, v5
	v_add_u32_e32 v0, 18, v106
	v_cmp_gt_u32_e32 vcc, s82, v0
	v_add_u32_e32 v0, 18, v107
	v_cmp_gt_u32_e64 s[40:41], s45, v0
	s_and_b64 vcc, vcc, s[40:41]
	v_add_u32_e32 v0, 19, v106
	v_cndmask_b32_e32 v2, v229, v12, vcc
	v_cmp_gt_u32_e32 vcc, s82, v0
	v_add_u32_e32 v0, 19, v107
	v_cmp_gt_u32_e64 s[40:41], s45, v0
	s_and_b64 vcc, vcc, s[40:41]
	v_cndmask_b32_e32 v0, v229, v13, vcc
	v_max3_f32 v9, v3, v2, v0
	v_add_u32_e32 v3, 24, v106
	v_cmp_gt_u32_e32 vcc, s82, v3
	v_add_u32_e32 v3, 24, v107
	v_cmp_gt_u32_e64 s[40:41], s45, v3
	s_and_b64 vcc, vcc, s[40:41]
	v_add_u32_e32 v4, 25, v106
	v_cndmask_b32_e32 v3, v229, v14, vcc
	v_cmp_gt_u32_e32 vcc, s82, v4
	v_add_u32_e32 v4, 25, v107
	v_cmp_gt_u32_e64 s[40:41], s45, v4
	s_and_b64 vcc, vcc, s[40:41]
	v_cndmask_b32_e32 v4, v229, v15, vcc
	v_max3_f32 v11, v9, v3, v4
	v_add_u32_e32 v9, 26, v106
	v_cmp_gt_u32_e32 vcc, s82, v9
	v_add_u32_e32 v9, 26, v107
	v_cmp_gt_u32_e64 s[40:41], s45, v9
	s_and_b64 vcc, vcc, s[40:41]
	v_add_u32_e32 v10, 27, v106
	v_cndmask_b32_e32 v9, v229, v16, vcc
	v_cmp_gt_u32_e32 vcc, s82, v10
	v_add_u32_e32 v10, 27, v107
	v_cmp_gt_u32_e64 s[40:41], s45, v10
	s_and_b64 vcc, vcc, s[40:41]
	v_cndmask_b32_e32 v10, v229, v17, vcc
	v_max3_f32 v11, v11, v9, v10
	v_mov_b32_e32 v12, v11
	s_nop 1
	v_permlane32_swap_b32_e32 v12, v11
	s_waitcnt lgkmcnt(0)
	v_max_f32_e32 v12, v12, v12
	v_max_f32_e32 v11, v11, v12
	v_cmp_gt_f32_e32 vcc, v11, v133
	s_cbranch_vccz .LBB0_322
	v_max_f32_e32 v11, v11, v11
	v_max_f32_e32 v12, v133, v133
	v_max_f32_e32 v11, v12, v11
	v_sub_f32_e32 v12, v133, v11
	v_exp_f32_e32 v12, v12
	v_mov_b32_e32 v133, v11
	v_mul_f32_e32 v160, v160, v12
	v_pk_mul_f32 v[62:63], v[62:63], v[12:13] op_sel_hi:[1,0]
	v_pk_mul_f32 v[60:61], v[60:61], v[12:13] op_sel_hi:[1,0]
	v_pk_mul_f32 v[58:59], v[58:59], v[12:13] op_sel_hi:[1,0]
	v_pk_mul_f32 v[56:57], v[56:57], v[12:13] op_sel_hi:[1,0]
	v_pk_mul_f32 v[54:55], v[54:55], v[12:13] op_sel_hi:[1,0]
	v_pk_mul_f32 v[52:53], v[52:53], v[12:13] op_sel_hi:[1,0]
	v_pk_mul_f32 v[50:51], v[50:51], v[12:13] op_sel_hi:[1,0]
	v_pk_mul_f32 v[48:49], v[48:49], v[12:13] op_sel_hi:[1,0]
	v_pk_mul_f32 v[78:79], v[78:79], v[12:13] op_sel_hi:[1,0]
	v_pk_mul_f32 v[76:77], v[76:77], v[12:13] op_sel_hi:[1,0]
	v_pk_mul_f32 v[74:75], v[74:75], v[12:13] op_sel_hi:[1,0]
	v_pk_mul_f32 v[72:73], v[72:73], v[12:13] op_sel_hi:[1,0]
	v_pk_mul_f32 v[70:71], v[70:71], v[12:13] op_sel_hi:[1,0]
	v_pk_mul_f32 v[68:69], v[68:69], v[12:13] op_sel_hi:[1,0]
	v_pk_mul_f32 v[66:67], v[66:67], v[12:13] op_sel_hi:[1,0]
	v_pk_mul_f32 v[64:65], v[64:65], v[12:13] op_sel_hi:[1,0]

; #define LAS __attribute__((address_space(3)))
; DI float fexp2(float x) { return __builtin_amdgcn_exp2f(x); }
; DI float shx(float v, int o) { int l = (int)__builtin_amdgcn_mbcnt_hi(~0u, __builtin_amdgcn_mbcnt_lo(~0u, 0u)); asm volatile("" : "+v"(l)); return __int_as_float(__builtin_amdgcn_ds_bpermute((l ^ o) << 2, __float_as_int(v))); }
; DI f32x16 mfma32(bf16x8 a, bf16x8 b, f32x16 c) { return __builtin_amdgcn_mfma_f32_32x32x16_bf16(a, b, c, 0, 0, 0); }
;     DI void loadk(int t, bf16x8 (&kn)[4]) const { attn_load_k(P, tokbase, EIN, kcol, 1, 0, SEQ, (rsA + t) * 64 + c0, lane, kn); }
;     DI void loadv(int t, bf16x8 (&vn)[4]) const { attn_load_v(P, tokbase, EIN, vcol, 1, 0, SEQ, (rsA + t) * 64 + c0, lane, vn); }
;     DI void rest(int t, const f32x16& S, LAS unsigned char* LV, int ln, f32x16& O0, f32x16& O1, float& m_run, float& l_run) const { attn_rest(S, LV, ln, O0, O1, m_run, l_run, mask(t)); }
; DI f32x16 attn_scores(LAS unsigned char* LQ, int lane, const bf16x8 (&kf)[4]) {
;     f32x16 S;
; #pragma unroll
;     for (int i = 0; i < 16; ++i) S[i] = 0.f;
; #pragma unroll
;     for (int c = 0; c < 4; ++c) S = mfma32(kf[c], lds_r128(LQ, c * 1024 + lane * 16), S);
;     return S;
; }
; template <class MaskF>
; DI void attn_rest(const f32x16& S, LAS unsigned char* LV, int lane, f32x16& O0, f32x16& O1, float& m_run, float& l_run, const MaskF& maskf) {
;     const int h = lane >> 5;
;     float sv[16]; float mx = -1e30f;
; #pragma unroll
;     for (int r = 0; r < 16; ++r) { sv[r] = maskf((r & 3) + 8 * (r >> 2), S[r]); mx = fmaxf(mx, sv[r]); }
;     mx = fmaxf(mx, shx(mx, 32));
;     if (__builtin_amdgcn_ballot_w64(mx > m_run) != 0ull) {
;         const float mn = fmaxf(m_run, mx);
;         const float alpha = fexp2(m_run - mn);
;         m_run = mn; l_run *= alpha;
; #pragma unroll
;         for (int i = 0; i < 16; ++i) { O0[i] *= alpha; O1[i] *= alpha; }
;     }
; template <class Desc>
; DI void attn_loop(const Desc& d, int ntiles, const bf16x8 (&qf)[4], LAS unsigned char* LV, int lane, bf16_t* orow) {
;     ...
;         const f32x16 Sb = attn_scores(LQ, lane, kB);
;         d.loadk(t + 3 < tl ? t + 3 : tl, kB);
;         attn_store_v(LV, lane, vN);
;         d.loadv(t + 2 < tl ? t + 2 : tl, vN);
;         d.rest(t + 1, Sb, LV, lane, O0, O1, m_run, l_run);
.LBB0_323:
	s_or_b64 exec, exec, s[58:59]
	s_min_u32 s40, s44, 29
	s_cmp_lt_u32 s44, 25
	s_cselect_b32 s41, 2, 4
	s_cselect_b32 s49, s48, 0xffffffe4
	s_waitcnt vmcnt(11) lgkmcnt(0)
	v_mfma_f32_32x32x16_bf16 v[2:17], v[80:83], v[236:239], 0
	s_cmp_lt_u32 s44, 17
	s_cselect_b32 s49, 0, s49
	s_cselect_b32 s41, 0, s41
	s_add_i32 s40, s40, s49
	s_lshl_b32 s40, s40, 5
	s_lshr_b32 s49, 0x1000, s41
	s_waitcnt vmcnt(10) lgkmcnt(0)
	v_mfma_f32_32x32x16_bf16 v[2:17], v[42:45], v[240:243], v[2:17]
	s_addk_i32 s40, 0x60
	s_add_i32 s49, s49, -1
	v_bfe_u32 v0, v137, 0, s41
	s_xor_b64 s[38:39], s[38:39], -1
	s_waitcnt vmcnt(9) lgkmcnt(0)
	v_mfma_f32_32x32x16_bf16 v[2:17], v[38:41], v[244:247], v[2:17]
	s_waitcnt vmcnt(8) lgkmcnt(0)
	v_mfma_f32_32x32x16_bf16 v[2:17], v[30:33], v[248:251], v[2:17]
	v_lshrrev_b32_e32 v30, s41, v151
	v_add3_u32 v30, v147, v30, s40
	v_min_u32_e32 v31, s49, v30
	v_cmp_lt_i32_e32 vcc, -1, v30
	s_nop 1
	v_cndmask_b32_e32 v30, 0, v31, vcc
	v_lshl_add_u32 v0, v30, s41, v0
	v_lshl_add_u64 v[30:31], v[46:47], 0, v[0:1]
	v_mad_u64_u32 v[32:33], s[40:41], v30, s90, v[140:141]
	v_mad_u32_u24 v33, v31, s90, v33
	global_load_dwordx4 v[80:83], v[32:33], off
	global_load_dwordx4 v[42:45], v[32:33], off offset:32
	global_load_dwordx4 v[38:41], v[32:33], off offset:64
	s_nop 0
	global_load_dwordx4 v[30:33], v[32:33], off offset:96
	s_waitcnt vmcnt(7)
	ds_write_b128 v143, v[84:87] offset:16384
	s_waitcnt vmcnt(6)
	ds_write_b128 v143, v[88:91] offset:17920
	s_waitcnt vmcnt(5)
	ds_write_b128 v143, v[92:95] offset:19456
	s_waitcnt vmcnt(4)
	ds_write_b128 v143, v[96:99] offset:20992
	v_or_b32_e32 v88, v163, v123
	v_min_u32_e32 v0, s47, v88
	v_cmp_lt_i32_e32 vcc, -1, v163
	s_nop 1
	v_cndmask_b32_e32 v0, 0, v0, vcc
	v_lshl_add_u32 v0, v0, s46, v162
	v_lshl_add_u64 v[84:85], v[46:47], 0, v[0:1]
	v_add_u32_e32 v0, 8, v88
	v_mad_u64_u32 v[86:87], s[40:41], v84, s90, v[138:139]
	v_min_u32_e32 v84, s47, v0
	v_cmp_lt_i32_e32 vcc, -1, v0
	v_mad_u32_u24 v87, v85, s90, v87
	global_load_dwordx4 v[96:99], v[86:87], off
	v_cndmask_b32_e32 v0, 0, v84, vcc
	v_lshl_add_u32 v0, v0, s46, v162
	v_lshl_add_u64 v[84:85], v[46:47], 0, v[0:1]
	v_add_u32_e32 v0, 16, v88
	v_mad_u64_u32 v[86:87], s[40:41], v84, s90, v[138:139]
	v_min_u32_e32 v84, s47, v0
	v_cmp_lt_i32_e32 vcc, -1, v0
	v_mad_u32_u24 v87, v85, s90, v87
	global_load_dwordx4 v[100:103], v[86:87], off
	v_cndmask_b32_e32 v0, 0, v84, vcc
	v_lshl_add_u32 v0, v0, s46, v162
	v_lshl_add_u64 v[84:85], v[46:47], 0, v[0:1]
	v_add_u32_e32 v0, 24, v88
	v_mad_u64_u32 v[86:87], s[40:41], v84, s90, v[138:139]
	v_min_u32_e32 v84, s47, v0
	v_cmp_lt_i32_e32 vcc, -1, v0
	v_mad_u32_u24 v87, v85, s90, v87
	global_load_dwordx4 v[104:107], v[86:87], off
	v_cndmask_b32_e32 v0, 0, v84, vcc
	v_lshl_add_u32 v0, v0, s46, v162
	v_lshl_add_u64 v[84:85], v[46:47], 0, v[0:1]
	v_mad_u64_u32 v[86:87], s[40:41], v84, s90, v[138:139]
	v_mad_u32_u24 v87, v85, s90, v87
	global_load_dwordx4 v[108:111], v[86:87], off
	v_subrev_u32_e32 v0, 32, v159
	v_cmp_ge_i32_e32 vcc, s45, v0
	s_and_b64 s[38:39], s[38:39], vcc
	s_and_saveexec_b64 s[40:41], s[38:39]
	s_xor_b64 s[38:39], exec, s[40:41]
	s_cbranch_execz .LBB0_327
	v_sub_u32_e32 v0, v159, v164
	v_add_u32_e32 v91, v0, v114
	v_cmp_gt_u32_e32 vcc, s82, v91
	v_add_u32_e32 v0, 1, v91
	s_nop 0
	v_cndmask_b32_e32 v90, v229, v2, vcc
	v_cmp_gt_u32_e32 vcc, s82, v0
	v_add_u32_e32 v2, 2, v91
	s_nop 0
	v_cndmask_b32_e32 v89, v229, v3, vcc
	v_cmp_gt_u32_e32 vcc, s82, v2
	v_add_u32_e32 v2, 3, v91
	v_max3_f32 v0, v90, s83, v89
	v_cndmask_b32_e32 v88, v229, v4, vcc
	v_cmp_gt_u32_e32 vcc, s82, v2
	v_add_u32_e32 v2, 8, v91
	v_add_u32_e32 v3, 25, v91
	v_cndmask_b32_e32 v87, v229, v5, vcc
	v_cmp_gt_u32_e32 vcc, s82, v2
	v_add_u32_e32 v2, 9, v91
	v_max3_f32 v0, v0, v88, v87
	v_cndmask_b32_e32 v86, v229, v6, vcc
	v_cmp_gt_u32_e32 vcc, s82, v2
	v_add_u32_e32 v2, 10, v91
	v_add_u32_e32 v5, 27, v91
	v_cndmask_b32_e32 v85, v229, v7, vcc
	v_cmp_gt_u32_e32 vcc, s82, v2
	v_add_u32_e32 v2, 11, v91
	v_max3_f32 v0, v0, v86, v85
	v_cndmask_b32_e32 v84, v229, v8, vcc
	v_cmp_gt_u32_e32 vcc, s82, v2
	v_add_u32_e32 v2, 16, v91
	s_nop 0
	v_cndmask_b32_e32 v9, v229, v9, vcc
	v_cmp_gt_u32_e32 vcc, s82, v2
	v_add_u32_e32 v2, 17, v91
	v_max3_f32 v0, v0, v84, v9
	v_cndmask_b32_e32 v8, v229, v10, vcc
	v_cmp_gt_u32_e32 vcc, s82, v2
	s_nop 1
	v_cndmask_b32_e32 v7, v229, v11, vcc
	v_max3_f32 v2, v0, v8, v7
	v_add_u32_e32 v0, 18, v91
	v_cmp_gt_u32_e32 vcc, s82, v0
	v_add_u32_e32 v0, 19, v91
	v_cndmask_b32_e32 v6, v229, v12, vcc
	v_cmp_gt_u32_e32 vcc, s82, v0
	s_nop 0
	v_cndmask_b32_e32 v0, v229, v13, vcc
	v_max3_f32 v4, v2, v6, v0
	v_add_u32_e32 v2, 24, v91
	v_cmp_gt_u32_e32 vcc, s82, v2
	s_nop 0
	v_cndmask_b32_e32 v2, v229, v14, vcc
	v_cmp_gt_u32_e32 vcc, s82, v3
	s_nop 1
	v_cndmask_b32_e32 v3, v229, v15, vcc
	v_max3_f32 v10, v4, v2, v3
	v_add_u32_e32 v4, 26, v91
	v_cmp_gt_u32_e32 vcc, s82, v4
	s_nop 1
	v_cndmask_b32_e32 v4, v229, v16, vcc
	v_cmp_gt_u32_e32 vcc, s82, v5
	s_nop 1
	v_cndmask_b32_e32 v5, v229, v17, vcc
	v_max3_f32 v10, v10, v4, v5
	v_mov_b32_e32 v11, v10
	s_nop 1
	v_permlane32_swap_b32_e32 v11, v10
	s_waitcnt lgkmcnt(0)
	v_max_f32_e32 v11, v11, v11
	v_max_f32_e32 v10, v10, v11
	v_cmp_gt_f32_e32 vcc, v10, v133
	s_cbranch_vccz .LBB0_326
	v_max_f32_e32 v10, v10, v10
	v_max_f32_e32 v11, v133, v133
	v_max_f32_e32 v11, v11, v10
	v_sub_f32_e32 v10, v133, v11
	v_exp_f32_e32 v10, v10
	v_mov_b32_e32 v133, v11
	v_mul_f32_e32 v165, v165, v10
	v_pk_mul_f32 v[62:63], v[62:63], v[10:11] op_sel_hi:[1,0]
	v_pk_mul_f32 v[60:61], v[60:61], v[10:11] op_sel_hi:[1,0]
	v_pk_mul_f32 v[58:59], v[58:59], v[10:11] op_sel_hi:[1,0]
	v_pk_mul_f32 v[56:57], v[56:57], v[10:11] op_sel_hi:[1,0]
	v_pk_mul_f32 v[54:55], v[54:55], v[10:11] op_sel_hi:[1,0]
	v_pk_mul_f32 v[52:53], v[52:53], v[10:11] op_sel_hi:[1,0]
	v_pk_mul_f32 v[50:51], v[50:51], v[10:11] op_sel_hi:[1,0]
	v_pk_mul_f32 v[48:49], v[48:49], v[10:11] op_sel_hi:[1,0]
	v_pk_mul_f32 v[78:79], v[78:79], v[10:11] op_sel_hi:[1,0]
	v_pk_mul_f32 v[76:77], v[76:77], v[10:11] op_sel_hi:[1,0]
	v_pk_mul_f32 v[74:75], v[74:75], v[10:11] op_sel_hi:[1,0]
	v_pk_mul_f32 v[72:73], v[72:73], v[10:11] op_sel_hi:[1,0]
	v_pk_mul_f32 v[70:71], v[70:71], v[10:11] op_sel_hi:[1,0]
	v_pk_mul_f32 v[68:69], v[68:69], v[10:11] op_sel_hi:[1,0]
	v_pk_mul_f32 v[66:67], v[66:67], v[10:11] op_sel_hi:[1,0]
	v_pk_mul_f32 v[64:65], v[64:65], v[10:11] op_sel_hi:[1,0]

; #define LAS __attribute__((address_space(3)))
; DI float fexp2(float x) { return __builtin_amdgcn_exp2f(x); }
; DI float shx(float v, int o) { int l = (int)__builtin_amdgcn_mbcnt_hi(~0u, __builtin_amdgcn_mbcnt_lo(~0u, 0u)); asm volatile("" : "+v"(l)); return __int_as_float(__builtin_amdgcn_ds_bpermute((l ^ o) << 2, __float_as_int(v))); }
; template <class MaskF>
; DI void attn_rest(const f32x16& S, LAS unsigned char* LV, int lane, f32x16& O0, f32x16& O1, float& m_run, float& l_run, const MaskF& maskf) {
;     const int h = lane >> 5;
;     float sv[16]; float mx = -1e30f;
; #pragma unroll
;     for (int r = 0; r < 16; ++r) { sv[r] = maskf((r & 3) + 8 * (r >> 2), S[r]); mx = fmaxf(mx, sv[r]); }
;     mx = fmaxf(mx, shx(mx, 32));
;     if (__builtin_amdgcn_ballot_w64(mx > m_run) != 0ull) {
;         const float mn = fmaxf(m_run, mx);
;         const float alpha = fexp2(m_run - mn);
;         m_run = mn; l_run *= alpha;
; #pragma unroll
;         for (int i = 0; i < 16; ++i) { O0[i] *= alpha; O1[i] *= alpha; }
;     }
.LBB0_327:
	s_andn2_saveexec_b64 s[40:41], s[38:39]
	s_cbranch_execz .LBB0_314
	v_or_b32_e32 v0, v159, v114
	v_sub_u32_e32 v90, v0, v164
	v_or_b32_e32 v91, v161, v114
	v_cmp_gt_u32_e32 vcc, s82, v90
	v_cmp_gt_u32_e64 s[38:39], s45, v91
	s_and_b64 vcc, vcc, s[38:39]
	v_add_u32_e32 v0, 1, v90
	v_cndmask_b32_e32 v89, v229, v2, vcc
	v_cmp_gt_u32_e32 vcc, s82, v0
	v_or_b32_e32 v0, 1, v91
	v_cmp_gt_u32_e64 s[38:39], s45, v0
	s_and_b64 vcc, vcc, s[38:39]
	v_add_u32_e32 v2, 2, v90
	v_cndmask_b32_e32 v87, v229, v3, vcc
	v_cmp_gt_u32_e32 vcc, s82, v2
	v_or_b32_e32 v2, 2, v91
	v_cmp_gt_u32_e64 s[38:39], s45, v2
	s_and_b64 vcc, vcc, s[38:39]
	v_add_u32_e32 v2, 3, v90
	v_cndmask_b32_e32 v88, v229, v4, vcc
	v_cmp_gt_u32_e32 vcc, s82, v2
	v_or_b32_e32 v2, 3, v91
	v_cmp_gt_u32_e64 s[38:39], s45, v2
	s_and_b64 vcc, vcc, s[38:39]
	v_add_u32_e32 v2, 8, v90
	v_cndmask_b32_e32 v85, v229, v5, vcc
	v_cmp_gt_u32_e32 vcc, s82, v2
	v_add_u32_e32 v2, 8, v91
	v_cmp_gt_u32_e64 s[38:39], s45, v2
	s_and_b64 vcc, vcc, s[38:39]
	v_add_u32_e32 v2, 9, v90
	v_cndmask_b32_e32 v86, v229, v6, vcc
	v_cmp_gt_u32_e32 vcc, s82, v2
	v_add_u32_e32 v2, 9, v91
	v_cmp_gt_u32_e64 s[38:39], s45, v2
	s_and_b64 vcc, vcc, s[38:39]
	v_add_u32_e32 v2, 10, v90
	v_cndmask_b32_e32 v84, v229, v7, vcc
	v_cmp_gt_u32_e32 vcc, s82, v2
	v_add_u32_e32 v2, 10, v91
	v_cmp_gt_u32_e64 s[38:39], s45, v2
	s_and_b64 vcc, vcc, s[38:39]
	v_add_u32_e32 v2, 11, v90
	v_cndmask_b32_e32 v8, v229, v8, vcc
	v_cmp_gt_u32_e32 vcc, s82, v2
	v_add_u32_e32 v2, 11, v91
	v_cmp_gt_u32_e64 s[38:39], s45, v2
	s_and_b64 vcc, vcc, s[38:39]
	v_add_u32_e32 v2, 16, v90
	v_cndmask_b32_e32 v6, v229, v9, vcc
	v_cmp_gt_u32_e32 vcc, s82, v2
	v_add_u32_e32 v2, 16, v91
	v_cmp_gt_u32_e64 s[38:39], s45, v2
	s_and_b64 vcc, vcc, s[38:39]
	v_add_u32_e32 v2, 17, v90
	v_max3_f32 v0, v89, s83, v87
	v_cndmask_b32_e32 v7, v229, v10, vcc
	v_cmp_gt_u32_e32 vcc, s82, v2
	v_add_u32_e32 v2, 17, v91
	v_max3_f32 v0, v0, v88, v85
	v_cmp_gt_u32_e64 s[38:39], s45, v2
	v_max3_f32 v0, v0, v86, v84
	s_and_b64 vcc, vcc, s[38:39]
	v_max3_f32 v0, v0, v8, v6
	v_cndmask_b32_e32 v5, v229, v11, vcc
	v_max3_f32 v3, v0, v7, v5
	v_add_u32_e32 v0, 18, v90
	v_cmp_gt_u32_e32 vcc, s82, v0
	v_add_u32_e32 v0, 18, v91
	v_cmp_gt_u32_e64 s[38:39], s45, v0
	s_and_b64 vcc, vcc, s[38:39]
	v_add_u32_e32 v0, 19, v90
	v_cndmask_b32_e32 v2, v229, v12, vcc
	v_cmp_gt_u32_e32 vcc, s82, v0
	v_add_u32_e32 v0, 19, v91
	v_cmp_gt_u32_e64 s[38:39], s45, v0
	s_and_b64 vcc, vcc, s[38:39]
	v_cndmask_b32_e32 v0, v229, v13, vcc
	v_max3_f32 v9, v3, v2, v0
	v_add_u32_e32 v3, 24, v90
	v_cmp_gt_u32_e32 vcc, s82, v3
	v_add_u32_e32 v3, 24, v91
	v_cmp_gt_u32_e64 s[38:39], s45, v3
	s_and_b64 vcc, vcc, s[38:39]
	v_add_u32_e32 v4, 25, v90
	v_cndmask_b32_e32 v3, v229, v14, vcc
	v_cmp_gt_u32_e32 vcc, s82, v4
	v_add_u32_e32 v4, 25, v91
	v_cmp_gt_u32_e64 s[38:39], s45, v4
	s_and_b64 vcc, vcc, s[38:39]
	v_cndmask_b32_e32 v4, v229, v15, vcc
	v_max3_f32 v11, v9, v3, v4
	v_add_u32_e32 v9, 26, v90
	v_cmp_gt_u32_e32 vcc, s82, v9
	v_add_u32_e32 v9, 26, v91
	v_cmp_gt_u32_e64 s[38:39], s45, v9
	s_and_b64 vcc, vcc, s[38:39]
	v_add_u32_e32 v10, 27, v90
	v_cndmask_b32_e32 v9, v229, v16, vcc
	v_cmp_gt_u32_e32 vcc, s82, v10
	v_add_u32_e32 v10, 27, v91
	v_cmp_gt_u32_e64 s[38:39], s45, v10
	s_and_b64 vcc, vcc, s[38:39]
	v_cndmask_b32_e32 v10, v229, v17, vcc
	v_max3_f32 v11, v11, v9, v10
	v_mov_b32_e32 v12, v11
	s_nop 1
	v_permlane32_swap_b32_e32 v12, v11
	s_waitcnt lgkmcnt(0)
	v_max_f32_e32 v12, v12, v12
	v_max_f32_e32 v11, v11, v12
	v_cmp_gt_f32_e32 vcc, v11, v133
	s_cbranch_vccz .LBB0_313
	v_max_f32_e32 v11, v11, v11
	v_max_f32_e32 v12, v133, v133
	v_max_f32_e32 v11, v12, v11
	v_sub_f32_e32 v12, v133, v11
	v_exp_f32_e32 v12, v12
	v_mov_b32_e32 v133, v11
	v_mul_f32_e32 v165, v165, v12
	v_pk_mul_f32 v[62:63], v[62:63], v[12:13] op_sel_hi:[1,0]
	v_pk_mul_f32 v[60:61], v[60:61], v[12:13] op_sel_hi:[1,0]
	v_pk_mul_f32 v[58:59], v[58:59], v[12:13] op_sel_hi:[1,0]
	v_pk_mul_f32 v[56:57], v[56:57], v[12:13] op_sel_hi:[1,0]
	v_pk_mul_f32 v[54:55], v[54:55], v[12:13] op_sel_hi:[1,0]
	v_pk_mul_f32 v[52:53], v[52:53], v[12:13] op_sel_hi:[1,0]
	v_pk_mul_f32 v[50:51], v[50:51], v[12:13] op_sel_hi:[1,0]
	v_pk_mul_f32 v[48:49], v[48:49], v[12:13] op_sel_hi:[1,0]
	v_pk_mul_f32 v[78:79], v[78:79], v[12:13] op_sel_hi:[1,0]
	v_pk_mul_f32 v[76:77], v[76:77], v[12:13] op_sel_hi:[1,0]
	v_pk_mul_f32 v[74:75], v[74:75], v[12:13] op_sel_hi:[1,0]
	v_pk_mul_f32 v[72:73], v[72:73], v[12:13] op_sel_hi:[1,0]
	v_pk_mul_f32 v[70:71], v[70:71], v[12:13] op_sel_hi:[1,0]
	v_pk_mul_f32 v[68:69], v[68:69], v[12:13] op_sel_hi:[1,0]
	v_pk_mul_f32 v[66:67], v[66:67], v[12:13] op_sel_hi:[1,0]
	v_pk_mul_f32 v[64:65], v[64:65], v[12:13] op_sel_hi:[1,0]
	s_branch .LBB0_313
; #define LAS __attribute__((address_space(3)))
; DI float fexp2(float x) { return __builtin_amdgcn_exp2f(x); }
; DI float shx(float v, int o) { int l = (int)__builtin_amdgcn_mbcnt_hi(~0u, __builtin_amdgcn_mbcnt_lo(~0u, 0u)); asm volatile("" : "+v"(l)); return __int_as_float(__builtin_amdgcn_ds_bpermute((l ^ o) << 2, __float_as_int(v))); }
;     DI void rest(int t, const f32x16& S, LAS unsigned char* LV, int ln, f32x16& O0, f32x16& O1, float& m_run, float& l_run) const { attn_rest(S, LV, ln, O0, O1, m_run, l_run, mask(t)); }
; template <class MaskF>
; DI void attn_rest(const f32x16& S, LAS unsigned char* LV, int lane, f32x16& O0, f32x16& O1, float& m_run, float& l_run, const MaskF& maskf) {
;     const int h = lane >> 5;
;     float sv[16]; float mx = -1e30f;
; #pragma unroll
;     for (int r = 0; r < 16; ++r) { sv[r] = maskf((r & 3) + 8 * (r >> 2), S[r]); mx = fmaxf(mx, sv[r]); }
;     mx = fmaxf(mx, shx(mx, 32));
;     if (__builtin_amdgcn_ballot_w64(mx > m_run) != 0ull) {
;         const float mn = fmaxf(m_run, mx);
;         const float alpha = fexp2(m_run - mn);
;         m_run = mn; l_run *= alpha;
; #pragma unroll
;         for (int i = 0; i < 16; ++i) { O0[i] *= alpha; O1[i] *= alpha; }
;     }
; template <class Desc>
; DI void attn_loop(const Desc& d, int ntiles, const bf16x8 (&qf)[4], LAS unsigned char* LV, int lane, bf16_t* orow) {
;     ...
;     if (ntiles & 1) {
;         const f32x16 Sa = attn_scores(LQ, lane, kA);
;         attn_store_v(LV, lane, vN);
;         d.rest(tl, Sa, LV, lane, O0, O1, m_run, l_run);
.LBB0_330:
	s_waitcnt vmcnt(7) lgkmcnt(0)
	v_mfma_f32_32x32x16_bf16 v[80:95], v[34:37], v[236:239], 0
	s_waitcnt lgkmcnt(0)
	v_mfma_f32_32x32x16_bf16 v[80:95], v[26:29], v[240:243], v[80:95]
	s_waitcnt lgkmcnt(0)
	v_mfma_f32_32x32x16_bf16 v[80:95], v[22:25], v[244:247], v[80:95]
	s_waitcnt vmcnt(3)
	ds_write_b128 v143, v[96:99] offset:16384
	s_waitcnt vmcnt(2)
	ds_write_b128 v143, v[100:103] offset:17920
	s_waitcnt vmcnt(1)
	ds_write_b128 v143, v[104:107] offset:19456
	s_waitcnt vmcnt(0)
	ds_write_b128 v143, v[108:111] offset:20992
	s_waitcnt lgkmcnt(4)
	v_mfma_f32_32x32x16_bf16 v[80:95], v[18:21], v[248:251], v[80:95]
	s_and_saveexec_b64 s[38:39], s[0:1]
	v_readlane_b32 s46, v255, 29
	s_xor_b64 s[38:39], exec, s[38:39]
	v_readlane_b32 s47, v255, 30
	s_mov_b32 s49, 0x800000
	s_cbranch_execz .LBB0_334
	s_nop 5
	v_cndmask_b32_e64 v96, v229, v80, s[4:5]
	v_cndmask_b32_e64 v81, v229, v81, s[6:7]
	v_max3_f32 v0, v96, s83, v81
	v_cndmask_b32_e64 v80, v229, v82, s[8:9]
	v_cndmask_b32_e64 v15, v229, v83, s[10:11]
	v_max3_f32 v0, v0, v80, v15
	v_cndmask_b32_e64 v14, v229, v84, s[12:13]
	v_cndmask_b32_e64 v13, v229, v85, s[14:15]
	v_max3_f32 v0, v0, v14, v13
	v_cndmask_b32_e64 v12, v229, v86, s[16:17]
	v_cndmask_b32_e64 v11, v229, v87, s[18:19]
	v_max3_f32 v0, v0, v12, v11
	v_cndmask_b32_e64 v10, v229, v88, s[20:21]
	v_cndmask_b32_e64 v9, v229, v89, s[22:23]
	v_max3_f32 v0, v0, v10, v9
	v_cndmask_b32_e64 v6, v229, v90, s[24:25]
	v_cndmask_b32_e64 v5, v229, v91, s[26:27]
	v_max3_f32 v0, v0, v6, v5
	v_cndmask_b32_e64 v4, v229, v92, s[28:29]
	v_cndmask_b32_e64 v3, v229, v93, s[30:31]
	v_max3_f32 v7, v0, v4, v3
	v_cndmask_b32_e64 v2, v229, v94, s[34:35]
	v_cndmask_b32_e64 v0, v229, v95, s[36:37]
	v_max3_f32 v7, v7, v2, v0
	v_mov_b32_e32 v8, v7
	s_nop 1
	v_permlane32_swap_b32_e32 v8, v7
	v_mov_b64_e32 v[32:33], v[64:65]
	v_mov_b64_e32 v[16:17], v[48:49]
	v_mov_b64_e32 v[34:35], v[66:67]
	v_mov_b64_e32 v[36:37], v[68:69]
	s_waitcnt lgkmcnt(0)
	v_max_f32_e32 v8, v8, v8
	v_max_f32_e32 v82, v7, v8
	v_cmp_gt_f32_e32 vcc, v82, v133
	v_mov_b32_e32 v7, v160
	v_mov_b64_e32 v[38:39], v[70:71]
	v_mov_b64_e32 v[40:41], v[72:73]
	v_mov_b64_e32 v[42:43], v[74:75]
	v_mov_b64_e32 v[44:45], v[76:77]
	v_mov_b64_e32 v[46:47], v[78:79]
	v_mov_b64_e32 v[18:19], v[50:51]
	v_mov_b64_e32 v[20:21], v[52:53]
	v_mov_b64_e32 v[22:23], v[54:55]
	v_mov_b64_e32 v[24:25], v[56:57]
	v_mov_b64_e32 v[26:27], v[58:59]
	v_mov_b64_e32 v[28:29], v[60:61]
	v_mov_b64_e32 v[30:31], v[62:63]
	v_mov_b32_e32 v8, v133
	s_cbranch_vccz .LBB0_333
	v_max_f32_e32 v7, v82, v82
	v_max_f32_e32 v8, v133, v133
	v_max_f32_e32 v8, v8, v7
	v_sub_f32_e32 v7, v133, v8
	v_exp_f32_e32 v32, v7
	s_nop 0
	v_mul_f32_e32 v7, v160, v32
	v_pk_mul_f32 v[30:31], v[62:63], v[32:33] op_sel_hi:[1,0]
	v_pk_mul_f32 v[28:29], v[60:61], v[32:33] op_sel_hi:[1,0]
	v_pk_mul_f32 v[26:27], v[58:59], v[32:33] op_sel_hi:[1,0]
	v_pk_mul_f32 v[24:25], v[56:57], v[32:33] op_sel_hi:[1,0]
	v_pk_mul_f32 v[22:23], v[54:55], v[32:33] op_sel_hi:[1,0]
	v_pk_mul_f32 v[20:21], v[52:53], v[32:33] op_sel_hi:[1,0]
	v_pk_mul_f32 v[18:19], v[50:51], v[32:33] op_sel_hi:[1,0]
	v_pk_mul_f32 v[16:17], v[48:49], v[32:33] op_sel_hi:[1,0]
	v_pk_mul_f32 v[46:47], v[78:79], v[32:33] op_sel_hi:[1,0]
	v_pk_mul_f32 v[44:45], v[76:77], v[32:33] op_sel_hi:[1,0]
	v_pk_mul_f32 v[42:43], v[74:75], v[32:33] op_sel_hi:[1,0]
	v_pk_mul_f32 v[40:41], v[72:73], v[32:33] op_sel_hi:[1,0]
	v_pk_mul_f32 v[38:39], v[70:71], v[32:33] op_sel_hi:[1,0]
	v_pk_mul_f32 v[36:37], v[68:69], v[32:33] op_sel_hi:[1,0]
	v_pk_mul_f32 v[34:35], v[66:67], v[32:33] op_sel_hi:[1,0]
	v_pk_mul_f32 v[32:33], v[64:65], v[32:33] op_sel_hi:[1,0]

; #define LAS __attribute__((address_space(3)))
; DI float fexp2(float x) { return __builtin_amdgcn_exp2f(x); }
; DI float shx(float v, int o) { int l = (int)__builtin_amdgcn_mbcnt_hi(~0u, __builtin_amdgcn_mbcnt_lo(~0u, 0u)); asm volatile("" : "+v"(l)); return __int_as_float(__builtin_amdgcn_ds_bpermute((l ^ o) << 2, __float_as_int(v))); }
;     DI void loadk(int t, bf16x8 (&kn)[4]) const { attn_load_k(P, tokbase, EIN, kcol, 1, 0, SEQ, (rsA + t) * 64 + c0, lane, kn); }
;     DI void loadv(int t, bf16x8 (&vn)[4]) const { attn_load_v(P, tokbase, EIN, vcol, 1, 0, SEQ, (rsA + t) * 64 + c0, lane, vn); }
;     DI void rest(int t, const f32x16& S, LAS unsigned char* LV, int ln, f32x16& O0, f32x16& O1, float& m_run, float& l_run) const { attn_rest(S, LV, ln, O0, O1, m_run, l_run, mask(t)); }
;     DI void loadk(int T, bf16x8 (&kn)[4]) const { const int sh = sh_of(T); attn_load_k(P, tokbase, EIN, kcol, 1 << sh, r & ((1 << sh) - 1), SEQ >> sh, m0_of(T), lane, kn); }
;     DI void loadv(int T, bf16x8 (&vn)[4]) const { const int sh = sh_of(T); attn_load_v(P, tokbase, EIN, vcol, 1 << sh, r & ((1 << sh) - 1), SEQ >> sh, m0_of(T), lane, vn); }
; template <class MaskF>
; DI void attn_rest(const f32x16& S, LAS unsigned char* LV, int lane, f32x16& O0, f32x16& O1, float& m_run, float& l_run, const MaskF& maskf) {
;     const int h = lane >> 5;
;     float sv[16]; float mx = -1e30f;
; #pragma unroll
;     for (int r = 0; r < 16; ++r) { sv[r] = maskf((r & 3) + 8 * (r >> 2), S[r]); mx = fmaxf(mx, sv[r]); }
;     mx = fmaxf(mx, shx(mx, 32));
;     if (__builtin_amdgcn_ballot_w64(mx > m_run) != 0ull) {
;         const float mn = fmaxf(m_run, mx);
;         const float alpha = fexp2(m_run - mn);
;         m_run = mn; l_run *= alpha;
; #pragma unroll
;         for (int i = 0; i < 16; ++i) { O0[i] *= alpha; O1[i] *= alpha; }
;     }
; template <class Desc>
; DI void attn_loop(const Desc& d, int ntiles, const bf16x8 (&qf)[4], LAS unsigned char* LV, int lane, bf16_t* orow) {
;     ...
;     for (int t = 0; t + 1 < ntiles; t += 2) {
;         const f32x16 Sa = attn_scores(LQ, lane, kA);
;         d.loadk(t + 2 < tl ? t + 2 : tl, kA);
;         attn_store_v(LV, lane, vN);
;         d.loadv(t + 1, vN);
;         d.rest(t, Sa, LV, lane, O0, O1, m_run, l_run);
.LBB0_347:
	s_add_i32 s38, s44, -1
	v_min_i32_e32 v0, s38, v169
	v_add_u32_e32 v0, v0, v165
	v_lshl_or_b32 v15, v0, 6, v135
	s_waitcnt vmcnt(11) lgkmcnt(0)
	v_mfma_f32_32x32x16_bf16 v[48:63], v[76:79], v[236:239], 0
	v_add_u32_e32 v0, v15, v121
	v_med3_i32 v0, v0, 0, v228
	v_or_b32_e32 v0, v138, v0
	v_add_u32_e32 v175, v125, v127
	v_add_u32_e32 v14, s44, v170
	s_waitcnt vmcnt(10) lgkmcnt(0)
	v_mfma_f32_32x32x16_bf16 v[48:63], v[72:75], v[240:243], v[48:63]
	s_waitcnt vmcnt(9) lgkmcnt(0)
	v_mfma_f32_32x32x16_bf16 v[48:63], v[68:71], v[244:247], v[48:63]
	s_waitcnt vmcnt(8) lgkmcnt(0)
	v_mfma_f32_32x32x16_bf16 v[48:63], v[64:67], v[248:251], v[48:63]
	v_mad_u64_u32 v[2:3], s[38:39], v0, s90, v[142:143]
	v_min_u32_e32 v0, 0xfff, v174
	v_mad_i32_i24 v3, v139, s90, v3
	v_or_b32_e32 v0, v138, v0
	global_load_dwordx4 v[76:79], v[2:3], off offset:1024
	global_load_dwordx4 v[72:75], v[2:3], off offset:1056
	global_load_dwordx4 v[68:71], v[2:3], off offset:1088
	global_load_dwordx4 v[64:67], v[2:3], off offset:1120
	v_mad_u64_u32 v[2:3], s[38:39], v0, s90, v[140:141]
	v_min_u32_e32 v0, 0xff7, v174
	v_add_u32_e32 v0, 8, v0
	v_lshl_add_u64 v[6:7], v[138:139], 0, v[0:1]
	v_min_u32_e32 v0, 0xfef, v174
	v_add_u32_e32 v0, 16, v0
	v_lshl_add_u64 v[10:11], v[138:139], 0, v[0:1]
	v_min_u32_e32 v0, 0xfe7, v174
	v_add_u32_e32 v0, 24, v0
	s_waitcnt vmcnt(7)
	ds_write_b128 v175, v[96:99] offset:16384
	s_waitcnt vmcnt(6)
	ds_write_b128 v175, v[100:103] offset:17920
	s_waitcnt vmcnt(5)
	ds_write_b128 v175, v[104:107] offset:19456
	s_waitcnt vmcnt(4)
	ds_write_b128 v175, v[108:111] offset:20992
	v_lshl_add_u64 v[96:97], v[138:139], 0, v[0:1]
	v_mad_u64_u32 v[8:9], s[38:39], v6, s90, v[140:141]
	v_mad_u64_u32 v[12:13], s[38:39], v10, s90, v[140:141]
	v_mad_u64_u32 v[98:99], s[38:39], v96, s90, v[140:141]
	v_mad_i32_i24 v3, v139, s90, v3
	v_mad_i32_i24 v9, v7, s90, v9
	v_mad_i32_i24 v13, v11, s90, v13
	v_mad_i32_i24 v99, v97, s90, v99
	global_load_dwordx4 v[2:5], v[2:3], off offset:2048
	ds_read2_b32 v[100:101], v173 offset1:1
	global_load_dwordx4 v[6:9], v[8:9], off offset:2048
	v_add_u32_e32 v0, -7, v14
	global_load_dwordx4 v[10:13], v[12:13], off offset:2048
	v_cmp_ge_u32_e32 vcc, v0, v163
	global_load_dwordx4 v[96:99], v[98:99], off offset:2048
	v_cmp_lt_u32_e64 s[38:39], v0, v137
	s_and_b64 vcc, vcc, s[38:39]
	v_cndmask_b32_e32 v102, v230, v171, vcc
	v_cmp_gt_u32_e32 vcc, 16, v102
	s_waitcnt lgkmcnt(0)
	v_add_f32_e32 v0, v48, v100
	v_cndmask_b32_e32 v48, v229, v0, vcc
	v_add_u32_e32 v0, 1, v102
	v_cmp_gt_u32_e32 vcc, 16, v0
	v_add_f32_e32 v0, v49, v101
	ds_read2_b32 v[100:101], v173 offset0:2 offset1:3
	v_add_u32_e32 v49, 2, v102
	v_cndmask_b32_e32 v0, v229, v0, vcc
	v_cmp_gt_u32_e32 vcc, 16, v49
	v_max3_f32 v103, v48, s83, v0
	s_waitcnt lgkmcnt(0)
	v_add_f32_e32 v49, v50, v100
	v_cndmask_b32_e32 v50, v229, v49, vcc
	v_add_u32_e32 v49, 3, v102
	v_cmp_gt_u32_e32 vcc, 16, v49
	v_add_f32_e32 v49, v51, v101
	ds_read2_b32 v[100:101], v173 offset0:8 offset1:9
	v_add_u32_e32 v51, 8, v102
	v_cndmask_b32_e32 v49, v229, v49, vcc
	v_cmp_gt_u32_e32 vcc, 16, v51
	v_max3_f32 v103, v103, v50, v49
	s_waitcnt lgkmcnt(0)
	v_add_f32_e32 v51, v52, v100
	v_cndmask_b32_e32 v52, v229, v51, vcc
	v_add_u32_e32 v51, 9, v102
	v_cmp_gt_u32_e32 vcc, 16, v51
	v_add_f32_e32 v51, v53, v101
	ds_read2_b32 v[100:101], v173 offset0:10 offset1:11
	v_add_u32_e32 v53, 10, v102
	v_cndmask_b32_e32 v51, v229, v51, vcc
	v_cmp_gt_u32_e32 vcc, 16, v53
	v_max3_f32 v103, v103, v52, v51
	s_waitcnt lgkmcnt(0)
	v_add_f32_e32 v53, v54, v100
	v_add_u32_e32 v54, 11, v102
	v_cndmask_b32_e32 v53, v229, v53, vcc
	v_cmp_gt_u32_e32 vcc, 16, v54
	v_add_f32_e32 v54, v55, v101
	ds_read2_b32 v[100:101], v173 offset0:16 offset1:17
	v_cndmask_b32_e32 v54, v229, v54, vcc
	v_cmp_lt_u32_e32 vcc, s54, v102
	v_max3_f32 v103, v103, v53, v54
	s_waitcnt lgkmcnt(0)
	v_add_f32_e32 v55, v56, v100
	v_cndmask_b32_e32 v56, v229, v55, vcc
	v_add_u32_e32 v55, 17, v102
	v_cmp_gt_u32_e32 vcc, 16, v55
	v_add_f32_e32 v55, v57, v101
	ds_read2_b32 v[100:101], v173 offset0:18 offset1:19
	v_add_u32_e32 v57, 18, v102
	v_cndmask_b32_e32 v55, v229, v55, vcc
	v_cmp_gt_u32_e32 vcc, 16, v57
	v_max3_f32 v103, v103, v56, v55
	s_waitcnt lgkmcnt(0)
	v_add_f32_e32 v57, v58, v100
	v_cndmask_b32_e32 v58, v229, v57, vcc
	v_add_u32_e32 v57, 19, v102
	v_cmp_gt_u32_e32 vcc, 16, v57
	v_add_f32_e32 v57, v59, v101
	ds_read2_b32 v[100:101], v173 offset0:24 offset1:25
	v_add_u32_e32 v59, 24, v102
	v_cndmask_b32_e32 v57, v229, v57, vcc
	v_cmp_gt_u32_e32 vcc, 16, v59
	v_max3_f32 v103, v103, v58, v57
	s_waitcnt lgkmcnt(0)
	v_add_f32_e32 v59, v60, v100
	v_add_u32_e32 v60, 25, v102
	v_cndmask_b32_e32 v59, v229, v59, vcc
	v_cmp_gt_u32_e32 vcc, 16, v60
	v_add_f32_e32 v60, v61, v101
	ds_read2_b32 v[100:101], v173 offset0:26 offset1:27
	v_add_u32_e32 v61, 26, v102
	v_cndmask_b32_e32 v60, v229, v60, vcc
	v_cmp_gt_u32_e32 vcc, 16, v61
	v_max3_f32 v103, v103, v59, v60
	s_waitcnt lgkmcnt(0)
	v_add_f32_e32 v61, v62, v100
	v_add_u32_e32 v62, 27, v102
	v_cndmask_b32_e32 v61, v229, v61, vcc
	v_cmp_gt_u32_e32 vcc, 16, v62
	v_add_f32_e32 v62, v63, v101
	s_nop 0
	v_cndmask_b32_e32 v62, v229, v62, vcc
	v_max3_f32 v63, v103, v61, v62
	v_mov_b32_e32 v100, v63
	s_nop 1
	v_permlane32_swap_b32_e32 v100, v63
	s_waitcnt lgkmcnt(0)
	v_max_f32_e32 v100, v100, v100
	v_max_f32_e32 v63, v63, v100
	v_cmp_gt_f32_e32 vcc, v63, v133
	s_cbranch_vccz .LBB0_349
	v_max_f32_e32 v63, v63, v63
	v_max_f32_e32 v100, v133, v133
	v_max_f32_e32 v63, v100, v63
	v_sub_f32_e32 v100, v133, v63
	v_exp_f32_e32 v100, v100
	v_mov_b32_e32 v133, v63
	v_mul_f32_e32 v159, v159, v100
	v_pk_mul_f32 v[30:31], v[30:31], v[100:101] op_sel_hi:[1,0]
	v_pk_mul_f32 v[28:29], v[28:29], v[100:101] op_sel_hi:[1,0]
	v_pk_mul_f32 v[26:27], v[26:27], v[100:101] op_sel_hi:[1,0]
	v_pk_mul_f32 v[24:25], v[24:25], v[100:101] op_sel_hi:[1,0]
	v_pk_mul_f32 v[22:23], v[22:23], v[100:101] op_sel_hi:[1,0]
	v_pk_mul_f32 v[20:21], v[20:21], v[100:101] op_sel_hi:[1,0]
	v_pk_mul_f32 v[18:19], v[18:19], v[100:101] op_sel_hi:[1,0]
	v_pk_mul_f32 v[16:17], v[16:17], v[100:101] op_sel_hi:[1,0]
	v_pk_mul_f32 v[46:47], v[46:47], v[100:101] op_sel_hi:[1,0]
	v_pk_mul_f32 v[44:45], v[44:45], v[100:101] op_sel_hi:[1,0]
	v_pk_mul_f32 v[42:43], v[42:43], v[100:101] op_sel_hi:[1,0]
	v_pk_mul_f32 v[40:41], v[40:41], v[100:101] op_sel_hi:[1,0]
	v_pk_mul_f32 v[38:39], v[38:39], v[100:101] op_sel_hi:[1,0]
	v_pk_mul_f32 v[36:37], v[36:37], v[100:101] op_sel_hi:[1,0]
	v_pk_mul_f32 v[34:35], v[34:35], v[100:101] op_sel_hi:[1,0]
	v_pk_mul_f32 v[32:33], v[32:33], v[100:101] op_sel_hi:[1,0]
; DI float fexp2(float x) { return __builtin_amdgcn_exp2f(x); }
; DI s16x4 lds_tr(LAS unsigned char* L, int off) { return __builtin_amdgcn_ds_read_tr16_b64_v4i16((LAS s16x4*)(L + off)); }
; DI bf16x8 cat4(s16x4 lo, s16x4 hi) { return __builtin_shufflevector(lo, hi, 0, 1, 2, 3, 4, 5, 6, 7); }
; DI f32x16 mfma32(bf16x8 a, bf16x8 b, f32x16 c) { return __builtin_amdgcn_mfma_f32_32x32x16_bf16(a, b, c, 0, 0, 0); }
; DI bf16x8 pack8(const float* v) { u32x4 w; w.x = pack_bf16(v[0], v[1]); w.y = pack_bf16(v[2], v[3]); w.z = pack_bf16(v[4], v[5]); w.w = pack_bf16(v[6], v[7]); return __builtin_bit_cast(bf16x8, w); }
;     DI void loadk(int t, bf16x8 (&kn)[4]) const { attn_load_k(P, tokbase, EIN, kcol, 1, 0, SEQ, (rsA + t) * 64 + c0, lane, kn); }
;     DI void loadv(int t, bf16x8 (&vn)[4]) const { attn_load_v(P, tokbase, EIN, vcol, 1, 0, SEQ, (rsA + t) * 64 + c0, lane, vn); }
;     DI void rest(int t, const f32x16& S, LAS unsigned char* LV, int ln, f32x16& O0, f32x16& O1, float& m_run, float& l_run) const { attn_rest(S, LV, ln, O0, O1, m_run, l_run, mask(t)); }
; template <class MaskF>
; DI void attn_rest(const f32x16& S, LAS unsigned char* LV, int lane, f32x16& O0, f32x16& O1, float& m_run, float& l_run, const MaskF& maskf) {
;     ...
;     float ps = 0.f;
; #pragma unroll
;     for (int r = 0; r < 16; ++r) { const float p = fexp2(sv[r] - m_run); sv[r] = p; ps += p; }
;     l_run += ps;
;     const int i16 = lane & 15, q4 = i16 >> 2, p4 = i16 & 3, blk = (lane >> 4) & 1;
; #pragma unroll
;     for (int s = 0; s < 2; ++s) {
;         const bf16x8 pf = pack8(&sv[8 * s]);
;         const int r0 = 16 * s + 4 * h + q4, cb = 2 * (16 * blk + 4 * p4);
;         const s16x4 lo0 = lds_tr(LV, r0 * ATT_RSV + cb), hi0 = lds_tr(LV, (r0 + 8) * ATT_RSV + cb);
;         const s16x4 lo1 = lds_tr(LV, r0 * ATT_RSV + 64 + cb), hi1 = lds_tr(LV, (r0 + 8) * ATT_RSV + 64 + cb);
;         O0 = mfma32(cat4(lo0, hi0), pf, O0);
;         O1 = mfma32(cat4(lo1, hi1), pf, O1);
;     }
; template <class Desc>
; DI void attn_loop(const Desc& d, int ntiles, const bf16x8 (&qf)[4], LAS unsigned char* LV, int lane, bf16_t* orow) {
;     ...
;         const f32x16 Sb = attn_scores(LQ, lane, kB);
;         d.loadk(t + 3 < tl ? t + 3 : tl, kB);
;         attn_store_v(LV, lane, vN);
;         d.loadv(t + 2 < tl ? t + 2 : tl, vN);
;         d.rest(t + 1, Sb, LV, lane, O0, O1, m_run, l_run);
.LBB0_349:
	v_add_u32_e32 v176, -6, v14
	v_sub_f32_e32 v14, v48, v133
	v_exp_f32_e32 v14, v14
	v_sub_f32_e32 v0, v0, v133
	v_exp_f32_e32 v0, v0
	v_sub_f32_e32 v50, v50, v133
	v_exp_f32_e32 v50, v50
	v_sub_f32_e32 v49, v49, v133
	v_exp_f32_e32 v49, v49
	v_sub_f32_e32 v52, v52, v133
	v_add_f32_e32 v48, 0, v14
	v_exp_f32_e32 v52, v52
	v_sub_f32_e32 v51, v51, v133
	v_add_f32_e32 v48, v0, v48
	v_exp_f32_e32 v51, v51
	v_sub_f32_e32 v53, v53, v133
	v_add_f32_e32 v48, v50, v48
	v_exp_f32_e32 v53, v53
	v_sub_f32_e32 v54, v54, v133
	v_add_f32_e32 v48, v49, v48
	v_exp_f32_e32 v54, v54
	v_sub_f32_e32 v56, v56, v133
	v_add_f32_e32 v48, v52, v48
	v_exp_f32_e32 v63, v56
	v_sub_f32_e32 v55, v55, v133
	v_add_f32_e32 v48, v51, v48
	v_exp_f32_e32 v100, v55
	v_sub_f32_e32 v55, v58, v133
	v_add_f32_e32 v48, v53, v48
	v_exp_f32_e32 v101, v55
	v_sub_f32_e32 v55, v57, v133
	v_add_f32_e32 v48, v54, v48
	v_exp_f32_e32 v102, v55
	v_sub_f32_e32 v55, v59, v133
	v_add_f32_e32 v48, v63, v48
	v_exp_f32_e32 v103, v55
	v_sub_f32_e32 v55, v60, v133
	v_add_f32_e32 v48, v100, v48
	v_exp_f32_e32 v60, v55
	v_sub_f32_e32 v55, v61, v133
	v_add_f32_e32 v48, v101, v48
	v_exp_f32_e32 v61, v55
	v_sub_f32_e32 v55, v62, v133
	v_add_f32_e32 v48, v102, v48
	v_exp_f32_e32 v62, v55
	v_add_f32_e32 v48, v103, v48
	v_add_f32_e32 v48, v60, v48
	v_add_f32_e32 v48, v61, v48
	v_add_f32_e32 v48, v62, v48
	v_add_f32_e32 v159, v159, v48
	v_cvt_pk_bf16_f32 v48, v14, v0
	v_add_u32_e32 v14, v144, v145
	v_cvt_pk_bf16_f32 v49, v50, v49
	v_cvt_pk_bf16_f32 v50, v52, v51
	v_cvt_pk_bf16_f32 v51, v53, v54
	ds_read_b64_tr_b16 v[52:53], v14 offset:16384
	v_add_u32_e32 v0, v146, v129
	ds_read_b64_tr_b16 v[54:55], v0 offset:17920
	ds_read_b64_tr_b16 v[56:57], v0 offset:16448
	ds_read_b64_tr_b16 v[58:59], v0 offset:17984
	s_waitcnt lgkmcnt(2)
	v_mfma_f32_32x32x16_bf16 v[16:31], v[52:55], v[48:51], v[16:31]
	v_cmp_ge_u32_e32 vcc, v176, v163
	s_waitcnt lgkmcnt(0)
	v_mfma_f32_32x32x16_bf16 v[32:47], v[56:59], v[48:51], v[32:47]
	ds_read_b64_tr_b16 v[52:53], v14 offset:19456
	ds_read_b64_tr_b16 v[54:55], v0 offset:20992
	ds_read_b64_tr_b16 v[56:57], v0 offset:19520
	ds_read_b64_tr_b16 v[58:59], v0 offset:21056
	v_cvt_pk_bf16_f32 v48, v63, v100
	v_cvt_pk_bf16_f32 v49, v101, v102
	v_cvt_pk_bf16_f32 v50, v103, v60
	v_cvt_pk_bf16_f32 v51, v61, v62
	s_waitcnt lgkmcnt(2)
	s_nop 0
	v_mfma_f32_32x32x16_bf16 v[16:31], v[52:55], v[48:51], v[16:31]
	s_waitcnt lgkmcnt(0)
	v_mfma_f32_32x32x16_bf16 v[32:47], v[56:59], v[48:51], v[32:47]
	s_waitcnt vmcnt(8) lgkmcnt(0)
	v_mfma_f32_32x32x16_bf16 v[48:63], v[92:95], v[236:239], 0
	s_waitcnt lgkmcnt(0)
	v_mfma_f32_32x32x16_bf16 v[48:63], v[88:91], v[240:243], v[48:63]
	s_waitcnt lgkmcnt(0)
	v_mfma_f32_32x32x16_bf16 v[48:63], v[84:87], v[244:247], v[48:63]
	s_waitcnt lgkmcnt(0)
	v_mfma_f32_32x32x16_bf16 v[48:63], v[80:83], v[248:251], v[48:63]
	v_min_i32_e32 v80, s44, v169
	v_add_u32_e32 v80, v80, v165
	v_lshl_add_u32 v80, v80, 6, v172
	v_med3_i32 v80, v80, 0, v228
	v_or_b32_e32 v80, v138, v80
	v_mad_u64_u32 v[80:81], s[38:39], v80, s90, v[142:143]
	v_mad_i32_i24 v81, v139, s90, v81
	global_load_dwordx4 v[92:95], v[80:81], off offset:1024
	global_load_dwordx4 v[88:91], v[80:81], off offset:1056
	global_load_dwordx4 v[84:87], v[80:81], off offset:1088
	s_nop 0
	global_load_dwordx4 v[80:83], v[80:81], off offset:1120
	s_waitcnt vmcnt(7)
	ds_write_b128 v175, v[2:5] offset:16384
	s_waitcnt vmcnt(6)
	ds_write_b128 v175, v[6:9] offset:17920
	s_waitcnt vmcnt(5)
	ds_write_b128 v175, v[10:13] offset:19456
	s_waitcnt vmcnt(4)
	ds_write_b128 v175, v[96:99] offset:20992
	v_or_b32_e32 v4, v15, v123
	v_med3_i32 v2, v4, 0, v228
	v_or_b32_e32 v2, v138, v2
	v_mad_u64_u32 v[2:3], s[38:39], v2, s90, v[140:141]
	v_mad_i32_i24 v3, v139, s90, v3
	global_load_dwordx4 v[96:99], v[2:3], off offset:2048
	v_add_u32_e32 v2, 8, v4
	v_med3_i32 v2, v2, 0, v228
	v_or_b32_e32 v2, v138, v2
	v_mad_u64_u32 v[2:3], s[38:39], v2, s90, v[140:141]
	v_mad_i32_i24 v3, v139, s90, v3
	global_load_dwordx4 v[100:103], v[2:3], off offset:2048
	v_add_u32_e32 v2, 16, v4
	v_med3_i32 v2, v2, 0, v228
	v_or_b32_e32 v2, v138, v2
	v_mad_u64_u32 v[2:3], s[38:39], v2, s90, v[140:141]
	v_mad_i32_i24 v3, v139, s90, v3
	global_load_dwordx4 v[104:107], v[2:3], off offset:2048
	v_add_u32_e32 v2, 24, v4
	v_med3_i32 v2, v2, 0, v228
	v_or_b32_e32 v2, v138, v2
	v_mad_u64_u32 v[2:3], s[38:39], v2, s90, v[140:141]
	v_mad_i32_i24 v3, v139, s90, v3
	global_load_dwordx4 v[108:111], v[2:3], off offset:2048
	ds_read2_b32 v[4:5], v173 offset0:31 offset1:32
	ds_read2_b32 v[6:7], v173 offset0:33 offset1:34
	ds_read2_b32 v[12:13], v173 offset0:47 offset1:48
	v_cmp_lt_u32_e64 s[38:39], v176, v137
	s_and_b64 vcc, vcc, s[38:39]
	v_cndmask_b32_e32 v175, v230, v171, vcc
	v_cmp_gt_u32_e32 vcc, 16, v175
	s_waitcnt lgkmcnt(2)
; #define LAS __attribute__((address_space(3)))
; DI float fexp2(float x) { return __builtin_amdgcn_exp2f(x); }
; DI float shx(float v, int o) { int l = (int)__builtin_amdgcn_mbcnt_hi(~0u, __builtin_amdgcn_mbcnt_lo(~0u, 0u)); asm volatile("" : "+v"(l)); return __int_as_float(__builtin_amdgcn_ds_bpermute((l ^ o) << 2, __float_as_int(v))); }
; template <class MaskF>
; DI void attn_rest(const f32x16& S, LAS unsigned char* LV, int lane, f32x16& O0, f32x16& O1, float& m_run, float& l_run, const MaskF& maskf) {
;     const int h = lane >> 5;
;     float sv[16]; float mx = -1e30f;
; #pragma unroll
;     for (int r = 0; r < 16; ++r) { sv[r] = maskf((r & 3) + 8 * (r >> 2), S[r]); mx = fmaxf(mx, sv[r]); }
;     mx = fmaxf(mx, shx(mx, 32));
;     if (__builtin_amdgcn_ballot_w64(mx > m_run) != 0ull) {
;         const float mn = fmaxf(m_run, mx);
;         const float alpha = fexp2(m_run - mn);
;         m_run = mn; l_run *= alpha;
; #pragma unroll
;         for (int i = 0; i < 16; ++i) { O0[i] *= alpha; O1[i] *= alpha; }
;     }
	v_add_f32_e32 v2, v48, v4
	v_add_u32_e32 v4, 2, v175
	v_cndmask_b32_e32 v3, v229, v2, vcc
	v_add_u32_e32 v2, 1, v175
	v_cmp_gt_u32_e32 vcc, 16, v2
	v_add_f32_e32 v2, v49, v5
	ds_read2_b32 v[48:49], v173 offset0:49 offset1:50
	v_cndmask_b32_e32 v2, v229, v2, vcc
	v_cmp_gt_u32_e32 vcc, 16, v4
	s_waitcnt lgkmcnt(2)
	v_add_f32_e32 v4, v50, v6
	v_max3_f32 v8, v3, s83, v2
	v_cndmask_b32_e32 v5, v229, v4, vcc
	v_add_u32_e32 v4, 3, v175
	v_cmp_gt_u32_e32 vcc, 16, v4
	v_add_f32_e32 v4, v51, v7
	v_add_u32_e32 v6, 8, v175
	v_cndmask_b32_e32 v4, v229, v4, vcc
	v_max3_f32 v10, v8, v5, v4
	ds_read2_b32 v[8:9], v173 offset0:39 offset1:40
	v_cmp_gt_u32_e32 vcc, 16, v6
	v_add_u32_e32 v11, 10, v175
	s_waitcnt lgkmcnt(0)
	v_add_f32_e32 v6, v52, v8
	v_cndmask_b32_e32 v7, v229, v6, vcc
	v_add_u32_e32 v6, 9, v175
	v_cmp_gt_u32_e32 vcc, 16, v6
	v_add_f32_e32 v6, v53, v9
	ds_read2_b32 v[8:9], v173 offset0:41 offset1:42
	v_cndmask_b32_e32 v6, v229, v6, vcc
	v_cmp_gt_u32_e32 vcc, 16, v11
	v_add_u32_e32 v11, 11, v175
	v_max3_f32 v10, v10, v7, v6
	s_waitcnt lgkmcnt(0)
	v_add_f32_e32 v8, v54, v8
	v_cndmask_b32_e32 v8, v229, v8, vcc
	v_cmp_gt_u32_e32 vcc, 16, v11
	v_add_f32_e32 v9, v55, v9
	s_nop 0
	v_cndmask_b32_e32 v9, v229, v9, vcc
	v_max3_f32 v15, v10, v8, v9
	v_cmp_lt_u32_e32 vcc, s54, v175
	v_add_f32_e32 v10, v56, v12
	v_add_u32_e32 v12, 18, v175
	v_cndmask_b32_e32 v11, v229, v10, vcc
	v_add_u32_e32 v10, 17, v175
	v_cmp_gt_u32_e32 vcc, 16, v10
	v_add_f32_e32 v10, v57, v13
	s_nop 0
	v_cndmask_b32_e32 v10, v229, v10, vcc
	v_cmp_gt_u32_e32 vcc, 16, v12
	v_add_f32_e32 v12, v58, v48
	v_max3_f32 v15, v15, v11, v10
	v_cndmask_b32_e32 v13, v229, v12, vcc
	v_add_u32_e32 v12, 19, v175
	v_cmp_gt_u32_e32 vcc, 16, v12
	v_add_f32_e32 v12, v59, v49
	ds_read2_b32 v[48:49], v173 offset0:55 offset1:56
	v_cndmask_b32_e32 v12, v229, v12, vcc
	v_max3_f32 v50, v15, v13, v12
	v_add_u32_e32 v15, 24, v175
	v_cmp_gt_u32_e32 vcc, 16, v15
	s_waitcnt lgkmcnt(0)
	v_add_f32_e32 v15, v60, v48
	v_add_u32_e32 v48, 25, v175
	v_cndmask_b32_e32 v15, v229, v15, vcc
	v_cmp_gt_u32_e32 vcc, 16, v48
	v_add_f32_e32 v48, v61, v49
	v_add_u32_e32 v49, 26, v175
	v_cndmask_b32_e32 v48, v229, v48, vcc
	v_max3_f32 v52, v50, v15, v48
	ds_read2_b32 v[50:51], v173 offset0:57 offset1:58
	v_cmp_gt_u32_e32 vcc, 16, v49
	s_waitcnt lgkmcnt(0)
	v_add_f32_e32 v49, v62, v50
	v_add_u32_e32 v50, 27, v175
	v_cndmask_b32_e32 v49, v229, v49, vcc
	v_cmp_gt_u32_e32 vcc, 16, v50
	v_add_f32_e32 v50, v63, v51
	s_nop 0
	v_cndmask_b32_e32 v50, v229, v50, vcc
	v_max3_f32 v51, v52, v49, v50
	s_nop 0
	v_mov_b32_e32 v52, v51
	s_nop 1
	v_permlane32_swap_b32_e32 v52, v51
	s_waitcnt lgkmcnt(0)
	v_max_f32_e32 v52, v52, v52
	v_max_f32_e32 v51, v51, v52
	v_cmp_gt_f32_e32 vcc, v51, v133
	s_cbranch_vccz .LBB0_346
	v_max_f32_e32 v51, v51, v51
	v_max_f32_e32 v52, v133, v133
	v_max_f32_e32 v51, v52, v51
	v_sub_f32_e32 v52, v133, v51
	v_exp_f32_e32 v52, v52
	v_mov_b32_e32 v133, v51
	v_mul_f32_e32 v159, v159, v52
	v_pk_mul_f32 v[30:31], v[30:31], v[52:53] op_sel_hi:[1,0]
	v_pk_mul_f32 v[28:29], v[28:29], v[52:53] op_sel_hi:[1,0]
	v_pk_mul_f32 v[26:27], v[26:27], v[52:53] op_sel_hi:[1,0]
	v_pk_mul_f32 v[24:25], v[24:25], v[52:53] op_sel_hi:[1,0]
	v_pk_mul_f32 v[22:23], v[22:23], v[52:53] op_sel_hi:[1,0]
	v_pk_mul_f32 v[20:21], v[20:21], v[52:53] op_sel_hi:[1,0]
	v_pk_mul_f32 v[18:19], v[18:19], v[52:53] op_sel_hi:[1,0]
	v_pk_mul_f32 v[16:17], v[16:17], v[52:53] op_sel_hi:[1,0]
	v_pk_mul_f32 v[46:47], v[46:47], v[52:53] op_sel_hi:[1,0]
	v_pk_mul_f32 v[44:45], v[44:45], v[52:53] op_sel_hi:[1,0]
	v_pk_mul_f32 v[42:43], v[42:43], v[52:53] op_sel_hi:[1,0]
	v_pk_mul_f32 v[40:41], v[40:41], v[52:53] op_sel_hi:[1,0]
	v_pk_mul_f32 v[38:39], v[38:39], v[52:53] op_sel_hi:[1,0]
	v_pk_mul_f32 v[36:37], v[36:37], v[52:53] op_sel_hi:[1,0]
	v_pk_mul_f32 v[34:35], v[34:35], v[52:53] op_sel_hi:[1,0]
	v_pk_mul_f32 v[32:33], v[32:33], v[52:53] op_sel_hi:[1,0]
	s_branch .LBB0_346

; #define LAS __attribute__((address_space(3)))
; DI float fexp2(float x) { return __builtin_amdgcn_exp2f(x); }
; DI float shx(float v, int o) { int l = (int)__builtin_amdgcn_mbcnt_hi(~0u, __builtin_amdgcn_mbcnt_lo(~0u, 0u)); asm volatile("" : "+v"(l)); return __int_as_float(__builtin_amdgcn_ds_bpermute((l ^ o) << 2, __float_as_int(v))); }
;     DI void rest(int t, const f32x16& S, LAS unsigned char* LV, int ln, f32x16& O0, f32x16& O1, float& m_run, float& l_run) const { attn_rest(S, LV, ln, O0, O1, m_run, l_run, mask(t)); }
; template <class MaskF>
; DI void attn_rest(const f32x16& S, LAS unsigned char* LV, int lane, f32x16& O0, f32x16& O1, float& m_run, float& l_run, const MaskF& maskf) {
;     const int h = lane >> 5;
;     float sv[16]; float mx = -1e30f;
; #pragma unroll
;     for (int r = 0; r < 16; ++r) { sv[r] = maskf((r & 3) + 8 * (r >> 2), S[r]); mx = fmaxf(mx, sv[r]); }
;     mx = fmaxf(mx, shx(mx, 32));
;     if (__builtin_amdgcn_ballot_w64(mx > m_run) != 0ull) {
;         const float mn = fmaxf(m_run, mx);
;         const float alpha = fexp2(m_run - mn);
;         m_run = mn; l_run *= alpha;
; #pragma unroll
;         for (int i = 0; i < 16; ++i) { O0[i] *= alpha; O1[i] *= alpha; }
;     }
; template <class Desc>
; DI void attn_loop(const Desc& d, int ntiles, const bf16x8 (&qf)[4], LAS unsigned char* LV, int lane, bf16_t* orow) {
;     ...
;     if (ntiles & 1) {
;         const f32x16 Sa = attn_scores(LQ, lane, kA);
;         attn_store_v(LV, lane, vN);
;         d.rest(tl, Sa, LV, lane, O0, O1, m_run, l_run);
.LBB0_352:
	s_or_b64 exec, exec, s[96:97]
	v_and_b32_e32 v0, 1, v167
	v_mov_b32_e32 v135, v139
	v_cmp_eq_u32_e32 vcc, 1, v0
	s_and_saveexec_b64 s[58:59], vcc
	s_cbranch_execz .LBB0_309
	v_cmp_gt_u32_e64 s[38:39], v162, v161
	v_add_u32_e32 v0, 0, v166
	s_waitcnt vmcnt(7) lgkmcnt(0)
	v_mfma_f32_32x32x16_bf16 v[48:63], v[76:79], v[236:239], 0
	s_waitcnt vmcnt(6) lgkmcnt(0)
	v_mfma_f32_32x32x16_bf16 v[48:63], v[72:75], v[240:243], v[48:63]
	s_waitcnt vmcnt(5) lgkmcnt(0)
	v_mfma_f32_32x32x16_bf16 v[48:63], v[68:71], v[244:247], v[48:63]
	s_waitcnt vmcnt(4) lgkmcnt(0)
	v_mfma_f32_32x32x16_bf16 v[48:63], v[64:67], v[248:251], v[48:63]
	v_add_u32_e32 v2, v125, v127
	s_waitcnt vmcnt(3)
	ds_write_b128 v2, v[96:99] offset:16384
	s_waitcnt vmcnt(2)
	ds_write_b128 v2, v[100:103] offset:17920
	s_waitcnt vmcnt(1)
	ds_write_b128 v2, v[104:107] offset:19456
	s_waitcnt vmcnt(0)
	ds_write_b128 v2, v[108:111] offset:20992
	v_add_u32_e32 v2, 4, v161
	v_cmp_ge_i32_e32 vcc, v2, v163
	s_and_b64 vcc, vcc, s[38:39]
	v_sub_u32_e32 v3, v164, v155
	v_cndmask_b32_e32 v64, v230, v3, vcc
	v_sub_u32_e32 v2, v2, v160
	v_sub_u32_e32 v3, v164, v153
	v_lshlrev_b32_e32 v3, 2, v3
	v_mul_i32_i24_e32 v2, 0x7c, v2
	v_add3_u32 v65, v0, v3, v2
	ds_read2_b32 v[2:3], v65 offset0:248 offset1:249
	ds_read2_b32 v[6:7], v65 offset0:250 offset1:251
	v_cmp_gt_u32_e32 vcc, 16, v64
	s_waitcnt lgkmcnt(1)
	v_add_f32_e32 v0, v48, v2
	v_cndmask_b32_e32 v2, v229, v0, vcc
	v_add_u32_e32 v0, 1, v64
	v_cmp_gt_u32_e32 vcc, 16, v0
	v_add_f32_e32 v0, v49, v3
	s_nop 0
	v_cndmask_b32_e32 v4, v229, v0, vcc
	v_add_u32_e32 v0, 2, v64
	v_cmp_gt_u32_e32 vcc, 16, v0
	s_waitcnt lgkmcnt(0)
	v_add_f32_e32 v0, v50, v6
	v_max3_f32 v5, v2, s83, v4
	v_cndmask_b32_e32 v3, v229, v0, vcc
	v_add_u32_e32 v0, 3, v64
	v_cmp_gt_u32_e32 vcc, 16, v0
	v_add_f32_e32 v0, v51, v7
	s_nop 0
	v_cndmask_b32_e32 v0, v229, v0, vcc
	v_max3_f32 v8, v5, v3, v0
	v_add_u32_e32 v5, 0x400, v65
	ds_read2_b32 v[6:7], v5 offset1:1
	v_add_u32_e32 v5, 8, v64
	v_cmp_gt_u32_e32 vcc, 16, v5
	s_waitcnt lgkmcnt(0)
	v_add_f32_e32 v5, v52, v6
	v_cndmask_b32_e32 v6, v229, v5, vcc
	v_add_u32_e32 v5, 9, v64
	v_cmp_gt_u32_e32 vcc, 16, v5
	v_add_f32_e32 v5, v53, v7
	v_add_u32_e32 v7, 0x408, v65
	v_cndmask_b32_e32 v5, v229, v5, vcc
	v_max3_f32 v10, v8, v6, v5
	ds_read2_b32 v[8:9], v7 offset1:1
	v_add_u32_e32 v7, 10, v64
	v_cmp_gt_u32_e32 vcc, 16, v7
	s_waitcnt lgkmcnt(0)
	v_add_f32_e32 v7, v54, v8
	v_add_u32_e32 v8, 11, v64
	v_cndmask_b32_e32 v7, v229, v7, vcc
	v_cmp_gt_u32_e32 vcc, 16, v8
	v_add_f32_e32 v8, v55, v9
	v_add_u32_e32 v9, 0x420, v65
	v_cndmask_b32_e32 v8, v229, v8, vcc
	v_max3_f32 v12, v10, v7, v8
	ds_read2_b32 v[10:11], v9 offset1:1
	v_cmp_lt_u32_e32 vcc, s54, v64
	s_waitcnt lgkmcnt(0)
	v_add_f32_e32 v9, v56, v10
	v_cndmask_b32_e32 v10, v229, v9, vcc
	v_add_u32_e32 v9, 17, v64
	v_cmp_gt_u32_e32 vcc, 16, v9
	v_add_f32_e32 v9, v57, v11
	v_add_u32_e32 v11, 0x428, v65
	v_cndmask_b32_e32 v9, v229, v9, vcc
	v_max3_f32 v14, v12, v10, v9
	ds_read2_b32 v[12:13], v11 offset1:1
	v_add_u32_e32 v11, 18, v64
	v_cmp_gt_u32_e32 vcc, 16, v11
	s_waitcnt lgkmcnt(0)
	v_add_f32_e32 v11, v58, v12
	v_cndmask_b32_e32 v12, v229, v11, vcc
	v_add_u32_e32 v11, 19, v64
	v_cmp_gt_u32_e32 vcc, 16, v11
	v_add_f32_e32 v11, v59, v13
	v_add_u32_e32 v13, 0x440, v65
	v_cndmask_b32_e32 v11, v229, v11, vcc
	v_max3_f32 v48, v14, v12, v11
	ds_read2_b32 v[14:15], v13 offset1:1
	v_add_u32_e32 v13, 24, v64
	v_cmp_gt_u32_e32 vcc, 16, v13
	s_waitcnt lgkmcnt(0)
	v_add_f32_e32 v13, v60, v14
	v_add_u32_e32 v14, 25, v64
	v_cndmask_b32_e32 v13, v229, v13, vcc
	v_cmp_gt_u32_e32 vcc, 16, v14
	v_add_f32_e32 v14, v61, v15
	v_add_u32_e32 v15, 0x448, v65
	v_cndmask_b32_e32 v14, v229, v14, vcc
	v_max3_f32 v50, v48, v13, v14
	ds_read2_b32 v[48:49], v15 offset1:1
	v_add_u32_e32 v15, 26, v64
	v_cmp_gt_u32_e32 vcc, 16, v15
	s_waitcnt lgkmcnt(0)
	v_add_f32_e32 v15, v62, v48
	v_add_u32_e32 v48, 27, v64
	v_cndmask_b32_e32 v15, v229, v15, vcc
	v_cmp_gt_u32_e32 vcc, 16, v48
	v_add_f32_e32 v48, v63, v49
	s_nop 0
	v_cndmask_b32_e32 v48, v229, v48, vcc
	v_max3_f32 v49, v50, v15, v48
	s_nop 0
	v_mov_b32_e32 v50, v49
	s_nop 1
	v_permlane32_swap_b32_e32 v50, v49
	s_waitcnt lgkmcnt(0)
	v_max_f32_e32 v50, v50, v50
	v_max_f32_e32 v49, v49, v50
	v_cmp_gt_f32_e32 vcc, v49, v133
	s_cbranch_vccz .LBB0_308
	v_max_f32_e32 v49, v49, v49
	v_max_f32_e32 v50, v133, v133
	v_max_f32_e32 v49, v50, v49
	v_sub_f32_e32 v50, v133, v49
	v_exp_f32_e32 v50, v50
	v_mov_b32_e32 v133, v49
	v_mul_f32_e32 v159, v159, v50
	v_pk_mul_f32 v[30:31], v[30:31], v[50:51] op_sel_hi:[1,0]
	v_pk_mul_f32 v[28:29], v[28:29], v[50:51] op_sel_hi:[1,0]
	v_pk_mul_f32 v[26:27], v[26:27], v[50:51] op_sel_hi:[1,0]
	v_pk_mul_f32 v[24:25], v[24:25], v[50:51] op_sel_hi:[1,0]
	v_pk_mul_f32 v[22:23], v[22:23], v[50:51] op_sel_hi:[1,0]
	v_pk_mul_f32 v[20:21], v[20:21], v[50:51] op_sel_hi:[1,0]
	v_pk_mul_f32 v[18:19], v[18:19], v[50:51] op_sel_hi:[1,0]
	v_pk_mul_f32 v[16:17], v[16:17], v[50:51] op_sel_hi:[1,0]
	v_pk_mul_f32 v[46:47], v[46:47], v[50:51] op_sel_hi:[1,0]
	v_pk_mul_f32 v[44:45], v[44:45], v[50:51] op_sel_hi:[1,0]
	v_pk_mul_f32 v[42:43], v[42:43], v[50:51] op_sel_hi:[1,0]
	v_pk_mul_f32 v[40:41], v[40:41], v[50:51] op_sel_hi:[1,0]
	v_pk_mul_f32 v[38:39], v[38:39], v[50:51] op_sel_hi:[1,0]
	v_pk_mul_f32 v[36:37], v[36:37], v[50:51] op_sel_hi:[1,0]
	v_pk_mul_f32 v[34:35], v[34:35], v[50:51] op_sel_hi:[1,0]
	v_pk_mul_f32 v[32:33], v[32:33], v[50:51] op_sel_hi:[1,0]
	s_branch .LBB0_308

; DI unsigned pack_bf16(float lo, float hi) { f32v2 f = {lo, hi}; bf16v2 b = __builtin_convertvector(f, bf16v2); return __builtin_bit_cast(unsigned, b); }
; DI float fexp2(float x) { return __builtin_amdgcn_exp2f(x); }
; DI float rotr1(float v) { return __int_as_float(__builtin_amdgcn_mov_dpp(__float_as_int(v), 0x121, 0xf, 0xf, false)); }
; DI float rotl1(float v) { return __int_as_float(__builtin_amdgcn_mov_dpp(__float_as_int(v), 0x12f, 0xf, 0xf, false)); }
; DI float gelu_tanh(float x) { const float t = x * (1.5957691216057308f + 0.0713548162726009f * x * x); return x * __builtin_amdgcn_rcpf(1.0f + fexp2(-LOG2E * t)); }
;     DI void operator()(const f32x4 (&acc)[2][2][4][2], const pg8::Unit& u, int wr, int wc, int fr, int fq, int ui) const {
;     ...
;                 for (int m = 0; m < 4; ++m) {
;                     float o[4];
; #pragma unroll
;                     for (int e = 0; e < 4; ++e) {
;                         const float pu_s = rotr1(U[m][e]), pg_s = rotr1(G[m][e]), nu_s = rotl1(U[m][e]), ng_s = rotl1(G[m][e]);
;                         const float pu_x = rotr1(U[m > 0 ? m - 1 : 0][e]), pg_x = rotr1(G[m > 0 ? m - 1 : 0][e]);
;                         const float nu_x = rotl1(U[m < 3 ? m + 1 : 3][e]), ng_x = rotl1(G[m < 3 ? m + 1 : 3][e]);
;                         const float pu = fr == 0 ? pu_x : pu_s, pg = fr == 0 ? pg_x : pg_s, nu = fr == 15 ? nu_x : nu_s, ng = fr == 15 ? ng_x : ng_s;
;                         const float yu = bu[e] + pu * wu[0][e] + U[m][e] * wu[1][e] + nu * wu[2][e];
;                         const float yg = bg[e] + pg * wg[0][e] + G[m][e] * wg[1][e] + ng * wg[2][e];
;                         o[e] = yu * gelu_tanh(yg);
;                     }
;                     const bool edge_row = (m == 0 && fr == 0) || (m == 3 && fr == 15);
;                     if (!edge_row) { u32x2 w; w.x = pack_bf16(o[0], o[1]); w.y = pack_bf16(o[2], o[3]); *(u32x2*)(O + (size_t)(rowb + m * 16 + fr) * FF + f0) = w; }
.LBB0_548:
	s_or_b64 exec, exec, s[58:59]
	v_mov_b32_e32 v220, v217
	v_pk_mul_f32 v[176:177], v[176:177], v[220:221] op_sel_hi:[1,0]
	v_pk_mul_f32 v[174:175], v[174:175], v[220:221] op_sel_hi:[1,0]
	v_pk_mul_f32 v[172:173], v[172:173], v[220:221] op_sel_hi:[1,0]
	v_pk_mul_f32 v[170:171], v[170:171], v[220:221] op_sel_hi:[1,0]
	v_or_b32_e32 v239, s35, v204
	v_mov_b32_dpp v220, v190 row_ror:1 row_mask:0xf bank_mask:0xf
	v_mov_b32_dpp v222, v218 row_ror:1 row_mask:0xf bank_mask:0xf
	v_mov_b32_dpp v245, v190 row_ror:15 row_mask:0xf bank_mask:0xf
	v_mov_b32_dpp v243, v218 row_ror:15 row_mask:0xf bank_mask:0xf
	v_mov_b32_dpp v246, v174 row_ror:15 row_mask:0xf bank_mask:0xf
	v_mov_b32_dpp v244, v170 row_ror:15 row_mask:0xf bank_mask:0xf
	v_mov_b32_dpp v221, v191 row_ror:1 row_mask:0xf bank_mask:0xf
	v_mov_b32_dpp v223, v219 row_ror:1 row_mask:0xf bank_mask:0xf
	v_mov_b32_dpp v241, v191 row_ror:15 row_mask:0xf bank_mask:0xf
	v_mov_b32_dpp v247, v219 row_ror:15 row_mask:0xf bank_mask:0xf
	v_mov_b32_dpp v242, v175 row_ror:15 row_mask:0xf bank_mask:0xf
	v_mov_b32_dpp v248, v171 row_ror:15 row_mask:0xf bank_mask:0xf
	v_mov_b32_dpp v224, v192 row_ror:1 row_mask:0xf bank_mask:0xf
	v_mov_b32_dpp v226, v188 row_ror:1 row_mask:0xf bank_mask:0xf
	v_mov_b32_dpp v207, v192 row_ror:15 row_mask:0xf bank_mask:0xf
	v_mov_b32_dpp v251, v188 row_ror:15 row_mask:0xf bank_mask:0xf
	v_mov_b32_dpp v232, v176 row_ror:15 row_mask:0xf bank_mask:0xf
	v_mov_b32_dpp v252, v172 row_ror:15 row_mask:0xf bank_mask:0xf
	v_mov_b32_dpp v225, v193 row_ror:1 row_mask:0xf bank_mask:0xf
	v_mov_b32_dpp v227, v189 row_ror:1 row_mask:0xf bank_mask:0xf
	v_mov_b32_dpp v249, v193 row_ror:15 row_mask:0xf bank_mask:0xf
	v_mov_b32_dpp v253, v189 row_ror:15 row_mask:0xf bank_mask:0xf
	v_mov_b32_dpp v250, v177 row_ror:15 row_mask:0xf bank_mask:0xf
	v_mov_b32_dpp v231, v173 row_ror:15 row_mask:0xf bank_mask:0xf
	s_and_saveexec_b64 s[58:59], s[10:11]
	s_xor_b64 s[58:59], exec, s[58:59]
	s_cbranch_execz .LBB0_550
	s_waitcnt vmcnt(0)
	v_pk_fma_f32 v[226:227], v[148:149], v[226:227], v[160:161]
	v_cndmask_b32_e64 v252, v251, v252, s[16:17]
	v_cndmask_b32_e64 v253, v253, v231, s[16:17]
	v_pk_fma_f32 v[226:227], v[152:153], v[188:189], v[226:227]
	v_cndmask_b32_e64 v234, v207, v232, s[16:17]
	v_pk_fma_f32 v[226:227], v[156:157], v[252:253], v[226:227]
	v_cndmask_b32_e64 v235, v249, v250, s[16:17]
	v_mul_f32_e32 v207, 0xbdd2d3e7, v227
	v_fmaak_f32 v207, v227, v207, 0xc0135761
	v_mul_f32_e32 v231, 0xbdd2d3e7, v226
	v_mul_f32_e32 v207, v227, v207
	v_fmaak_f32 v231, v226, v231, 0xc0135761
	v_mul_f32_e32 v231, v226, v231
	v_exp_f32_e32 v207, v207
	v_exp_f32_e32 v231, v231
	v_pk_fma_f32 v[224:225], v[132:133], v[224:225], v[144:145]
	v_add_f32_e32 v207, 1.0, v207
	v_rcp_f32_e32 v251, v207
	v_add_f32_e32 v207, 1.0, v231
	v_rcp_f32_e32 v250, v207
	v_pk_fma_f32 v[224:225], v[136:137], v[192:193], v[224:225]
	v_pk_fma_f32 v[222:223], v[146:147], v[222:223], v[158:159]
	v_pk_fma_f32 v[224:225], v[140:141], v[234:235], v[224:225]
	v_cndmask_b32_e64 v234, v243, v244, s[16:17]
	v_cndmask_b32_e64 v235, v247, v248, s[16:17]
	v_pk_fma_f32 v[222:223], v[150:151], v[218:219], v[222:223]
	v_pk_mul_f32 v[226:227], v[226:227], v[250:251]
	v_pk_fma_f32 v[222:223], v[154:155], v[234:235], v[222:223]
	v_pk_mul_f32 v[224:225], v[224:225], v[226:227]
	v_mul_f32_e32 v207, 0xbdd2d3e7, v223
	v_fmaak_f32 v207, v223, v207, 0xc0135761
	v_mul_f32_e32 v227, 0xbdd2d3e7, v222
	v_mul_f32_e32 v207, v223, v207
	v_fmaak_f32 v227, v222, v227, 0xc0135761
	v_mul_f32_e32 v227, v222, v227
	v_exp_f32_e32 v207, v207
	v_exp_f32_e32 v231, v227
	v_pk_fma_f32 v[220:221], v[130:131], v[220:221], v[142:143]
	v_add_f32_e32 v207, 1.0, v207
	v_rcp_f32_e32 v235, v207
	v_add_f32_e32 v207, 1.0, v231
	v_rcp_f32_e32 v234, v207
	v_cndmask_b32_e64 v226, v245, v246, s[16:17]
	v_cndmask_b32_e64 v227, v241, v242, s[16:17]
	v_pk_fma_f32 v[220:221], v[134:135], v[190:191], v[220:221]
	v_pk_mul_f32 v[222:223], v[222:223], v[234:235]
	v_pk_fma_f32 v[220:221], v[138:139], v[226:227], v[220:221]
	s_nop 0
	v_pk_mul_f32 v[220:221], v[220:221], v[222:223]
	v_mov_b64_e32 v[222:223], s[26:27]
	v_mad_i64_i32 v[222:223], s[70:71], v239, s57, v[222:223]
	v_cvt_pk_bf16_f32 v220, v220, v221
	v_cvt_pk_bf16_f32 v221, v224, v225
	v_lshl_add_u64 v[222:223], v[214:215], 1, v[222:223]
	global_store_dwordx2 v[222:223], v[220:221], off
; DI unsigned pack_bf16(float lo, float hi) { f32v2 f = {lo, hi}; bf16v2 b = __builtin_convertvector(f, bf16v2); return __builtin_bit_cast(unsigned, b); }
; DI float fexp2(float x) { return __builtin_amdgcn_exp2f(x); }
; DI float rotr1(float v) { return __int_as_float(__builtin_amdgcn_mov_dpp(__float_as_int(v), 0x121, 0xf, 0xf, false)); }
; DI float rotl1(float v) { return __int_as_float(__builtin_amdgcn_mov_dpp(__float_as_int(v), 0x12f, 0xf, 0xf, false)); }
; DI float gelu_tanh(float x) { const float t = x * (1.5957691216057308f + 0.0713548162726009f * x * x); return x * __builtin_amdgcn_rcpf(1.0f + fexp2(-LOG2E * t)); }
;     DI void operator()(const f32x4 (&acc)[2][2][4][2], const pg8::Unit& u, int wr, int wc, int fr, int fq, int ui) const {
;     ...
;                 for (int m = 0; m < 4; ++m) {
;                     float o[4];
; #pragma unroll
;                     for (int e = 0; e < 4; ++e) {
;                         const float pu_s = rotr1(U[m][e]), pg_s = rotr1(G[m][e]), nu_s = rotl1(U[m][e]), ng_s = rotl1(G[m][e]);
;                         const float pu_x = rotr1(U[m > 0 ? m - 1 : 0][e]), pg_x = rotr1(G[m > 0 ? m - 1 : 0][e]);
;                         const float nu_x = rotl1(U[m < 3 ? m + 1 : 3][e]), ng_x = rotl1(G[m < 3 ? m + 1 : 3][e]);
;                         const float pu = fr == 0 ? pu_x : pu_s, pg = fr == 0 ? pg_x : pg_s, nu = fr == 15 ? nu_x : nu_s, ng = fr == 15 ? ng_x : ng_s;
;                         const float yu = bu[e] + pu * wu[0][e] + U[m][e] * wu[1][e] + nu * wu[2][e];
;                         const float yg = bg[e] + pg * wg[0][e] + G[m][e] * wg[1][e] + ng * wg[2][e];
;                         o[e] = yu * gelu_tanh(yg);
;                     }
;                     const bool edge_row = (m == 0 && fr == 0) || (m == 3 && fr == 15);
;                     if (!edge_row) { u32x2 w; w.x = pack_bf16(o[0], o[1]); w.y = pack_bf16(o[2], o[3]); *(u32x2*)(O + (size_t)(rowb + m * 16 + fr) * FF + f0) = w; }
.LBB0_550:
	s_andn2_saveexec_b64 s[58:59], s[58:59]
	s_or_b64 exec, exec, s[58:59]
	v_pk_mul_f32 v[224:225], v[162:163], v[186:187] op_sel_hi:[1,0]
	v_mov_b32_dpp v243, v172 row_ror:1 row_mask:0xf bank_mask:0xf
	v_mov_b32_dpp v162, v188 row_ror:1 row_mask:0xf bank_mask:0xf
	v_mov_b32_dpp v251, v173 row_ror:1 row_mask:0xf bank_mask:0xf
	v_mov_b32_dpp v163, v189 row_ror:1 row_mask:0xf bank_mask:0xf
	v_pk_mul_f32 v[222:223], v[164:165], v[186:187] op_sel_hi:[1,0]
	v_cndmask_b32_e64 v163, v251, v163, s[12:13]
	v_cndmask_b32_e64 v162, v243, v162, s[12:13]
	v_mov_b32_dpp v164, v172 row_ror:15 row_mask:0xf bank_mask:0xf
	v_mov_b32_dpp v249, v222 row_ror:15 row_mask:0xf bank_mask:0xf
	v_mov_b32_dpp v165, v173 row_ror:15 row_mask:0xf bank_mask:0xf
	v_mov_b32_dpp v252, v223 row_ror:15 row_mask:0xf bank_mask:0xf
	s_waitcnt vmcnt(0)
	v_pk_fma_f32 v[162:163], v[148:149], v[162:163], v[160:161]
	v_cndmask_b32_e64 v165, v165, v252, s[16:17]
	v_pk_fma_f32 v[162:163], v[152:153], v[172:173], v[162:163]
	v_cndmask_b32_e64 v164, v164, v249, s[16:17]
	v_pk_fma_f32 v[162:163], v[156:157], v[164:165], v[162:163]
	v_pk_mul_f32 v[220:221], v[168:169], v[186:187] op_sel_hi:[1,0]
	v_mul_f32_e32 v164, 0xbdd2d3e7, v163
	v_fmaak_f32 v164, v163, v164, 0xc0135761
	v_mul_f32_e32 v164, v163, v164
	v_exp_f32_e32 v164, v164
	v_mov_b32_dpp v242, v176 row_ror:1 row_mask:0xf bank_mask:0xf
	v_mov_b32_dpp v168, v192 row_ror:1 row_mask:0xf bank_mask:0xf
	v_mov_b32_dpp v250, v177 row_ror:1 row_mask:0xf bank_mask:0xf
	v_add_f32_e32 v164, 1.0, v164
	v_rcp_f32_e32 v165, v164
	v_mul_f32_e32 v164, 0xbdd2d3e7, v162
	v_fmaak_f32 v164, v162, v164, 0xc0135761
	v_mul_f32_e32 v164, v162, v164
	v_mov_b32_dpp v169, v193 row_ror:1 row_mask:0xf bank_mask:0xf
	v_exp_f32_e32 v164, v164
	v_cndmask_b32_e64 v169, v250, v169, s[12:13]
	v_cndmask_b32_e64 v168, v242, v168, s[12:13]
	v_mov_b32_dpp v231, v170 row_ror:1 row_mask:0xf bank_mask:0xf
	v_mov_b32_dpp v218, v218 row_ror:1 row_mask:0xf bank_mask:0xf
	v_mov_b32_dpp v244, v171 row_ror:1 row_mask:0xf bank_mask:0xf
	v_mov_b32_dpp v219, v219 row_ror:1 row_mask:0xf bank_mask:0xf
	v_pk_fma_f32 v[168:169], v[132:133], v[168:169], v[144:145]
	v_mov_b32_dpp v245, v176 row_ror:15 row_mask:0xf bank_mask:0xf
	v_mov_b32_dpp v172, v177 row_ror:15 row_mask:0xf bank_mask:0xf
	v_pk_fma_f32 v[168:169], v[136:137], v[176:177], v[168:169]
	v_cndmask_b32_e64 v177, v244, v219, s[12:13]
	v_cndmask_b32_e64 v176, v231, v218, s[12:13]
	v_mov_b32_dpp v227, v170 row_ror:15 row_mask:0xf bank_mask:0xf
	v_mov_b32_dpp v241, v224 row_ror:15 row_mask:0xf bank_mask:0xf
	v_mov_b32_dpp v235, v171 row_ror:15 row_mask:0xf bank_mask:0xf
	v_mov_b32_dpp v248, v225 row_ror:15 row_mask:0xf bank_mask:0xf
	v_add_f32_e32 v164, 1.0, v164
	v_pk_fma_f32 v[176:177], v[146:147], v[176:177], v[158:159]
	v_rcp_f32_e32 v164, v164
	v_pk_fma_f32 v[170:171], v[150:151], v[170:171], v[176:177]
	v_cndmask_b32_e64 v177, v235, v248, s[16:17]
	v_cndmask_b32_e64 v176, v227, v241, s[16:17]
	v_pk_fma_f32 v[170:171], v[154:155], v[176:177], v[170:171]
	v_mov_b32_dpp v188, v220 row_ror:15 row_mask:0xf bank_mask:0xf
	v_mov_b32_dpp v253, v221 row_ror:15 row_mask:0xf bank_mask:0xf
	v_mul_f32_e32 v176, 0xbdd2d3e7, v171
	v_cndmask_b32_e64 v173, v172, v253, s[16:17]
	v_cndmask_b32_e64 v172, v245, v188, s[16:17]
	v_fmaak_f32 v176, v171, v176, 0xc0135761
	v_mov_b32_dpp v207, v174 row_ror:1 row_mask:0xf bank_mask:0xf
	v_mov_b32_dpp v190, v190 row_ror:1 row_mask:0xf bank_mask:0xf
	v_mov_b32_dpp v246, v175 row_ror:1 row_mask:0xf bank_mask:0xf
	v_mov_b32_dpp v191, v191 row_ror:1 row_mask:0xf bank_mask:0xf
	v_mul_f32_e32 v176, v171, v176
	v_pk_fma_f32 v[168:169], v[140:141], v[172:173], v[168:169]
	v_pk_mul_f32 v[162:163], v[162:163], v[164:165]
	v_pk_mul_f32 v[166:167], v[166:167], v[186:187] op_sel_hi:[1,0]
	v_pk_mul_f32 v[162:163], v[168:169], v[162:163]
	v_cndmask_b32_e64 v169, v246, v191, s[12:13]
	v_cndmask_b32_e64 v168, v207, v190, s[12:13]
	v_mov_b32_dpp v226, v174 row_ror:15 row_mask:0xf bank_mask:0xf
	v_mov_b32_dpp v232, v166 row_ror:15 row_mask:0xf bank_mask:0xf
	v_mov_b32_dpp v234, v175 row_ror:15 row_mask:0xf bank_mask:0xf
	v_mov_b32_dpp v247, v167 row_ror:15 row_mask:0xf bank_mask:0xf
	v_exp_f32_e32 v176, v176
	v_pk_fma_f32 v[168:169], v[130:131], v[168:169], v[142:143]
	v_cndmask_b32_e64 v173, v234, v247, s[16:17]
	v_pk_fma_f32 v[168:169], v[134:135], v[174:175], v[168:169]
	v_cndmask_b32_e64 v172, v226, v232, s[16:17]
	v_mov_b32_dpp v192, v222 row_ror:1 row_mask:0xf bank_mask:0xf
	v_mov_b32_dpp v193, v223 row_ror:1 row_mask:0xf bank_mask:0xf
	v_pk_fma_f32 v[168:169], v[138:139], v[172:173], v[168:169]
	v_cndmask_b32_e64 v173, v193, v251, s[12:13]
	v_cndmask_b32_e64 v172, v192, v243, s[12:13]
	v_mov_b32_dpp v174, v180 row_ror:15 row_mask:0xf bank_mask:0xf
	v_mov_b32_dpp v175, v181 row_ror:15 row_mask:0xf bank_mask:0xf
	v_pk_fma_f32 v[172:173], v[148:149], v[172:173], v[160:161]
	v_add_f32_e32 v164, 1.0, v176
	v_pk_fma_f32 v[172:173], v[152:153], v[222:223], v[172:173]
	v_cndmask_b32_e64 v219, v252, v175, s[16:17]
	v_cndmask_b32_e64 v218, v249, v174, s[16:17]
	v_rcp_f32_e32 v165, v164
	v_mul_f32_e32 v164, 0xbdd2d3e7, v170
	v_pk_fma_f32 v[222:223], v[156:157], v[218:219], v[172:173]
	v_fmaak_f32 v164, v170, v164, 0xc0135761
	v_mul_f32_e32 v172, 0xbdd2d3e7, v223
	v_mul_f32_e32 v164, v170, v164
	v_fmaak_f32 v172, v223, v172, 0xc0135761
	v_mul_f32_e32 v172, v223, v172
	v_exp_f32_e32 v164, v164
	v_exp_f32_e32 v219, v172
	v_mov_b64_e32 v[226:227], s[26:27]
	v_add_f32_e32 v164, 1.0, v164
	v_rcp_f32_e32 v164, v164
	v_add_f32_e32 v219, 1.0, v219
	v_rcp_f32_e32 v235, v219
	v_mul_f32_e32 v219, 0xbdd2d3e7, v222
; DI unsigned pack_bf16(float lo, float hi) { f32v2 f = {lo, hi}; bf16v2 b = __builtin_convertvector(f, bf16v2); return __builtin_bit_cast(unsigned, b); }
; DI float fexp2(float x) { return __builtin_amdgcn_exp2f(x); }
; DI float rotr1(float v) { return __int_as_float(__builtin_amdgcn_mov_dpp(__float_as_int(v), 0x121, 0xf, 0xf, false)); }
; DI float rotl1(float v) { return __int_as_float(__builtin_amdgcn_mov_dpp(__float_as_int(v), 0x12f, 0xf, 0xf, false)); }
; DI float gelu_tanh(float x) { const float t = x * (1.5957691216057308f + 0.0713548162726009f * x * x); return x * __builtin_amdgcn_rcpf(1.0f + fexp2(-LOG2E * t)); }
;     DI void operator()(const f32x4 (&acc)[2][2][4][2], const pg8::Unit& u, int wr, int wc, int fr, int fq, int ui) const {
;     ...
;                 for (int m = 0; m < 4; ++m) {
;                     float o[4];
; #pragma unroll
;                     for (int e = 0; e < 4; ++e) {
;                         const float pu_s = rotr1(U[m][e]), pg_s = rotr1(G[m][e]), nu_s = rotl1(U[m][e]), ng_s = rotl1(G[m][e]);
;                         const float pu_x = rotr1(U[m > 0 ? m - 1 : 0][e]), pg_x = rotr1(G[m > 0 ? m - 1 : 0][e]);
;                         const float nu_x = rotl1(U[m < 3 ? m + 1 : 3][e]), ng_x = rotl1(G[m < 3 ? m + 1 : 3][e]);
;                         const float pu = fr == 0 ? pu_x : pu_s, pg = fr == 0 ? pg_x : pg_s, nu = fr == 15 ? nu_x : nu_s, ng = fr == 15 ? ng_x : ng_s;
;                         const float yu = bu[e] + pu * wu[0][e] + U[m][e] * wu[1][e] + nu * wu[2][e];
;                         const float yg = bg[e] + pg * wg[0][e] + G[m][e] * wg[1][e] + ng * wg[2][e];
;                         o[e] = yu * gelu_tanh(yg);
;                     }
;                     const bool edge_row = (m == 0 && fr == 0) || (m == 3 && fr == 15);
;                     if (!edge_row) { u32x2 w; w.x = pack_bf16(o[0], o[1]); w.y = pack_bf16(o[2], o[3]); *(u32x2*)(O + (size_t)(rowb + m * 16 + fr) * FF + f0) = w; }
	v_fmaak_f32 v219, v222, v219, 0xc0135761
	v_mul_f32_e32 v219, v222, v219
	v_pk_mul_f32 v[164:165], v[170:171], v[164:165]
	v_cvt_pk_bf16_f32 v171, v162, v163
	v_or_b32_e32 v162, 16, v239
	v_pk_mul_f32 v[164:165], v[168:169], v[164:165]
	v_mad_i64_i32 v[162:163], s[58:59], v162, s57, v[226:227]
	v_lshlrev_b64 v[168:169], 1, v[214:215]
	v_mov_b32_dpp v177, v224 row_ror:1 row_mask:0xf bank_mask:0xf
	v_mov_b32_dpp v189, v225 row_ror:1 row_mask:0xf bank_mask:0xf
	v_exp_f32_e32 v219, v219
	v_cvt_pk_bf16_f32 v170, v164, v165
	v_lshl_add_u64 v[164:165], v[162:163], 0, v[168:169]
	v_mov_b32_dpp v191, v220 row_ror:1 row_mask:0xf bank_mask:0xf
	v_mov_b32_dpp v218, v221 row_ror:1 row_mask:0xf bank_mask:0xf
	v_cndmask_b32_e64 v245, v189, v244, s[12:13]
	v_cndmask_b32_e64 v244, v177, v231, s[12:13]
	global_store_dwordx2 v[164:165], v[170:171], off
	v_mov_b32_dpp v170, v178 row_ror:15 row_mask:0xf bank_mask:0xf
	v_mov_b32_dpp v171, v179 row_ror:15 row_mask:0xf bank_mask:0xf
	v_cndmask_b32_e64 v243, v218, v250, s[12:13]
	v_cndmask_b32_e64 v242, v191, v242, s[12:13]
	v_pk_fma_f32 v[244:245], v[146:147], v[244:245], v[158:159]
	v_mov_b32_dpp v172, v184 row_ror:15 row_mask:0xf bank_mask:0xf
	v_pk_fma_f32 v[242:243], v[132:133], v[242:243], v[144:145]
	v_pk_fma_f32 v[224:225], v[150:151], v[224:225], v[244:245]
	v_cndmask_b32_e64 v245, v248, v171, s[16:17]
	v_cndmask_b32_e64 v244, v241, v170, s[16:17]
	v_pk_fma_f32 v[220:221], v[136:137], v[220:221], v[242:243]
	v_cndmask_b32_e64 v242, v188, v172, s[16:17]
	v_add_f32_e32 v188, 1.0, v219
	v_pk_fma_f32 v[224:225], v[154:155], v[244:245], v[224:225]
	v_rcp_f32_e32 v234, v188
	v_mul_f32_e32 v188, 0xbdd2d3e7, v225
	v_fmaak_f32 v188, v225, v188, 0xc0135761
	v_mul_f32_e32 v188, v225, v188
	v_exp_f32_e32 v188, v188
	v_mov_b32_dpp v173, v185 row_ror:15 row_mask:0xf bank_mask:0xf
	v_cndmask_b32_e64 v243, v253, v173, s[16:17]
	v_pk_fma_f32 v[220:221], v[140:141], v[242:243], v[220:221]
	v_pk_mul_f32 v[222:223], v[222:223], v[234:235]
	v_add_f32_e32 v188, 1.0, v188
	v_pk_mul_f32 v[220:221], v[220:221], v[222:223]
	v_rcp_f32_e32 v223, v188
	v_mul_f32_e32 v188, 0xbdd2d3e7, v224
	v_fmaak_f32 v188, v224, v188, 0xc0135761
	v_mul_f32_e32 v188, v224, v188
	v_exp_f32_e32 v188, v188
	v_mov_b32_dpp v176, v166 row_ror:1 row_mask:0xf bank_mask:0xf
	v_mov_b32_dpp v190, v167 row_ror:1 row_mask:0xf bank_mask:0xf
	v_cndmask_b32_e64 v235, v190, v246, s[12:13]
	v_add_f32_e32 v188, 1.0, v188
	v_rcp_f32_e32 v222, v188
	v_cndmask_b32_e64 v234, v176, v207, s[12:13]
	v_mov_b32_dpp v162, v182 row_ror:15 row_mask:0xf bank_mask:0xf
	v_mov_b32_dpp v163, v183 row_ror:15 row_mask:0xf bank_mask:0xf
	v_pk_fma_f32 v[234:235], v[130:131], v[234:235], v[142:143]
	v_pk_mul_f32 v[222:223], v[224:225], v[222:223]
	v_pk_fma_f32 v[166:167], v[134:135], v[166:167], v[234:235]
	v_cndmask_b32_e64 v235, v247, v163, s[16:17]
	v_cndmask_b32_e64 v234, v232, v162, s[16:17]
	v_pk_fma_f32 v[166:167], v[138:139], v[234:235], v[166:167]
	v_mov_b32_dpp v219, v182 row_ror:1 row_mask:0xf bank_mask:0xf
	v_pk_mul_f32 v[166:167], v[166:167], v[222:223]
	v_cvt_pk_bf16_f32 v223, v220, v221
	v_cvt_pk_bf16_f32 v222, v166, v167
	v_or_b32_e32 v166, 32, v239
	v_mad_i64_i32 v[166:167], s[58:59], v166, s57, v[226:227]
	v_lshl_add_u64 v[166:167], v[166:167], 0, v[168:169]
	global_store_dwordx2 v[166:167], v[222:223], off
	v_mov_b32_dpp v220, v178 row_ror:1 row_mask:0xf bank_mask:0xf
	v_mov_b32_dpp v222, v183 row_ror:1 row_mask:0xf bank_mask:0xf
	v_mov_b32_dpp v221, v179 row_ror:1 row_mask:0xf bank_mask:0xf
	v_mov_b32_dpp v207, v184 row_ror:1 row_mask:0xf bank_mask:0xf
	v_mov_b32_dpp v223, v180 row_ror:1 row_mask:0xf bank_mask:0xf
	v_mov_b32_dpp v225, v185 row_ror:1 row_mask:0xf bank_mask:0xf
	v_mov_b32_dpp v224, v181 row_ror:1 row_mask:0xf bank_mask:0xf
	v_or_b32_e32 v188, 48, v239
	s_and_saveexec_b64 s[58:59], s[14:15]
	s_cbranch_execz .LBB0_552
	v_cndmask_b32_e64 v193, v224, v193, s[12:13]
	v_cndmask_b32_e64 v192, v223, v192, s[12:13]
	v_pk_fma_f32 v[192:193], v[148:149], v[192:193], v[160:161]
	v_cndmask_b32_e64 v225, v225, v218, s[12:13]
	v_pk_fma_f32 v[180:181], v[152:153], v[180:181], v[192:193]
	v_cndmask_b32_e64 v224, v207, v191, s[12:13]
	v_pk_fma_f32 v[174:175], v[156:157], v[174:175], v[180:181]
	s_nop 0
	v_mul_f32_e32 v180, 0xbdd2d3e7, v175
	v_fmaak_f32 v180, v175, v180, 0xc0135761
	v_mul_f32_e32 v181, 0xbdd2d3e7, v174
	v_mul_f32_e32 v180, v175, v180
	v_fmaak_f32 v181, v174, v181, 0xc0135761
	v_mul_f32_e32 v181, v174, v181
	v_exp_f32_e32 v180, v180
	v_exp_f32_e32 v192, v181
	v_add_f32_e32 v180, 1.0, v180
	v_rcp_f32_e32 v181, v180
	v_add_f32_e32 v180, 1.0, v192
	v_rcp_f32_e32 v180, v180
	v_pk_fma_f32 v[192:193], v[132:133], v[224:225], v[144:145]
	v_pk_mul_f32 v[174:175], v[174:175], v[180:181]
	v_cndmask_b32_e64 v181, v221, v189, s[12:13]
	v_cndmask_b32_e64 v180, v220, v177, s[12:13]
	v_pk_fma_f32 v[180:181], v[146:147], v[180:181], v[158:159]
	v_pk_fma_f32 v[184:185], v[136:137], v[184:185], v[192:193]
	v_pk_fma_f32 v[178:179], v[150:151], v[178:179], v[180:181]
	v_pk_fma_f32 v[172:173], v[140:141], v[172:173], v[184:185]
	v_pk_fma_f32 v[170:171], v[154:155], v[170:171], v[178:179]
	v_pk_mul_f32 v[172:173], v[172:173], v[174:175]
	v_mul_f32_e32 v174, 0xbdd2d3e7, v171
	v_fmaak_f32 v174, v171, v174, 0xc0135761
	v_mul_f32_e32 v174, v171, v174
	v_exp_f32_e32 v177, v174
	v_mul_f32_e32 v174, 0xbdd2d3e7, v170
	v_fmaak_f32 v174, v170, v174, 0xc0135761
	v_mul_f32_e32 v174, v170, v174
	v_exp_f32_e32 v178, v174
	v_cndmask_b32_e64 v174, v219, v176, s[12:13]
	v_add_f32_e32 v176, 1.0, v177
	v_rcp_f32_e32 v177, v176
	v_add_f32_e32 v176, 1.0, v178
	v_rcp_f32_e32 v176, v176
	v_cndmask_b32_e64 v175, v222, v190, s[12:13]
	v_pk_fma_f32 v[174:175], v[130:131], v[174:175], v[142:143]
	v_pk_mul_f32 v[170:171], v[170:171], v[176:177]
	v_pk_fma_f32 v[174:175], v[134:135], v[182:183], v[174:175]
	s_nop 0
	v_pk_fma_f32 v[162:163], v[138:139], v[162:163], v[174:175]
	s_nop 0
	v_pk_mul_f32 v[162:163], v[162:163], v[170:171]
	v_mov_b64_e32 v[170:171], s[26:27]
	v_mad_i64_i32 v[170:171], s[70:71], v188, s57, v[170:171]
	v_cvt_pk_bf16_f32 v162, v162, v163
	v_cvt_pk_bf16_f32 v163, v172, v173
	v_lshl_add_u64 v[170:171], v[214:215], 1, v[170:171]
	global_store_dwordx2 v[170:171], v[162:163], off

; DI unsigned pack_bf16(float lo, float hi) { f32v2 f = {lo, hi}; bf16v2 b = __builtin_convertvector(f, bf16v2); return __builtin_bit_cast(unsigned, b); }
; DI float fexp2(float x) { return __builtin_amdgcn_exp2f(x); }
; DI float rotr1(float v) { return __int_as_float(__builtin_amdgcn_mov_dpp(__float_as_int(v), 0x121, 0xf, 0xf, false)); }
; DI float rotl1(float v) { return __int_as_float(__builtin_amdgcn_mov_dpp(__float_as_int(v), 0x12f, 0xf, 0xf, false)); }
; DI float gelu_tanh(float x) { const float t = x * (1.5957691216057308f + 0.0713548162726009f * x * x); return x * __builtin_amdgcn_rcpf(1.0f + fexp2(-LOG2E * t)); }
;     DI void operator()(const f32x4 (&acc)[2][2][4][2], const pg8::Unit& u, int wr, int wc, int fr, int fq, int ui) const {
;     ...
;                 for (int m = 0; m < 4; ++m) { const float s_ = tab[ai * 128 + m * 16]; U[m] = acc[ai][0][m][n] * s_; G[m] = acc[ai][1][m][n] * s_; }
;     ...
;                 for (int m = 0; m < 4; ++m) {
;                     float o[4];
; #pragma unroll
;                     for (int e = 0; e < 4; ++e) {
;                         const float pu_s = rotr1(U[m][e]), pg_s = rotr1(G[m][e]), nu_s = rotl1(U[m][e]), ng_s = rotl1(G[m][e]);
;                         const float pu_x = rotr1(U[m > 0 ? m - 1 : 0][e]), pg_x = rotr1(G[m > 0 ? m - 1 : 0][e]);
;                         const float nu_x = rotl1(U[m < 3 ? m + 1 : 3][e]), ng_x = rotl1(G[m < 3 ? m + 1 : 3][e]);
;                         const float pu = fr == 0 ? pu_x : pu_s, pg = fr == 0 ? pg_x : pg_s, nu = fr == 15 ? nu_x : nu_s, ng = fr == 15 ? ng_x : ng_s;
;                         const float yu = bu[e] + pu * wu[0][e] + U[m][e] * wu[1][e] + nu * wu[2][e];
;                         const float yg = bg[e] + pg * wg[0][e] + G[m][e] * wg[1][e] + ng * wg[2][e];
;                         o[e] = yu * gelu_tanh(yg);
;                     }
;                     const bool edge_row = (m == 0 && fr == 0) || (m == 3 && fr == 15);
;                     if (!edge_row) { u32x2 w; w.x = pack_bf16(o[0], o[1]); w.y = pack_bf16(o[2], o[3]); *(u32x2*)(O + (size_t)(rowb + m * 16 + fr) * FF + f0) = w; }
.LBB0_556:
	s_or_b64 exec, exec, s[58:59]
	v_mov_b32_e32 v172, v163
	v_pk_mul_f32 v[116:117], v[116:117], v[172:173] op_sel_hi:[1,0]
	v_pk_mul_f32 v[114:115], v[114:115], v[172:173] op_sel_hi:[1,0]
	v_pk_mul_f32 v[108:109], v[108:109], v[172:173] op_sel_hi:[1,0]
	v_pk_mul_f32 v[106:107], v[106:107], v[172:173] op_sel_hi:[1,0]
	v_or_b32_e32 v180, s37, v204
	v_mov_b32_dpp v172, v126 row_ror:1 row_mask:0xf bank_mask:0xf
	v_mov_b32_dpp v174, v170 row_ror:1 row_mask:0xf bank_mask:0xf
	v_mov_b32_dpp v185, v126 row_ror:15 row_mask:0xf bank_mask:0xf
	v_mov_b32_dpp v183, v170 row_ror:15 row_mask:0xf bank_mask:0xf
	v_mov_b32_dpp v189, v114 row_ror:15 row_mask:0xf bank_mask:0xf
	v_mov_b32_dpp v184, v106 row_ror:15 row_mask:0xf bank_mask:0xf
	v_mov_b32_dpp v173, v127 row_ror:1 row_mask:0xf bank_mask:0xf
	v_mov_b32_dpp v175, v171 row_ror:1 row_mask:0xf bank_mask:0xf
	v_mov_b32_dpp v181, v127 row_ror:15 row_mask:0xf bank_mask:0xf
	v_mov_b32_dpp v190, v171 row_ror:15 row_mask:0xf bank_mask:0xf
	v_mov_b32_dpp v182, v115 row_ror:15 row_mask:0xf bank_mask:0xf
	v_mov_b32_dpp v191, v107 row_ror:15 row_mask:0xf bank_mask:0xf
	v_mov_b32_dpp v176, v128 row_ror:1 row_mask:0xf bank_mask:0xf
	v_mov_b32_dpp v178, v124 row_ror:1 row_mask:0xf bank_mask:0xf
	v_mov_b32_dpp v220, v128 row_ror:15 row_mask:0xf bank_mask:0xf
	v_mov_b32_dpp v207, v124 row_ror:15 row_mask:0xf bank_mask:0xf
	v_mov_b32_dpp v222, v116 row_ror:15 row_mask:0xf bank_mask:0xf
	v_mov_b32_dpp v218, v108 row_ror:15 row_mask:0xf bank_mask:0xf
	v_mov_b32_dpp v177, v129 row_ror:1 row_mask:0xf bank_mask:0xf
	v_mov_b32_dpp v179, v125 row_ror:1 row_mask:0xf bank_mask:0xf
	v_mov_b32_dpp v192, v129 row_ror:15 row_mask:0xf bank_mask:0xf
	v_mov_b32_dpp v219, v125 row_ror:15 row_mask:0xf bank_mask:0xf
	v_mov_b32_dpp v193, v117 row_ror:15 row_mask:0xf bank_mask:0xf
	v_mov_b32_dpp v221, v109 row_ror:15 row_mask:0xf bank_mask:0xf
	s_and_saveexec_b64 s[58:59], s[10:11]
	s_cbranch_execz .LBB0_558
	v_pk_fma_f32 v[178:179], v[148:149], v[178:179], v[160:161]
	v_cndmask_b32_e64 v218, v207, v218, s[16:17]
	v_cndmask_b32_e64 v219, v219, v221, s[16:17]
	v_pk_fma_f32 v[178:179], v[152:153], v[124:125], v[178:179]
	v_cndmask_b32_e64 v221, v192, v193, s[16:17]
	v_pk_fma_f32 v[178:179], v[156:157], v[218:219], v[178:179]
	v_pk_fma_f32 v[176:177], v[132:133], v[176:177], v[144:145]
	v_mul_f32_e32 v207, 0xbdd2d3e7, v179
	v_fmaak_f32 v207, v179, v207, 0xc0135761
	v_mul_f32_e32 v218, 0xbdd2d3e7, v178
	v_mul_f32_e32 v207, v179, v207
	v_fmaak_f32 v218, v178, v218, 0xc0135761
	v_mul_f32_e32 v218, v178, v218
	v_exp_f32_e32 v207, v207
	v_exp_f32_e32 v218, v218
	v_cndmask_b32_e64 v220, v220, v222, s[16:17]
	v_add_f32_e32 v192, 1.0, v207
	v_rcp_f32_e32 v193, v192
	v_add_f32_e32 v192, 1.0, v218
	v_rcp_f32_e32 v192, v192
	v_pk_fma_f32 v[176:177], v[136:137], v[128:129], v[176:177]
	v_pk_fma_f32 v[174:175], v[146:147], v[174:175], v[158:159]
	v_pk_fma_f32 v[176:177], v[140:141], v[220:221], v[176:177]
	v_pk_mul_f32 v[178:179], v[178:179], v[192:193]
	v_cndmask_b32_e64 v184, v183, v184, s[16:17]
	v_pk_mul_f32 v[176:177], v[176:177], v[178:179]
	v_cndmask_b32_e64 v178, v185, v189, s[16:17]
	v_cndmask_b32_e64 v185, v190, v191, s[16:17]
	v_pk_fma_f32 v[174:175], v[150:151], v[170:171], v[174:175]
	v_pk_fma_f32 v[172:173], v[130:131], v[172:173], v[142:143]
	v_pk_fma_f32 v[174:175], v[154:155], v[184:185], v[174:175]
	v_pk_fma_f32 v[172:173], v[134:135], v[126:127], v[172:173]
	v_mul_f32_e32 v179, 0xbdd2d3e7, v175
	v_fmaak_f32 v179, v175, v179, 0xc0135761
	v_mul_f32_e32 v179, v175, v179
	v_exp_f32_e32 v183, v179
	v_mul_f32_e32 v179, 0xbdd2d3e7, v174
	v_fmaak_f32 v179, v174, v179, 0xc0135761
	v_mul_f32_e32 v179, v174, v179
	v_exp_f32_e32 v184, v179
	v_cndmask_b32_e64 v179, v181, v182, s[16:17]
	v_add_f32_e32 v181, 1.0, v183
	v_rcp_f32_e32 v183, v181
	v_add_f32_e32 v181, 1.0, v184
	v_rcp_f32_e32 v182, v181
	v_pk_fma_f32 v[172:173], v[138:139], v[178:179], v[172:173]
	v_pk_mul_f32 v[174:175], v[174:175], v[182:183]
	s_nop 0
	v_pk_mul_f32 v[172:173], v[172:173], v[174:175]
	v_mov_b64_e32 v[174:175], s[26:27]
	v_mad_i64_i32 v[174:175], s[70:71], v180, s57, v[174:175]
	v_cvt_pk_bf16_f32 v172, v172, v173
	v_cvt_pk_bf16_f32 v173, v176, v177
	v_lshl_add_u64 v[174:175], v[214:215], 1, v[174:175]
	global_store_dwordx2 v[174:175], v[172:173], off
; DI unsigned pack_bf16(float lo, float hi) { f32v2 f = {lo, hi}; bf16v2 b = __builtin_convertvector(f, bf16v2); return __builtin_bit_cast(unsigned, b); }
; DI float fexp2(float x) { return __builtin_amdgcn_exp2f(x); }
; DI float rotr1(float v) { return __int_as_float(__builtin_amdgcn_mov_dpp(__float_as_int(v), 0x121, 0xf, 0xf, false)); }
; DI float rotl1(float v) { return __int_as_float(__builtin_amdgcn_mov_dpp(__float_as_int(v), 0x12f, 0xf, 0xf, false)); }
; DI float gelu_tanh(float x) { const float t = x * (1.5957691216057308f + 0.0713548162726009f * x * x); return x * __builtin_amdgcn_rcpf(1.0f + fexp2(-LOG2E * t)); }
;     DI void operator()(const f32x4 (&acc)[2][2][4][2], const pg8::Unit& u, int wr, int wc, int fr, int fq, int ui) const {
;     ...
;                 for (int m = 0; m < 4; ++m) {
;                     float o[4];
; #pragma unroll
;                     for (int e = 0; e < 4; ++e) {
;                         const float pu_s = rotr1(U[m][e]), pg_s = rotr1(G[m][e]), nu_s = rotl1(U[m][e]), ng_s = rotl1(G[m][e]);
;                         const float pu_x = rotr1(U[m > 0 ? m - 1 : 0][e]), pg_x = rotr1(G[m > 0 ? m - 1 : 0][e]);
;                         const float nu_x = rotl1(U[m < 3 ? m + 1 : 3][e]), ng_x = rotl1(G[m < 3 ? m + 1 : 3][e]);
;                         const float pu = fr == 0 ? pu_x : pu_s, pg = fr == 0 ? pg_x : pg_s, nu = fr == 15 ? nu_x : nu_s, ng = fr == 15 ? ng_x : ng_s;
;                         const float yu = bu[e] + pu * wu[0][e] + U[m][e] * wu[1][e] + nu * wu[2][e];
;                         const float yg = bg[e] + pg * wg[0][e] + G[m][e] * wg[1][e] + ng * wg[2][e];
;                         o[e] = yu * gelu_tanh(yg);
;                     }
;                     const bool edge_row = (m == 0 && fr == 0) || (m == 3 && fr == 15);
;                     if (!edge_row) { u32x2 w; w.x = pack_bf16(o[0], o[1]); w.y = pack_bf16(o[2], o[3]); *(u32x2*)(O + (size_t)(rowb + m * 16 + fr) * FF + f0) = w; }
.LBB0_558:
	s_or_b64 exec, exec, s[58:59]
	v_pk_mul_f32 v[176:177], v[98:99], v[122:123] op_sel_hi:[1,0]
	v_mov_b32_dpp v218, v108 row_ror:1 row_mask:0xf bank_mask:0xf
	v_mov_b32_dpp v98, v124 row_ror:1 row_mask:0xf bank_mask:0xf
	v_mov_b32_dpp v222, v109 row_ror:1 row_mask:0xf bank_mask:0xf
	v_mov_b32_dpp v99, v125 row_ror:1 row_mask:0xf bank_mask:0xf
	v_pk_mul_f32 v[100:101], v[100:101], v[122:123] op_sel_hi:[1,0]
	v_cndmask_b32_e64 v99, v222, v99, s[12:13]
	v_cndmask_b32_e64 v98, v218, v98, s[12:13]
	v_pk_mul_f32 v[172:173], v[104:105], v[122:123] op_sel_hi:[1,0]
	v_pk_mul_f32 v[174:175], v[102:103], v[122:123] op_sel_hi:[1,0]
	v_mov_b32_dpp v102, v108 row_ror:15 row_mask:0xf bank_mask:0xf
	v_mov_b32_dpp v104, v128 row_ror:1 row_mask:0xf bank_mask:0xf
	v_mov_b32_dpp v128, v100 row_ror:15 row_mask:0xf bank_mask:0xf
	v_mov_b32_dpp v103, v109 row_ror:15 row_mask:0xf bank_mask:0xf
	v_mov_b32_dpp v223, v101 row_ror:15 row_mask:0xf bank_mask:0xf
	v_pk_fma_f32 v[98:99], v[148:149], v[98:99], v[160:161]
	v_cndmask_b32_e64 v103, v103, v223, s[16:17]
	v_pk_fma_f32 v[98:99], v[152:153], v[108:109], v[98:99]
	v_cndmask_b32_e64 v102, v102, v128, s[16:17]
	v_pk_fma_f32 v[98:99], v[156:157], v[102:103], v[98:99]
	v_mov_b32_dpp v207, v116 row_ror:1 row_mask:0xf bank_mask:0xf
	v_mul_f32_e32 v102, 0xbdd2d3e7, v99
	v_fmaak_f32 v102, v99, v102, 0xc0135761
	v_mul_f32_e32 v102, v99, v102
	v_exp_f32_e32 v102, v102
	v_mov_b32_dpp v221, v117 row_ror:1 row_mask:0xf bank_mask:0xf
	v_mov_b32_dpp v105, v129 row_ror:1 row_mask:0xf bank_mask:0xf
	v_cndmask_b32_e64 v105, v221, v105, s[12:13]
	v_add_f32_e32 v102, 1.0, v102
	v_cndmask_b32_e64 v104, v207, v104, s[12:13]
	v_mov_b32_dpp v184, v106 row_ror:1 row_mask:0xf bank_mask:0xf
	v_mov_b32_dpp v170, v170 row_ror:1 row_mask:0xf bank_mask:0xf
	v_mov_b32_dpp v185, v107 row_ror:1 row_mask:0xf bank_mask:0xf
	v_mov_b32_dpp v171, v171 row_ror:1 row_mask:0xf bank_mask:0xf
	v_rcp_f32_e32 v103, v102
	v_pk_fma_f32 v[104:105], v[132:133], v[104:105], v[144:145]
	v_mul_f32_e32 v102, 0xbdd2d3e7, v98
	v_mov_b32_dpp v219, v116 row_ror:15 row_mask:0xf bank_mask:0xf
	v_mov_b32_dpp v108, v117 row_ror:15 row_mask:0xf bank_mask:0xf
	v_fmaak_f32 v102, v98, v102, 0xc0135761
	v_pk_fma_f32 v[104:105], v[136:137], v[116:117], v[104:105]
	v_cndmask_b32_e64 v117, v185, v171, s[12:13]
	v_cndmask_b32_e64 v116, v184, v170, s[12:13]
	v_mov_b32_dpp v179, v106 row_ror:15 row_mask:0xf bank_mask:0xf
	v_mov_b32_dpp v190, v176 row_ror:15 row_mask:0xf bank_mask:0xf
	v_mov_b32_dpp v183, v107 row_ror:15 row_mask:0xf bank_mask:0xf
	v_mov_b32_dpp v193, v177 row_ror:15 row_mask:0xf bank_mask:0xf
	v_mul_f32_e32 v102, v98, v102
	v_pk_fma_f32 v[116:117], v[146:147], v[116:117], v[158:159]
	v_pk_fma_f32 v[106:107], v[150:151], v[106:107], v[116:117]
	v_cndmask_b32_e64 v117, v183, v193, s[16:17]
	v_cndmask_b32_e64 v116, v179, v190, s[16:17]
	v_exp_f32_e32 v102, v102
	v_pk_fma_f32 v[106:107], v[154:155], v[116:117], v[106:107]
	v_mov_b32_dpp v220, v172 row_ror:15 row_mask:0xf bank_mask:0xf
	v_mul_f32_e32 v116, 0xbdd2d3e7, v107
	v_fmaak_f32 v116, v107, v116, 0xc0135761
	v_mul_f32_e32 v116, v107, v116
	v_add_f32_e32 v102, 1.0, v102
	v_rcp_f32_e32 v102, v102
	v_exp_f32_e32 v116, v116
	v_mov_b32_dpp v129, v173 row_ror:15 row_mask:0xf bank_mask:0xf
	v_cndmask_b32_e64 v109, v108, v129, s[16:17]
	v_pk_mul_f32 v[98:99], v[98:99], v[102:103]
	v_add_f32_e32 v102, 1.0, v116
	v_rcp_f32_e32 v103, v102
	v_mul_f32_e32 v102, 0xbdd2d3e7, v106
	v_fmaak_f32 v102, v106, v102, 0xc0135761
	v_mul_f32_e32 v102, v106, v102
	v_exp_f32_e32 v102, v102
	v_cndmask_b32_e64 v108, v219, v220, s[16:17]
	v_mov_b32_dpp v181, v114 row_ror:1 row_mask:0xf bank_mask:0xf
	v_mov_b32_dpp v126, v126 row_ror:1 row_mask:0xf bank_mask:0xf
	v_add_f32_e32 v102, 1.0, v102
	v_rcp_f32_e32 v102, v102
	v_mov_b32_dpp v191, v115 row_ror:1 row_mask:0xf bank_mask:0xf
	v_mov_b32_dpp v127, v127 row_ror:1 row_mask:0xf bank_mask:0xf
	v_pk_fma_f32 v[104:105], v[140:141], v[108:109], v[104:105]
	v_mov_b32_dpp v178, v114 row_ror:15 row_mask:0xf bank_mask:0xf
	v_pk_mul_f32 v[98:99], v[104:105], v[98:99]
	v_cndmask_b32_e64 v105, v191, v127, s[12:13]
	v_cndmask_b32_e64 v104, v181, v126, s[12:13]
	v_mov_b32_dpp v189, v174 row_ror:15 row_mask:0xf bank_mask:0xf
	v_mov_b32_dpp v182, v115 row_ror:15 row_mask:0xf bank_mask:0xf
	v_mov_b32_dpp v192, v175 row_ror:15 row_mask:0xf bank_mask:0xf
	v_pk_fma_f32 v[104:105], v[130:131], v[104:105], v[142:143]
	v_mov_b32_dpp v126, v100 row_ror:1 row_mask:0xf bank_mask:0xf
	v_mov_b32_dpp v127, v101 row_ror:1 row_mask:0xf bank_mask:0xf
	v_pk_fma_f32 v[104:105], v[134:135], v[114:115], v[104:105]
	v_cndmask_b32_e64 v109, v182, v192, s[16:17]
	v_cndmask_b32_e64 v108, v178, v189, s[16:17]
	v_pk_mul_f32 v[102:103], v[106:107], v[102:103]
	v_cndmask_b32_e64 v107, v127, v222, s[12:13]
	v_cndmask_b32_e64 v106, v126, v218, s[12:13]
	v_pk_fma_f32 v[104:105], v[138:139], v[108:109], v[104:105]
	v_mov_b32_dpp v108, v112 row_ror:15 row_mask:0xf bank_mask:0xf
	v_mov_b32_dpp v109, v113 row_ror:15 row_mask:0xf bank_mask:0xf
	v_pk_fma_f32 v[106:107], v[148:149], v[106:107], v[160:161]
	v_mov_b32_dpp v116, v176 row_ror:1 row_mask:0xf bank_mask:0xf
	v_pk_fma_f32 v[100:101], v[152:153], v[100:101], v[106:107]
	v_cndmask_b32_e64 v107, v223, v109, s[16:17]
	v_cndmask_b32_e64 v106, v128, v108, s[16:17]
	v_pk_fma_f32 v[100:101], v[156:157], v[106:107], v[100:101]
	v_mov_b32_dpp v117, v177 row_ror:1 row_mask:0xf bank_mask:0xf
	v_mul_f32_e32 v106, 0xbdd2d3e7, v101
	v_fmaak_f32 v106, v101, v106, 0xc0135761
	v_mul_f32_e32 v106, v101, v106
	v_exp_f32_e32 v114, v106
	v_cndmask_b32_e64 v185, v117, v185, s[12:13]
; DI unsigned pack_bf16(float lo, float hi) { f32v2 f = {lo, hi}; bf16v2 b = __builtin_convertvector(f, bf16v2); return __builtin_bit_cast(unsigned, b); }
; DI float fexp2(float x) { return __builtin_amdgcn_exp2f(x); }
; DI float rotr1(float v) { return __int_as_float(__builtin_amdgcn_mov_dpp(__float_as_int(v), 0x121, 0xf, 0xf, false)); }
; DI float rotl1(float v) { return __int_as_float(__builtin_amdgcn_mov_dpp(__float_as_int(v), 0x12f, 0xf, 0xf, false)); }
; DI float gelu_tanh(float x) { const float t = x * (1.5957691216057308f + 0.0713548162726009f * x * x); return x * __builtin_amdgcn_rcpf(1.0f + fexp2(-LOG2E * t)); }
;     DI void operator()(const f32x4 (&acc)[2][2][4][2], const pg8::Unit& u, int wr, int wc, int fr, int fq, int ui) const {
;     ...
;                 for (int m = 0; m < 4; ++m) {
;                     float o[4];
; #pragma unroll
;                     for (int e = 0; e < 4; ++e) {
;                         const float pu_s = rotr1(U[m][e]), pg_s = rotr1(G[m][e]), nu_s = rotl1(U[m][e]), ng_s = rotl1(G[m][e]);
;                         const float pu_x = rotr1(U[m > 0 ? m - 1 : 0][e]), pg_x = rotr1(G[m > 0 ? m - 1 : 0][e]);
;                         const float nu_x = rotl1(U[m < 3 ? m + 1 : 3][e]), ng_x = rotl1(G[m < 3 ? m + 1 : 3][e]);
;                         const float pu = fr == 0 ? pu_x : pu_s, pg = fr == 0 ? pg_x : pg_s, nu = fr == 15 ? nu_x : nu_s, ng = fr == 15 ? ng_x : ng_s;
;                         const float yu = bu[e] + pu * wu[0][e] + U[m][e] * wu[1][e] + nu * wu[2][e];
;                         const float yg = bg[e] + pg * wg[0][e] + G[m][e] * wg[1][e] + ng * wg[2][e];
;                         o[e] = yu * gelu_tanh(yg);
;                     }
;                     const bool edge_row = (m == 0 && fr == 0) || (m == 3 && fr == 15);
;                     if (!edge_row) { u32x2 w; w.x = pack_bf16(o[0], o[1]); w.y = pack_bf16(o[2], o[3]); *(u32x2*)(O + (size_t)(rowb + m * 16 + fr) * FF + f0) = w; }
	v_cndmask_b32_e64 v184, v116, v184, s[12:13]
	v_pk_mul_f32 v[102:103], v[104:105], v[102:103]
	v_add_f32_e32 v114, 1.0, v114
	v_rcp_f32_e32 v179, v114
	v_mul_f32_e32 v114, 0xbdd2d3e7, v100
	v_fmaak_f32 v114, v100, v114, 0xc0135761
	v_mul_f32_e32 v114, v100, v114
	v_exp_f32_e32 v114, v114
	v_mov_b32_dpp v104, v110 row_ror:15 row_mask:0xf bank_mask:0xf
	v_mov_b32_dpp v105, v111 row_ror:15 row_mask:0xf bank_mask:0xf
	v_pk_fma_f32 v[184:185], v[146:147], v[184:185], v[158:159]
	v_add_f32_e32 v114, 1.0, v114
	v_pk_fma_f32 v[176:177], v[150:151], v[176:177], v[184:185]
	v_cndmask_b32_e64 v185, v193, v105, s[16:17]
	v_cndmask_b32_e64 v184, v190, v104, s[16:17]
	v_pk_fma_f32 v[176:177], v[154:155], v[184:185], v[176:177]
	v_rcp_f32_e32 v178, v114
	v_mul_f32_e32 v114, 0xbdd2d3e7, v177
	v_fmaak_f32 v114, v177, v114, 0xc0135761
	v_mul_f32_e32 v114, v177, v114
	v_mov_b32_dpp v125, v172 row_ror:1 row_mask:0xf bank_mask:0xf
	v_mov_b32_dpp v128, v173 row_ror:1 row_mask:0xf bank_mask:0xf
	v_exp_f32_e32 v114, v114
	v_cndmask_b32_e64 v183, v128, v221, s[12:13]
	v_cndmask_b32_e64 v182, v125, v207, s[12:13]
	v_mov_b32_dpp v106, v120 row_ror:15 row_mask:0xf bank_mask:0xf
	v_mov_b32_dpp v107, v121 row_ror:15 row_mask:0xf bank_mask:0xf
	v_pk_fma_f32 v[182:183], v[132:133], v[182:183], v[144:145]
	v_pk_mul_f32 v[100:101], v[100:101], v[178:179]
	v_pk_fma_f32 v[172:173], v[136:137], v[172:173], v[182:183]
	v_cndmask_b32_e64 v183, v129, v107, s[16:17]
	v_cndmask_b32_e64 v182, v220, v106, s[16:17]
	v_pk_fma_f32 v[172:173], v[140:141], v[182:183], v[172:173]
	v_add_f32_e32 v114, 1.0, v114
	v_pk_mul_f32 v[100:101], v[172:173], v[100:101]
	v_rcp_f32_e32 v173, v114
	v_mul_f32_e32 v114, 0xbdd2d3e7, v176
	v_fmaak_f32 v114, v176, v114, 0xc0135761
	v_mul_f32_e32 v114, v176, v114
	v_exp_f32_e32 v114, v114
	v_cvt_pk_bf16_f32 v102, v102, v103
	v_cvt_pk_bf16_f32 v103, v98, v99
	v_or_b32_e32 v98, 16, v180
	v_mov_b64_e32 v[170:171], s[26:27]
	v_add_f32_e32 v114, 1.0, v114
	v_mad_i64_i32 v[98:99], s[58:59], v98, s57, v[170:171]
	v_mov_b32_dpp v115, v174 row_ror:1 row_mask:0xf bank_mask:0xf
	v_mov_b32_dpp v124, v175 row_ror:1 row_mask:0xf bank_mask:0xf
	v_rcp_f32_e32 v172, v114
	v_lshl_add_u64 v[98:99], v[98:99], 0, v[168:169]
	v_cndmask_b32_e64 v179, v124, v191, s[12:13]
	v_cndmask_b32_e64 v178, v115, v181, s[12:13]
	global_store_dwordx2 v[98:99], v[102:103], off
	v_mov_b32_dpp v102, v118 row_ror:15 row_mask:0xf bank_mask:0xf
	v_mov_b32_dpp v103, v119 row_ror:15 row_mask:0xf bank_mask:0xf
	v_pk_fma_f32 v[178:179], v[130:131], v[178:179], v[142:143]
	v_pk_mul_f32 v[172:173], v[176:177], v[172:173]
	v_pk_fma_f32 v[174:175], v[134:135], v[174:175], v[178:179]
	v_cndmask_b32_e64 v179, v192, v103, s[16:17]
	v_cndmask_b32_e64 v178, v189, v102, s[16:17]
	v_pk_fma_f32 v[174:175], v[138:139], v[178:179], v[174:175]
	v_mov_b32_dpp v129, v118 row_ror:1 row_mask:0xf bank_mask:0xf
	v_pk_mul_f32 v[172:173], v[174:175], v[172:173]
	v_mov_b32_dpp v174, v121 row_ror:1 row_mask:0xf bank_mask:0xf
	v_cvt_pk_bf16_f32 v172, v172, v173
	v_cvt_pk_bf16_f32 v173, v100, v101
	v_or_b32_e32 v100, 32, v180
	v_mad_i64_i32 v[100:101], s[58:59], v100, s57, v[170:171]
	v_lshl_add_u64 v[100:101], v[100:101], 0, v[168:169]
	global_store_dwordx2 v[100:101], v[172:173], off
	v_mov_b32_dpp v168, v110 row_ror:1 row_mask:0xf bank_mask:0xf
	v_mov_b32_dpp v170, v119 row_ror:1 row_mask:0xf bank_mask:0xf
	v_mov_b32_dpp v169, v111 row_ror:1 row_mask:0xf bank_mask:0xf
	v_mov_b32_dpp v171, v120 row_ror:1 row_mask:0xf bank_mask:0xf
	v_mov_b32_dpp v172, v112 row_ror:1 row_mask:0xf bank_mask:0xf
	v_mov_b32_dpp v173, v113 row_ror:1 row_mask:0xf bank_mask:0xf
	v_or_b32_e32 v114, 48, v180
	s_and_saveexec_b64 s[58:59], s[14:15]
	s_cbranch_execz .LBB0_560
	v_cndmask_b32_e64 v127, v173, v127, s[12:13]
	v_cndmask_b32_e64 v126, v172, v126, s[12:13]
	v_pk_fma_f32 v[126:127], v[148:149], v[126:127], v[160:161]
	v_cndmask_b32_e64 v175, v174, v128, s[12:13]
	v_pk_fma_f32 v[112:113], v[152:153], v[112:113], v[126:127]
	v_cndmask_b32_e64 v174, v171, v125, s[12:13]
	v_pk_fma_f32 v[108:109], v[156:157], v[108:109], v[112:113]
	s_nop 0
	v_mul_f32_e32 v112, 0xbdd2d3e7, v109
	v_fmaak_f32 v112, v109, v112, 0xc0135761
	v_mul_f32_e32 v113, 0xbdd2d3e7, v108
	v_mul_f32_e32 v112, v109, v112
	v_fmaak_f32 v113, v108, v113, 0xc0135761
	v_mul_f32_e32 v113, v108, v113
	v_exp_f32_e32 v112, v112
	v_exp_f32_e32 v126, v113
	v_add_f32_e32 v112, 1.0, v112
	v_rcp_f32_e32 v113, v112
	v_add_f32_e32 v112, 1.0, v126
	v_rcp_f32_e32 v112, v112
	v_pk_fma_f32 v[126:127], v[132:133], v[174:175], v[144:145]
	v_pk_mul_f32 v[108:109], v[108:109], v[112:113]
	v_cndmask_b32_e64 v113, v169, v117, s[12:13]
	v_cndmask_b32_e64 v112, v168, v116, s[12:13]
	v_pk_fma_f32 v[112:113], v[146:147], v[112:113], v[158:159]
	v_pk_fma_f32 v[120:121], v[136:137], v[120:121], v[126:127]
	v_pk_fma_f32 v[110:111], v[150:151], v[110:111], v[112:113]
	v_pk_fma_f32 v[106:107], v[140:141], v[106:107], v[120:121]
	v_pk_fma_f32 v[104:105], v[154:155], v[104:105], v[110:111]
	v_pk_mul_f32 v[106:107], v[106:107], v[108:109]
	v_mul_f32_e32 v108, 0xbdd2d3e7, v105
	v_fmaak_f32 v108, v105, v108, 0xc0135761
	v_mul_f32_e32 v108, v105, v108
	v_exp_f32_e32 v110, v108
	v_mul_f32_e32 v108, 0xbdd2d3e7, v104
	v_fmaak_f32 v108, v104, v108, 0xc0135761
	v_mul_f32_e32 v108, v104, v108
	v_exp_f32_e32 v112, v108
	v_add_f32_e32 v110, 1.0, v110
	v_rcp_f32_e32 v111, v110
	v_cndmask_b32_e64 v109, v170, v124, s[12:13]
	v_add_f32_e32 v110, 1.0, v112
	v_rcp_f32_e32 v110, v110
	v_cndmask_b32_e64 v108, v129, v115, s[12:13]
	v_pk_fma_f32 v[108:109], v[130:131], v[108:109], v[142:143]
	v_pk_mul_f32 v[104:105], v[104:105], v[110:111]
	v_pk_fma_f32 v[108:109], v[134:135], v[118:119], v[108:109]
	s_nop 0
	v_pk_fma_f32 v[102:103], v[138:139], v[102:103], v[108:109]
	s_nop 0
	v_pk_mul_f32 v[102:103], v[102:103], v[104:105]
	v_mov_b64_e32 v[104:105], s[26:27]
	v_mad_i64_i32 v[104:105], s[70:71], v114, s57, v[104:105]
	v_cvt_pk_bf16_f32 v102, v102, v103
	v_cvt_pk_bf16_f32 v103, v106, v107
	v_lshl_add_u64 v[104:105], v[214:215], 1, v[104:105]
	global_store_dwordx2 v[104:105], v[102:103], off

; DI unsigned pack_bf16(float lo, float hi) { f32v2 f = {lo, hi}; bf16v2 b = __builtin_convertvector(f, bf16v2); return __builtin_bit_cast(unsigned, b); }
; DI float fexp2(float x) { return __builtin_amdgcn_exp2f(x); }
; DI float rotr1(float v) { return __int_as_float(__builtin_amdgcn_mov_dpp(__float_as_int(v), 0x121, 0xf, 0xf, false)); }
; DI float rotl1(float v) { return __int_as_float(__builtin_amdgcn_mov_dpp(__float_as_int(v), 0x12f, 0xf, 0xf, false)); }
; DI float gelu_tanh(float x) { const float t = x * (1.5957691216057308f + 0.0713548162726009f * x * x); return x * __builtin_amdgcn_rcpf(1.0f + fexp2(-LOG2E * t)); }
;     DI void operator()(const f32x4 (&acc)[2][2][4][2], const pg8::Unit& u, int wr, int wc, int fr, int fq, int ui) const {
;     ...
;                 for (int m = 0; m < 4; ++m) { const float s_ = tab[ai * 128 + m * 16]; U[m] = acc[ai][0][m][n] * s_; G[m] = acc[ai][1][m][n] * s_; }
;     ...
;                 for (int m = 0; m < 4; ++m) {
;                     float o[4];
; #pragma unroll
;                     for (int e = 0; e < 4; ++e) {
;                         const float pu_s = rotr1(U[m][e]), pg_s = rotr1(G[m][e]), nu_s = rotl1(U[m][e]), ng_s = rotl1(G[m][e]);
;                         const float pu_x = rotr1(U[m > 0 ? m - 1 : 0][e]), pg_x = rotr1(G[m > 0 ? m - 1 : 0][e]);
;                         const float nu_x = rotl1(U[m < 3 ? m + 1 : 3][e]), ng_x = rotl1(G[m < 3 ? m + 1 : 3][e]);
;                         const float pu = fr == 0 ? pu_x : pu_s, pg = fr == 0 ? pg_x : pg_s, nu = fr == 15 ? nu_x : nu_s, ng = fr == 15 ? ng_x : ng_s;
;                         const float yu = bu[e] + pu * wu[0][e] + U[m][e] * wu[1][e] + nu * wu[2][e];
;                         const float yg = bg[e] + pg * wg[0][e] + G[m][e] * wg[1][e] + ng * wg[2][e];
;                         o[e] = yu * gelu_tanh(yg);
;                     }
;                     const bool edge_row = (m == 0 && fr == 0) || (m == 3 && fr == 15);
;                     if (!edge_row) { u32x2 w; w.x = pack_bf16(o[0], o[1]); w.y = pack_bf16(o[2], o[3]); *(u32x2*)(O + (size_t)(rowb + m * 16 + fr) * FF + f0) = w; }
.LBB0_564:
	s_or_b64 exec, exec, s[58:59]
	v_mov_b32_e32 v216, v217
	v_mov_b32_e32 v102, v217
	v_mov_b32_e32 v103, v217
	v_pk_mul_f32 v[84:85], v[84:85], v[102:103]
	v_pk_mul_f32 v[82:83], v[82:83], v[216:217]
	v_pk_mul_f32 v[76:77], v[76:77], v[102:103]
	v_pk_mul_f32 v[74:75], v[74:75], v[216:217]
	v_mov_b32_dpp v102, v94 row_ror:1 row_mask:0xf bank_mask:0xf
	v_mov_b32_dpp v104, v90 row_ror:1 row_mask:0xf bank_mask:0xf
	v_mov_b32_dpp v115, v94 row_ror:15 row_mask:0xf bank_mask:0xf
	v_mov_b32_dpp v112, v90 row_ror:15 row_mask:0xf bank_mask:0xf
	v_mov_b32_dpp v116, v82 row_ror:15 row_mask:0xf bank_mask:0xf
	v_mov_b32_dpp v113, v74 row_ror:15 row_mask:0xf bank_mask:0xf
	v_mov_b32_dpp v103, v95 row_ror:1 row_mask:0xf bank_mask:0xf
	v_mov_b32_dpp v105, v91 row_ror:1 row_mask:0xf bank_mask:0xf
	v_mov_b32_dpp v110, v95 row_ror:15 row_mask:0xf bank_mask:0xf
	v_mov_b32_dpp v117, v91 row_ror:15 row_mask:0xf bank_mask:0xf
	v_mov_b32_dpp v111, v83 row_ror:15 row_mask:0xf bank_mask:0xf
	v_mov_b32_dpp v118, v75 row_ror:15 row_mask:0xf bank_mask:0xf
	v_mov_b32_dpp v106, v96 row_ror:1 row_mask:0xf bank_mask:0xf
	v_mov_b32_dpp v108, v92 row_ror:1 row_mask:0xf bank_mask:0xf
	v_mov_b32_dpp v126, v96 row_ror:15 row_mask:0xf bank_mask:0xf
	v_mov_b32_dpp v121, v92 row_ror:15 row_mask:0xf bank_mask:0xf
	v_mov_b32_dpp v128, v84 row_ror:15 row_mask:0xf bank_mask:0xf
	v_mov_b32_dpp v124, v76 row_ror:15 row_mask:0xf bank_mask:0xf
	v_mov_b32_dpp v107, v97 row_ror:1 row_mask:0xf bank_mask:0xf
	v_mov_b32_dpp v109, v93 row_ror:1 row_mask:0xf bank_mask:0xf
	v_mov_b32_dpp v119, v97 row_ror:15 row_mask:0xf bank_mask:0xf
	v_mov_b32_dpp v125, v93 row_ror:15 row_mask:0xf bank_mask:0xf
	v_mov_b32_dpp v120, v85 row_ror:15 row_mask:0xf bank_mask:0xf
	v_mov_b32_dpp v127, v77 row_ror:15 row_mask:0xf bank_mask:0xf
	s_and_saveexec_b64 s[58:59], s[10:11]
	s_xor_b64 s[58:59], exec, s[58:59]
	s_cbranch_execz .LBB0_566
	v_pk_fma_f32 v[108:109], v[52:53], v[108:109], v[64:65]
	v_cndmask_b32_e64 v124, v121, v124, s[16:17]
	v_cndmask_b32_e64 v125, v125, v127, s[16:17]
	v_pk_fma_f32 v[108:109], v[56:57], v[92:93], v[108:109]
	v_cndmask_b32_e64 v127, v119, v120, s[16:17]
	v_pk_fma_f32 v[108:109], v[60:61], v[124:125], v[108:109]
	v_pk_fma_f32 v[106:107], v[36:37], v[106:107], v[48:49]
	v_mul_f32_e32 v121, 0xbdd2d3e7, v109
	v_fmaak_f32 v121, v109, v121, 0xc0135761
	v_mul_f32_e32 v124, 0xbdd2d3e7, v108
	v_mul_f32_e32 v121, v109, v121
	v_fmaak_f32 v124, v108, v124, 0xc0135761
	v_mul_f32_e32 v124, v108, v124
	v_exp_f32_e32 v121, v121
	v_exp_f32_e32 v124, v124
	v_pk_fma_f32 v[104:105], v[50:51], v[104:105], v[62:63]
	v_add_f32_e32 v119, 1.0, v121
	v_rcp_f32_e32 v121, v119
	v_add_f32_e32 v119, 1.0, v124
	v_rcp_f32_e32 v120, v119
	v_cndmask_b32_e64 v126, v126, v128, s[16:17]
	v_pk_fma_f32 v[106:107], v[40:41], v[96:97], v[106:107]
	v_cndmask_b32_e64 v112, v112, v113, s[16:17]
	v_cndmask_b32_e64 v113, v117, v118, s[16:17]
	v_pk_fma_f32 v[104:105], v[54:55], v[90:91], v[104:105]
	v_pk_fma_f32 v[106:107], v[44:45], v[126:127], v[106:107]
	v_pk_mul_f32 v[108:109], v[108:109], v[120:121]
	v_pk_fma_f32 v[104:105], v[58:59], v[112:113], v[104:105]
	v_pk_mul_f32 v[106:107], v[106:107], v[108:109]
	v_mul_f32_e32 v109, 0xbdd2d3e7, v105
	v_fmaak_f32 v109, v105, v109, 0xc0135761
	v_mul_f32_e32 v109, v105, v109
	v_exp_f32_e32 v112, v109
	v_mul_f32_e32 v109, 0xbdd2d3e7, v104
	v_fmaak_f32 v109, v104, v109, 0xc0135761
	v_mul_f32_e32 v109, v104, v109
	v_exp_f32_e32 v113, v109
	v_cndmask_b32_e64 v109, v110, v111, s[16:17]
	v_add_f32_e32 v110, 1.0, v112
	v_rcp_f32_e32 v111, v110
	v_add_f32_e32 v110, 1.0, v113
	v_rcp_f32_e32 v110, v110
	v_pk_fma_f32 v[102:103], v[34:35], v[102:103], v[46:47]
	v_cndmask_b32_e64 v108, v115, v116, s[16:17]
	v_pk_fma_f32 v[102:103], v[38:39], v[94:95], v[102:103]
	v_pk_mul_f32 v[104:105], v[104:105], v[110:111]
	v_pk_fma_f32 v[102:103], v[42:43], v[108:109], v[102:103]
	s_nop 0
	v_pk_mul_f32 v[102:103], v[102:103], v[104:105]
	v_mov_b64_e32 v[104:105], s[26:27]
	v_mad_i64_i32 v[104:105], s[70:71], v239, s57, v[104:105]
	v_cvt_pk_bf16_f32 v102, v102, v103
	v_cvt_pk_bf16_f32 v103, v106, v107
	v_lshl_add_u64 v[104:105], v[214:215], 1, v[104:105]
	global_store_dwordx2 v[104:105], v[102:103], off offset:8
; DI unsigned pack_bf16(float lo, float hi) { f32v2 f = {lo, hi}; bf16v2 b = __builtin_convertvector(f, bf16v2); return __builtin_bit_cast(unsigned, b); }
; DI float fexp2(float x) { return __builtin_amdgcn_exp2f(x); }
; DI float rotr1(float v) { return __int_as_float(__builtin_amdgcn_mov_dpp(__float_as_int(v), 0x121, 0xf, 0xf, false)); }
; DI float rotl1(float v) { return __int_as_float(__builtin_amdgcn_mov_dpp(__float_as_int(v), 0x12f, 0xf, 0xf, false)); }
; DI float gelu_tanh(float x) { const float t = x * (1.5957691216057308f + 0.0713548162726009f * x * x); return x * __builtin_amdgcn_rcpf(1.0f + fexp2(-LOG2E * t)); }
;     DI void operator()(const f32x4 (&acc)[2][2][4][2], const pg8::Unit& u, int wr, int wc, int fr, int fq, int ui) const {
;     ...
;                 for (int m = 0; m < 4; ++m) { const float s_ = tab[ai * 128 + m * 16]; U[m] = acc[ai][0][m][n] * s_; G[m] = acc[ai][1][m][n] * s_; }
;     ...
;                 for (int m = 0; m < 4; ++m) {
;                     float o[4];
; #pragma unroll
;                     for (int e = 0; e < 4; ++e) {
;                         const float pu_s = rotr1(U[m][e]), pg_s = rotr1(G[m][e]), nu_s = rotl1(U[m][e]), ng_s = rotl1(G[m][e]);
;                         const float pu_x = rotr1(U[m > 0 ? m - 1 : 0][e]), pg_x = rotr1(G[m > 0 ? m - 1 : 0][e]);
;                         const float nu_x = rotl1(U[m < 3 ? m + 1 : 3][e]), ng_x = rotl1(G[m < 3 ? m + 1 : 3][e]);
;                         const float pu = fr == 0 ? pu_x : pu_s, pg = fr == 0 ? pg_x : pg_s, nu = fr == 15 ? nu_x : nu_s, ng = fr == 15 ? ng_x : ng_s;
;                         const float yu = bu[e] + pu * wu[0][e] + U[m][e] * wu[1][e] + nu * wu[2][e];
;                         const float yg = bg[e] + pg * wg[0][e] + G[m][e] * wg[1][e] + ng * wg[2][e];
;                         o[e] = yu * gelu_tanh(yg);
;                     }
;                     const bool edge_row = (m == 0 && fr == 0) || (m == 3 && fr == 15);
;                     if (!edge_row) { u32x2 w; w.x = pack_bf16(o[0], o[1]); w.y = pack_bf16(o[2], o[3]); *(u32x2*)(O + (size_t)(rowb + m * 16 + fr) * FF + f0) = w; }
.LBB0_566:
	s_andn2_saveexec_b64 s[58:59], s[58:59]
	s_or_b64 exec, exec, s[58:59]
	v_mov_b32_e32 v187, v186
	v_mov_b32_e32 v102, v186
	v_mov_b32_e32 v103, v186
	v_pk_mul_f32 v[104:105], v[72:73], v[102:103]
	v_pk_mul_f32 v[72:73], v[68:69], v[102:103]
	v_pk_mul_f32 v[102:103], v[66:67], v[186:187]
	v_mov_b32_dpp v120, v76 row_ror:1 row_mask:0xf bank_mask:0xf
	v_mov_b32_dpp v66, v92 row_ror:1 row_mask:0xf bank_mask:0xf
	v_mov_b32_dpp v92, v77 row_ror:1 row_mask:0xf bank_mask:0xf
	v_mov_b32_dpp v67, v93 row_ror:1 row_mask:0xf bank_mask:0xf
	v_cndmask_b32_e64 v67, v92, v67, s[12:13]
	v_cndmask_b32_e64 v66, v120, v66, s[12:13]
	v_mov_b32_dpp v68, v76 row_ror:15 row_mask:0xf bank_mask:0xf
	v_mov_b32_dpp v125, v72 row_ror:15 row_mask:0xf bank_mask:0xf
	v_mov_b32_dpp v69, v77 row_ror:15 row_mask:0xf bank_mask:0xf
	v_mov_b32_dpp v127, v73 row_ror:15 row_mask:0xf bank_mask:0xf
	v_pk_fma_f32 v[66:67], v[52:53], v[66:67], v[64:65]
	v_cndmask_b32_e64 v69, v69, v127, s[16:17]
	v_pk_fma_f32 v[66:67], v[56:57], v[76:77], v[66:67]
	v_cndmask_b32_e64 v68, v68, v125, s[16:17]
	v_pk_fma_f32 v[66:67], v[60:61], v[68:69], v[66:67]
	v_mov_b32_dpp v106, v74 row_ror:1 row_mask:0xf bank_mask:0xf
	v_mul_f32_e32 v68, 0xbdd2d3e7, v67
	v_fmaak_f32 v68, v67, v68, 0xc0135761
	v_mul_f32_e32 v68, v67, v68
	v_exp_f32_e32 v68, v68
	v_mov_b32_dpp v90, v90 row_ror:1 row_mask:0xf bank_mask:0xf
	v_mov_b32_dpp v113, v75 row_ror:1 row_mask:0xf bank_mask:0xf
	v_mov_b32_dpp v91, v91 row_ror:1 row_mask:0xf bank_mask:0xf
	v_add_f32_e32 v68, 1.0, v68
	v_rcp_f32_e32 v69, v68
	v_mul_f32_e32 v68, 0xbdd2d3e7, v66
	v_fmaak_f32 v68, v66, v68, 0xc0135761
	v_cndmask_b32_e64 v91, v113, v91, s[12:13]
	v_cndmask_b32_e64 v90, v106, v90, s[12:13]
	v_mov_b32_dpp v109, v74 row_ror:15 row_mask:0xf bank_mask:0xf
	v_mov_b32_dpp v111, v102 row_ror:15 row_mask:0xf bank_mask:0xf
	v_mov_b32_dpp v116, v75 row_ror:15 row_mask:0xf bank_mask:0xf
	v_mov_b32_dpp v118, v103 row_ror:15 row_mask:0xf bank_mask:0xf
	v_mul_f32_e32 v68, v66, v68
	v_pk_fma_f32 v[90:91], v[50:51], v[90:91], v[62:63]
	v_pk_fma_f32 v[74:75], v[54:55], v[74:75], v[90:91]
	v_cndmask_b32_e64 v91, v116, v118, s[16:17]
	v_cndmask_b32_e64 v90, v109, v111, s[16:17]
	v_exp_f32_e32 v68, v68
	v_pk_fma_f32 v[74:75], v[58:59], v[90:91], v[74:75]
	v_mov_b32_dpp v119, v84 row_ror:1 row_mask:0xf bank_mask:0xf
	v_mul_f32_e32 v90, 0xbdd2d3e7, v75
	v_fmaak_f32 v90, v75, v90, 0xc0135761
	v_mul_f32_e32 v90, v75, v90
	v_add_f32_e32 v68, 1.0, v68
	v_rcp_f32_e32 v68, v68
	v_exp_f32_e32 v90, v90
	v_mov_b32_dpp v96, v96 row_ror:1 row_mask:0xf bank_mask:0xf
	v_mov_b32_dpp v126, v85 row_ror:1 row_mask:0xf bank_mask:0xf
	v_pk_mul_f32 v[66:67], v[66:67], v[68:69]
	v_add_f32_e32 v68, 1.0, v90
	v_rcp_f32_e32 v69, v68
	v_mul_f32_e32 v68, 0xbdd2d3e7, v74
	v_fmaak_f32 v68, v74, v68, 0xc0135761
	v_mul_f32_e32 v68, v74, v68
	v_exp_f32_e32 v68, v68
	v_mov_b32_dpp v76, v97 row_ror:1 row_mask:0xf bank_mask:0xf
	v_cndmask_b32_e64 v77, v126, v76, s[12:13]
	v_cndmask_b32_e64 v76, v119, v96, s[12:13]
	v_add_f32_e32 v68, 1.0, v68
	v_mov_b32_dpp v121, v84 row_ror:15 row_mask:0xf bank_mask:0xf
	v_mov_b32_dpp v124, v104 row_ror:15 row_mask:0xf bank_mask:0xf
	v_mov_b32_dpp v93, v85 row_ror:15 row_mask:0xf bank_mask:0xf
	v_mov_b32_dpp v128, v105 row_ror:15 row_mask:0xf bank_mask:0xf
	v_pk_fma_f32 v[76:77], v[36:37], v[76:77], v[48:49]
	v_rcp_f32_e32 v68, v68
	v_pk_fma_f32 v[76:77], v[40:41], v[84:85], v[76:77]
	v_cndmask_b32_e64 v85, v93, v128, s[16:17]
	v_cndmask_b32_e64 v84, v121, v124, s[16:17]
	v_pk_fma_f32 v[76:77], v[44:45], v[84:85], v[76:77]
	v_mov_b32_dpp v85, v72 row_ror:1 row_mask:0xf bank_mask:0xf
	v_mov_b32_dpp v90, v73 row_ror:1 row_mask:0xf bank_mask:0xf
	v_cndmask_b32_e64 v93, v90, v92, s[12:13]
	v_cndmask_b32_e64 v92, v85, v120, s[12:13]
	v_pk_mul_f32 v[68:69], v[74:75], v[68:69]
	v_mov_b32_dpp v74, v80 row_ror:15 row_mask:0xf bank_mask:0xf
	v_mov_b32_dpp v75, v81 row_ror:15 row_mask:0xf bank_mask:0xf
	v_pk_fma_f32 v[92:93], v[52:53], v[92:93], v[64:65]
	v_mov_b32_dpp v108, v82 row_ror:1 row_mask:0xf bank_mask:0xf
	v_pk_fma_f32 v[72:73], v[56:57], v[72:73], v[92:93]
	v_cndmask_b32_e64 v93, v127, v75, s[16:17]
	v_cndmask_b32_e64 v92, v125, v74, s[16:17]
	v_pk_fma_f32 v[92:93], v[60:61], v[92:93], v[72:73]
	v_mov_b32_dpp v94, v94 row_ror:1 row_mask:0xf bank_mask:0xf
	v_mul_f32_e32 v72, 0xbdd2d3e7, v93
	v_fmaak_f32 v72, v93, v72, 0xc0135761
	v_mul_f32_e32 v72, v93, v72
	v_mov_b32_dpp v112, v83 row_ror:1 row_mask:0xf bank_mask:0xf
	v_mov_b32_dpp v95, v95 row_ror:1 row_mask:0xf bank_mask:0xf
	v_pk_mul_f32 v[66:67], v[76:77], v[66:67]
	v_cndmask_b32_e64 v76, v108, v94, s[12:13]
	v_exp_f32_e32 v94, v72
	v_pk_mul_f32 v[70:71], v[70:71], v[186:187]
	v_cndmask_b32_e64 v77, v112, v95, s[12:13]
	v_mov_b32_dpp v107, v82 row_ror:15 row_mask:0xf bank_mask:0xf
	v_mov_b32_dpp v110, v70 row_ror:15 row_mask:0xf bank_mask:0xf
	v_mov_b32_dpp v115, v83 row_ror:15 row_mask:0xf bank_mask:0xf
	v_mov_b32_dpp v117, v71 row_ror:15 row_mask:0xf bank_mask:0xf
	v_pk_fma_f32 v[76:77], v[34:35], v[76:77], v[46:47]
	v_add_f32_e32 v94, 1.0, v94
	v_pk_fma_f32 v[76:77], v[38:39], v[82:83], v[76:77]
	v_cndmask_b32_e64 v83, v115, v117, s[16:17]
	v_cndmask_b32_e64 v82, v107, v110, s[16:17]
	v_pk_fma_f32 v[76:77], v[42:43], v[82:83], v[76:77]
	v_rcp_f32_e32 v95, v94
	v_pk_mul_f32 v[68:69], v[76:77], v[68:69]
	v_mov_b32_dpp v77, v102 row_ror:1 row_mask:0xf bank_mask:0xf
; DI unsigned pack_bf16(float lo, float hi) { f32v2 f = {lo, hi}; bf16v2 b = __builtin_convertvector(f, bf16v2); return __builtin_bit_cast(unsigned, b); }
; DI float fexp2(float x) { return __builtin_amdgcn_exp2f(x); }
; DI float rotr1(float v) { return __int_as_float(__builtin_amdgcn_mov_dpp(__float_as_int(v), 0x121, 0xf, 0xf, false)); }
; DI float rotl1(float v) { return __int_as_float(__builtin_amdgcn_mov_dpp(__float_as_int(v), 0x12f, 0xf, 0xf, false)); }
; DI float gelu_tanh(float x) { const float t = x * (1.5957691216057308f + 0.0713548162726009f * x * x); return x * __builtin_amdgcn_rcpf(1.0f + fexp2(-LOG2E * t)); }
;     DI void operator()(const f32x4 (&acc)[2][2][4][2], const pg8::Unit& u, int wr, int wc, int fr, int fq, int ui) const {
;     ...
;                 for (int m = 0; m < 4; ++m) {
;                     float o[4];
; #pragma unroll
;                     for (int e = 0; e < 4; ++e) {
;                         const float pu_s = rotr1(U[m][e]), pg_s = rotr1(G[m][e]), nu_s = rotl1(U[m][e]), ng_s = rotl1(G[m][e]);
;                         const float pu_x = rotr1(U[m > 0 ? m - 1 : 0][e]), pg_x = rotr1(G[m > 0 ? m - 1 : 0][e]);
;                         const float nu_x = rotl1(U[m < 3 ? m + 1 : 3][e]), ng_x = rotl1(G[m < 3 ? m + 1 : 3][e]);
;                         const float pu = fr == 0 ? pu_x : pu_s, pg = fr == 0 ? pg_x : pg_s, nu = fr == 15 ? nu_x : nu_s, ng = fr == 15 ? ng_x : ng_s;
;                         const float yu = bu[e] + pu * wu[0][e] + U[m][e] * wu[1][e] + nu * wu[2][e];
;                         const float yg = bg[e] + pg * wg[0][e] + G[m][e] * wg[1][e] + ng * wg[2][e];
;                         o[e] = yu * gelu_tanh(yg);
;                     }
;                     const bool edge_row = (m == 0 && fr == 0) || (m == 3 && fr == 15);
;                     if (!edge_row) { u32x2 w; w.x = pack_bf16(o[0], o[1]); w.y = pack_bf16(o[2], o[3]); *(u32x2*)(O + (size_t)(rowb + m * 16 + fr) * FF + f0) = w; }
	v_mov_b32_dpp v82, v103 row_ror:1 row_mask:0xf bank_mask:0xf
	v_mul_f32_e32 v94, 0xbdd2d3e7, v92
	v_cvt_pk_bf16_f32 v68, v68, v69
	v_cvt_pk_bf16_f32 v69, v66, v67
	v_fmaak_f32 v94, v92, v94, 0xc0135761
	v_cndmask_b32_e64 v107, v82, v113, s[12:13]
	v_cndmask_b32_e64 v106, v77, v106, s[12:13]
	global_store_dwordx2 v[164:165], v[68:69], off offset:8
	v_mov_b32_dpp v68, v78 row_ror:15 row_mask:0xf bank_mask:0xf
	v_mov_b32_dpp v69, v79 row_ror:15 row_mask:0xf bank_mask:0xf
	v_mul_f32_e32 v94, v92, v94
	v_pk_fma_f32 v[106:107], v[50:51], v[106:107], v[62:63]
	v_pk_fma_f32 v[102:103], v[54:55], v[102:103], v[106:107]
	v_cndmask_b32_e64 v107, v118, v69, s[16:17]
	v_cndmask_b32_e64 v106, v111, v68, s[16:17]
	v_exp_f32_e32 v94, v94
	v_pk_fma_f32 v[102:103], v[58:59], v[106:107], v[102:103]
	v_mov_b32_dpp v84, v104 row_ror:1 row_mask:0xf bank_mask:0xf
	v_mul_f32_e32 v106, 0xbdd2d3e7, v103
	v_fmaak_f32 v106, v103, v106, 0xc0135761
	v_mul_f32_e32 v106, v103, v106
	v_add_f32_e32 v94, 1.0, v94
	v_rcp_f32_e32 v94, v94
	v_exp_f32_e32 v106, v106
	v_mov_b32_dpp v91, v105 row_ror:1 row_mask:0xf bank_mask:0xf
	v_cndmask_b32_e64 v97, v91, v126, s[12:13]
	v_pk_mul_f32 v[92:93], v[92:93], v[94:95]
	v_add_f32_e32 v94, 1.0, v106
	v_rcp_f32_e32 v95, v94
	v_mul_f32_e32 v94, 0xbdd2d3e7, v102
	v_fmaak_f32 v94, v102, v94, 0xc0135761
	v_mul_f32_e32 v94, v102, v94
	v_exp_f32_e32 v94, v94
	v_cndmask_b32_e64 v96, v84, v119, s[12:13]
	v_mov_b32_dpp v72, v88 row_ror:15 row_mask:0xf bank_mask:0xf
	v_mov_b32_dpp v73, v89 row_ror:15 row_mask:0xf bank_mask:0xf
	v_pk_fma_f32 v[96:97], v[36:37], v[96:97], v[48:49]
	v_add_f32_e32 v94, 1.0, v94
	v_pk_fma_f32 v[96:97], v[40:41], v[104:105], v[96:97]
	v_cndmask_b32_e64 v105, v128, v73, s[16:17]
	v_cndmask_b32_e64 v104, v124, v72, s[16:17]
	v_mov_b32_dpp v76, v70 row_ror:1 row_mask:0xf bank_mask:0xf
	v_mov_b32_dpp v83, v71 row_ror:1 row_mask:0xf bank_mask:0xf
	v_pk_fma_f32 v[96:97], v[44:45], v[104:105], v[96:97]
	v_rcp_f32_e32 v94, v94
	v_pk_mul_f32 v[92:93], v[96:97], v[92:93]
	v_cndmask_b32_e64 v97, v83, v112, s[12:13]
	v_cndmask_b32_e64 v96, v76, v108, s[12:13]
	v_mov_b32_dpp v66, v86 row_ror:15 row_mask:0xf bank_mask:0xf
	v_mov_b32_dpp v67, v87 row_ror:15 row_mask:0xf bank_mask:0xf
	v_pk_fma_f32 v[96:97], v[34:35], v[96:97], v[46:47]
	v_pk_mul_f32 v[94:95], v[102:103], v[94:95]
	v_pk_fma_f32 v[70:71], v[38:39], v[70:71], v[96:97]
	v_cndmask_b32_e64 v97, v117, v67, s[16:17]
	v_cndmask_b32_e64 v96, v110, v66, s[16:17]
	v_pk_fma_f32 v[70:71], v[42:43], v[96:97], v[70:71]
	v_mov_b32_dpp v97, v89 row_ror:1 row_mask:0xf bank_mask:0xf
	v_pk_mul_f32 v[70:71], v[70:71], v[94:95]
	v_mov_b32_dpp v94, v88 row_ror:1 row_mask:0xf bank_mask:0xf
	v_cvt_pk_bf16_f32 v70, v70, v71
	v_cvt_pk_bf16_f32 v71, v92, v93
	global_store_dwordx2 v[166:167], v[70:71], off offset:8
	v_mov_b32_dpp v70, v86 row_ror:1 row_mask:0xf bank_mask:0xf
	v_mov_b32_dpp v71, v78 row_ror:1 row_mask:0xf bank_mask:0xf
	v_mov_b32_dpp v93, v87 row_ror:1 row_mask:0xf bank_mask:0xf
	v_mov_b32_dpp v92, v79 row_ror:1 row_mask:0xf bank_mask:0xf
	v_mov_b32_dpp v95, v80 row_ror:1 row_mask:0xf bank_mask:0xf
	v_mov_b32_dpp v96, v81 row_ror:1 row_mask:0xf bank_mask:0xf
	s_and_saveexec_b64 s[58:59], s[14:15]
	s_cbranch_execz .LBB0_568
	v_cndmask_b32_e64 v91, v97, v91, s[12:13]
	v_cndmask_b32_e64 v97, v96, v90, s[12:13]
	v_cndmask_b32_e64 v96, v95, v85, s[12:13]
	v_pk_fma_f32 v[96:97], v[52:53], v[96:97], v[64:65]
	v_cndmask_b32_e64 v90, v94, v84, s[12:13]
	v_pk_fma_f32 v[80:81], v[56:57], v[80:81], v[96:97]
	s_nop 0
	v_pk_fma_f32 v[74:75], v[60:61], v[74:75], v[80:81]
	s_nop 0
	v_mul_f32_e32 v80, 0xbdd2d3e7, v75
	v_fmaak_f32 v80, v75, v80, 0xc0135761
	v_mul_f32_e32 v81, 0xbdd2d3e7, v74
	v_mul_f32_e32 v80, v75, v80
	v_fmaak_f32 v81, v74, v81, 0xc0135761
	v_mul_f32_e32 v81, v74, v81
	v_exp_f32_e32 v80, v80
	v_exp_f32_e32 v85, v81
	v_add_f32_e32 v80, 1.0, v80
	v_rcp_f32_e32 v81, v80
	v_add_f32_e32 v80, 1.0, v85
	v_rcp_f32_e32 v80, v80
	v_pk_fma_f32 v[84:85], v[36:37], v[90:91], v[48:49]
	v_pk_mul_f32 v[74:75], v[74:75], v[80:81]
	v_cndmask_b32_e64 v81, v92, v82, s[12:13]
	v_cndmask_b32_e64 v80, v71, v77, s[12:13]
	v_pk_fma_f32 v[80:81], v[50:51], v[80:81], v[62:63]
	v_pk_fma_f32 v[84:85], v[40:41], v[88:89], v[84:85]
	v_pk_fma_f32 v[78:79], v[54:55], v[78:79], v[80:81]
	v_pk_fma_f32 v[72:73], v[44:45], v[72:73], v[84:85]
	v_pk_fma_f32 v[68:69], v[58:59], v[68:69], v[78:79]
	v_pk_mul_f32 v[72:73], v[72:73], v[74:75]
	v_mul_f32_e32 v71, 0xbdd2d3e7, v69
	v_fmaak_f32 v71, v69, v71, 0xc0135761
	v_mul_f32_e32 v74, 0xbdd2d3e7, v68
	v_mul_f32_e32 v71, v69, v71
	v_fmaak_f32 v74, v68, v74, 0xc0135761
	v_mul_f32_e32 v74, v68, v74
	v_exp_f32_e32 v71, v71
	v_exp_f32_e32 v77, v74
	v_cndmask_b32_e64 v74, v70, v76, s[12:13]
	v_add_f32_e32 v70, 1.0, v71
	v_rcp_f32_e32 v71, v70
	v_add_f32_e32 v70, 1.0, v77
	v_rcp_f32_e32 v70, v70
	v_cndmask_b32_e64 v75, v93, v83, s[12:13]
	v_pk_fma_f32 v[74:75], v[34:35], v[74:75], v[46:47]
	v_pk_mul_f32 v[68:69], v[68:69], v[70:71]
	v_pk_fma_f32 v[74:75], v[38:39], v[86:87], v[74:75]
	s_nop 0
	v_pk_fma_f32 v[66:67], v[42:43], v[66:67], v[74:75]
	s_nop 0
	v_pk_mul_f32 v[66:67], v[66:67], v[68:69]
	v_mov_b64_e32 v[68:69], s[26:27]
	v_mad_i64_i32 v[68:69], s[70:71], v188, s57, v[68:69]
	v_cvt_pk_bf16_f32 v66, v66, v67
	v_cvt_pk_bf16_f32 v67, v72, v73
	v_lshl_add_u64 v[68:69], v[214:215], 1, v[68:69]
	global_store_dwordx2 v[68:69], v[66:67], off offset:8

; DI unsigned pack_bf16(float lo, float hi) { f32v2 f = {lo, hi}; bf16v2 b = __builtin_convertvector(f, bf16v2); return __builtin_bit_cast(unsigned, b); }
; DI float fexp2(float x) { return __builtin_amdgcn_exp2f(x); }
; DI float rotr1(float v) { return __int_as_float(__builtin_amdgcn_mov_dpp(__float_as_int(v), 0x121, 0xf, 0xf, false)); }
; DI float rotl1(float v) { return __int_as_float(__builtin_amdgcn_mov_dpp(__float_as_int(v), 0x12f, 0xf, 0xf, false)); }
; DI float gelu_tanh(float x) { const float t = x * (1.5957691216057308f + 0.0713548162726009f * x * x); return x * __builtin_amdgcn_rcpf(1.0f + fexp2(-LOG2E * t)); }
;     DI void operator()(const f32x4 (&acc)[2][2][4][2], const pg8::Unit& u, int wr, int wc, int fr, int fq, int ui) const {
;     ...
;                 for (int m = 0; m < 4; ++m) { const float s_ = tab[ai * 128 + m * 16]; U[m] = acc[ai][0][m][n] * s_; G[m] = acc[ai][1][m][n] * s_; }
;     ...
;                 for (int m = 0; m < 4; ++m) {
;                     float o[4];
; #pragma unroll
;                     for (int e = 0; e < 4; ++e) {
;                         const float pu_s = rotr1(U[m][e]), pg_s = rotr1(G[m][e]), nu_s = rotl1(U[m][e]), ng_s = rotl1(G[m][e]);
;                         const float pu_x = rotr1(U[m > 0 ? m - 1 : 0][e]), pg_x = rotr1(G[m > 0 ? m - 1 : 0][e]);
;                         const float nu_x = rotl1(U[m < 3 ? m + 1 : 3][e]), ng_x = rotl1(G[m < 3 ? m + 1 : 3][e]);
;                         const float pu = fr == 0 ? pu_x : pu_s, pg = fr == 0 ? pg_x : pg_s, nu = fr == 15 ? nu_x : nu_s, ng = fr == 15 ? ng_x : ng_s;
;                         const float yu = bu[e] + pu * wu[0][e] + U[m][e] * wu[1][e] + nu * wu[2][e];
;                         const float yg = bg[e] + pg * wg[0][e] + G[m][e] * wg[1][e] + ng * wg[2][e];
;                         o[e] = yu * gelu_tanh(yg);
;                     }
;                     const bool edge_row = (m == 0 && fr == 0) || (m == 3 && fr == 15);
;                     if (!edge_row) { u32x2 w; w.x = pack_bf16(o[0], o[1]); w.y = pack_bf16(o[2], o[3]); *(u32x2*)(O + (size_t)(rowb + m * 16 + fr) * FF + f0) = w; }
.LBB0_572:
	s_or_b64 exec, exec, s[58:59]
	v_mov_b32_e32 v162, v163
	v_mov_b32_e32 v66, v163
	v_mov_b32_e32 v67, v163
	v_pk_mul_f32 v[20:21], v[20:21], v[66:67]
	v_pk_mul_f32 v[18:19], v[18:19], v[162:163]
	v_pk_mul_f32 v[12:13], v[12:13], v[66:67]
	v_pk_mul_f32 v[10:11], v[10:11], v[162:163]
	v_mov_b32_dpp v66, v30 row_ror:1 row_mask:0xf bank_mask:0xf
	v_mov_b32_dpp v68, v26 row_ror:1 row_mask:0xf bank_mask:0xf
	v_mov_b32_dpp v77, v30 row_ror:15 row_mask:0xf bank_mask:0xf
	v_mov_b32_dpp v75, v26 row_ror:15 row_mask:0xf bank_mask:0xf
	v_mov_b32_dpp v78, v18 row_ror:15 row_mask:0xf bank_mask:0xf
	v_mov_b32_dpp v76, v10 row_ror:15 row_mask:0xf bank_mask:0xf
	v_mov_b32_dpp v67, v31 row_ror:1 row_mask:0xf bank_mask:0xf
	v_mov_b32_dpp v69, v27 row_ror:1 row_mask:0xf bank_mask:0xf
	v_mov_b32_dpp v0, v31 row_ror:15 row_mask:0xf bank_mask:0xf
	v_mov_b32_dpp v79, v27 row_ror:15 row_mask:0xf bank_mask:0xf
	v_mov_b32_dpp v74, v19 row_ror:15 row_mask:0xf bank_mask:0xf
	v_mov_b32_dpp v80, v11 row_ror:15 row_mask:0xf bank_mask:0xf
	v_mov_b32_dpp v70, v32 row_ror:1 row_mask:0xf bank_mask:0xf
	v_mov_b32_dpp v72, v28 row_ror:1 row_mask:0xf bank_mask:0xf
	v_mov_b32_dpp v86, v32 row_ror:15 row_mask:0xf bank_mask:0xf
	v_mov_b32_dpp v83, v28 row_ror:15 row_mask:0xf bank_mask:0xf
	v_mov_b32_dpp v88, v20 row_ror:15 row_mask:0xf bank_mask:0xf
	v_mov_b32_dpp v84, v12 row_ror:15 row_mask:0xf bank_mask:0xf
	v_mov_b32_dpp v71, v33 row_ror:1 row_mask:0xf bank_mask:0xf
	v_mov_b32_dpp v73, v29 row_ror:1 row_mask:0xf bank_mask:0xf
	v_mov_b32_dpp v81, v33 row_ror:15 row_mask:0xf bank_mask:0xf
	v_mov_b32_dpp v85, v29 row_ror:15 row_mask:0xf bank_mask:0xf
	v_mov_b32_dpp v82, v21 row_ror:15 row_mask:0xf bank_mask:0xf
	v_mov_b32_dpp v87, v13 row_ror:15 row_mask:0xf bank_mask:0xf
	s_and_saveexec_b64 s[58:59], s[10:11]
	s_cbranch_execz .LBB0_574
	v_pk_fma_f32 v[72:73], v[52:53], v[72:73], v[64:65]
	v_cndmask_b32_e64 v84, v83, v84, s[16:17]
	v_cndmask_b32_e64 v85, v85, v87, s[16:17]
	v_pk_fma_f32 v[72:73], v[56:57], v[28:29], v[72:73]
	v_cndmask_b32_e64 v87, v81, v82, s[16:17]
	v_pk_fma_f32 v[72:73], v[60:61], v[84:85], v[72:73]
	v_pk_fma_f32 v[70:71], v[36:37], v[70:71], v[48:49]
	v_mul_f32_e32 v83, 0xbdd2d3e7, v73
	v_fmaak_f32 v83, v73, v83, 0xc0135761
	v_mul_f32_e32 v84, 0xbdd2d3e7, v72
	v_mul_f32_e32 v83, v73, v83
	v_fmaak_f32 v84, v72, v84, 0xc0135761
	v_mul_f32_e32 v84, v72, v84
	v_exp_f32_e32 v83, v83
	v_exp_f32_e32 v84, v84
	v_cndmask_b32_e64 v86, v86, v88, s[16:17]
	v_add_f32_e32 v81, 1.0, v83
	v_rcp_f32_e32 v83, v81
	v_add_f32_e32 v81, 1.0, v84
	v_rcp_f32_e32 v82, v81
	v_pk_fma_f32 v[70:71], v[40:41], v[32:33], v[70:71]
	v_pk_fma_f32 v[68:69], v[50:51], v[68:69], v[62:63]
	v_pk_fma_f32 v[70:71], v[44:45], v[86:87], v[70:71]
	v_pk_mul_f32 v[72:73], v[72:73], v[82:83]
	v_cndmask_b32_e64 v76, v75, v76, s[16:17]
	v_pk_mul_f32 v[70:71], v[70:71], v[72:73]
	v_cndmask_b32_e64 v72, v77, v78, s[16:17]
	v_cndmask_b32_e64 v77, v79, v80, s[16:17]
	v_pk_fma_f32 v[68:69], v[54:55], v[26:27], v[68:69]
	v_pk_fma_f32 v[66:67], v[34:35], v[66:67], v[46:47]
	v_pk_fma_f32 v[68:69], v[58:59], v[76:77], v[68:69]
	v_pk_fma_f32 v[66:67], v[38:39], v[30:31], v[66:67]
	v_mul_f32_e32 v73, 0xbdd2d3e7, v69
	v_fmaak_f32 v73, v69, v73, 0xc0135761
	v_mul_f32_e32 v73, v69, v73
	v_exp_f32_e32 v75, v73
	v_mul_f32_e32 v73, 0xbdd2d3e7, v68
	v_fmaak_f32 v73, v68, v73, 0xc0135761
	v_mul_f32_e32 v73, v68, v73
	v_exp_f32_e32 v76, v73
	v_cndmask_b32_e64 v73, v0, v74, s[16:17]
	v_add_f32_e32 v0, 1.0, v75
	v_rcp_f32_e32 v75, v0
	v_add_f32_e32 v0, 1.0, v76
	v_rcp_f32_e32 v74, v0
	v_pk_fma_f32 v[66:67], v[42:43], v[72:73], v[66:67]
	v_pk_mul_f32 v[68:69], v[68:69], v[74:75]
	s_nop 0
	v_pk_mul_f32 v[66:67], v[66:67], v[68:69]
	v_mov_b64_e32 v[68:69], s[26:27]
	v_mad_i64_i32 v[68:69], s[70:71], v180, s57, v[68:69]
	v_cvt_pk_bf16_f32 v66, v66, v67
	v_cvt_pk_bf16_f32 v67, v70, v71
	v_lshl_add_u64 v[68:69], v[214:215], 1, v[68:69]
	global_store_dwordx2 v[68:69], v[66:67], off offset:8
.LBB0_574:
	s_or_b64 exec, exec, s[58:59]
	v_mov_b32_e32 v123, v122
	v_mov_b32_e32 v66, v122
	v_mov_b32_e32 v67, v122
	v_pk_mul_f32 v[68:69], v[8:9], v[66:67]
	v_pk_mul_f32 v[70:71], v[6:7], v[122:123]
	v_pk_mul_f32 v[6:7], v[4:5], v[66:67]
	v_pk_mul_f32 v[66:67], v[2:3], v[122:123]
	v_mov_b32_dpp v84, v12 row_ror:1 row_mask:0xf bank_mask:0xf
	v_mov_b32_dpp v2, v28 row_ror:1 row_mask:0xf bank_mask:0xf
	v_mov_b32_dpp v87, v13 row_ror:1 row_mask:0xf bank_mask:0xf
	v_mov_b32_dpp v3, v29 row_ror:1 row_mask:0xf bank_mask:0xf
	v_cndmask_b32_e64 v3, v87, v3, s[12:13]
	v_cndmask_b32_e64 v2, v84, v2, s[12:13]
	v_mov_b32_dpp v4, v12 row_ror:15 row_mask:0xf bank_mask:0xf
	v_mov_b32_dpp v8, v32 row_ror:1 row_mask:0xf bank_mask:0xf
	v_mov_b32_dpp v32, v6 row_ror:15 row_mask:0xf bank_mask:0xf
	v_mov_b32_dpp v5, v13 row_ror:15 row_mask:0xf bank_mask:0xf
	v_mov_b32_dpp v29, v7 row_ror:15 row_mask:0xf bank_mask:0xf
	v_pk_fma_f32 v[2:3], v[52:53], v[2:3], v[64:65]
	v_cndmask_b32_e64 v5, v5, v29, s[16:17]
	v_pk_fma_f32 v[2:3], v[56:57], v[12:13], v[2:3]
	v_cndmask_b32_e64 v4, v4, v32, s[16:17]
	v_pk_fma_f32 v[2:3], v[60:61], v[4:5], v[2:3]
	v_mov_b32_dpp v83, v20 row_ror:1 row_mask:0xf bank_mask:0xf
	v_mul_f32_e32 v4, 0xbdd2d3e7, v3
	v_fmaak_f32 v4, v3, v4, 0xc0135761
	v_mul_f32_e32 v4, v3, v4
	v_exp_f32_e32 v4, v4
	v_mov_b32_dpp v86, v21 row_ror:1 row_mask:0xf bank_mask:0xf
	v_mov_b32_dpp v9, v33 row_ror:1 row_mask:0xf bank_mask:0xf
	v_cndmask_b32_e64 v9, v86, v9, s[12:13]
	v_add_f32_e32 v4, 1.0, v4
	v_cndmask_b32_e64 v8, v83, v8, s[12:13]
	v_mov_b32_dpp v73, v10 row_ror:1 row_mask:0xf bank_mask:0xf
	v_mov_b32_dpp v26, v26 row_ror:1 row_mask:0xf bank_mask:0xf
; DI unsigned pack_bf16(float lo, float hi) { f32v2 f = {lo, hi}; bf16v2 b = __builtin_convertvector(f, bf16v2); return __builtin_bit_cast(unsigned, b); }
; DI float fexp2(float x) { return __builtin_amdgcn_exp2f(x); }
; DI float rotr1(float v) { return __int_as_float(__builtin_amdgcn_mov_dpp(__float_as_int(v), 0x121, 0xf, 0xf, false)); }
; DI float rotl1(float v) { return __int_as_float(__builtin_amdgcn_mov_dpp(__float_as_int(v), 0x12f, 0xf, 0xf, false)); }
; DI float gelu_tanh(float x) { const float t = x * (1.5957691216057308f + 0.0713548162726009f * x * x); return x * __builtin_amdgcn_rcpf(1.0f + fexp2(-LOG2E * t)); }
;     DI void operator()(const f32x4 (&acc)[2][2][4][2], const pg8::Unit& u, int wr, int wc, int fr, int fq, int ui) const {
;     ...
;                 for (int m = 0; m < 4; ++m) {
;                     float o[4];
; #pragma unroll
;                     for (int e = 0; e < 4; ++e) {
;                         const float pu_s = rotr1(U[m][e]), pg_s = rotr1(G[m][e]), nu_s = rotl1(U[m][e]), ng_s = rotl1(G[m][e]);
;                         const float pu_x = rotr1(U[m > 0 ? m - 1 : 0][e]), pg_x = rotr1(G[m > 0 ? m - 1 : 0][e]);
;                         const float nu_x = rotl1(U[m < 3 ? m + 1 : 3][e]), ng_x = rotl1(G[m < 3 ? m + 1 : 3][e]);
;                         const float pu = fr == 0 ? pu_x : pu_s, pg = fr == 0 ? pg_x : pg_s, nu = fr == 15 ? nu_x : nu_s, ng = fr == 15 ? ng_x : ng_s;
;                         const float yu = bu[e] + pu * wu[0][e] + U[m][e] * wu[1][e] + nu * wu[2][e];
;                         const float yg = bg[e] + pg * wg[0][e] + G[m][e] * wg[1][e] + ng * wg[2][e];
;                         o[e] = yu * gelu_tanh(yg);
;                     }
;                     const bool edge_row = (m == 0 && fr == 0) || (m == 3 && fr == 15);
;                     if (!edge_row) { u32x2 w; w.x = pack_bf16(o[0], o[1]); w.y = pack_bf16(o[2], o[3]); *(u32x2*)(O + (size_t)(rowb + m * 16 + fr) * FF + f0) = w; }
	v_mov_b32_dpp v78, v11 row_ror:1 row_mask:0xf bank_mask:0xf
	v_mov_b32_dpp v27, v27 row_ror:1 row_mask:0xf bank_mask:0xf
	v_rcp_f32_e32 v5, v4
	v_pk_fma_f32 v[8:9], v[36:37], v[8:9], v[48:49]
	v_mul_f32_e32 v4, 0xbdd2d3e7, v2
	v_mov_b32_dpp v85, v20 row_ror:15 row_mask:0xf bank_mask:0xf
	v_mov_b32_dpp v12, v21 row_ror:15 row_mask:0xf bank_mask:0xf
	v_fmaak_f32 v4, v2, v4, 0xc0135761
	v_pk_fma_f32 v[8:9], v[40:41], v[20:21], v[8:9]
	v_cndmask_b32_e64 v21, v78, v27, s[12:13]
	v_cndmask_b32_e64 v20, v73, v26, s[12:13]
	v_mov_b32_dpp v74, v10 row_ror:15 row_mask:0xf bank_mask:0xf
	v_mov_b32_dpp v76, v66 row_ror:15 row_mask:0xf bank_mask:0xf
	v_mov_b32_dpp v80, v11 row_ror:15 row_mask:0xf bank_mask:0xf
	v_mov_b32_dpp v82, v67 row_ror:15 row_mask:0xf bank_mask:0xf
	v_mul_f32_e32 v4, v2, v4
	v_pk_fma_f32 v[20:21], v[50:51], v[20:21], v[62:63]
	v_pk_fma_f32 v[10:11], v[54:55], v[10:11], v[20:21]
	v_cndmask_b32_e64 v21, v80, v82, s[16:17]
	v_cndmask_b32_e64 v20, v74, v76, s[16:17]
	v_exp_f32_e32 v4, v4
	v_pk_fma_f32 v[10:11], v[58:59], v[20:21], v[10:11]
	v_mov_b32_dpp v28, v68 row_ror:15 row_mask:0xf bank_mask:0xf
	v_mul_f32_e32 v20, 0xbdd2d3e7, v11
	v_fmaak_f32 v20, v11, v20, 0xc0135761
	v_mul_f32_e32 v20, v11, v20
	v_add_f32_e32 v4, 1.0, v4
	v_rcp_f32_e32 v4, v4
	v_exp_f32_e32 v20, v20
	v_mov_b32_dpp v33, v69 row_ror:15 row_mask:0xf bank_mask:0xf
	v_cndmask_b32_e64 v13, v12, v33, s[16:17]
	v_pk_mul_f32 v[2:3], v[2:3], v[4:5]
	v_add_f32_e32 v4, 1.0, v20
	v_rcp_f32_e32 v5, v4
	v_mul_f32_e32 v4, 0xbdd2d3e7, v10
	v_fmaak_f32 v4, v10, v4, 0xc0135761
	v_mul_f32_e32 v4, v10, v4
	v_exp_f32_e32 v4, v4
	v_cndmask_b32_e64 v12, v85, v28, s[16:17]
	v_mov_b32_dpp v72, v18 row_ror:1 row_mask:0xf bank_mask:0xf
	v_mov_b32_dpp v30, v30 row_ror:1 row_mask:0xf bank_mask:0xf
	v_add_f32_e32 v4, 1.0, v4
	v_mov_b32_dpp v77, v19 row_ror:1 row_mask:0xf bank_mask:0xf
	v_mov_b32_dpp v31, v31 row_ror:1 row_mask:0xf bank_mask:0xf
	v_pk_fma_f32 v[8:9], v[44:45], v[12:13], v[8:9]
	v_rcp_f32_e32 v4, v4
	v_pk_mul_f32 v[2:3], v[8:9], v[2:3]
	v_cndmask_b32_e64 v9, v77, v31, s[12:13]
	v_cndmask_b32_e64 v8, v72, v30, s[12:13]
	v_mov_b32_dpp v0, v18 row_ror:15 row_mask:0xf bank_mask:0xf
	v_mov_b32_dpp v75, v70 row_ror:15 row_mask:0xf bank_mask:0xf
	v_mov_b32_dpp v79, v19 row_ror:15 row_mask:0xf bank_mask:0xf
	v_mov_b32_dpp v81, v71 row_ror:15 row_mask:0xf bank_mask:0xf
	v_pk_fma_f32 v[8:9], v[34:35], v[8:9], v[46:47]
	v_cndmask_b32_e64 v13, v79, v81, s[16:17]
	v_pk_fma_f32 v[8:9], v[38:39], v[18:19], v[8:9]
	v_cndmask_b32_e64 v12, v0, v75, s[16:17]
	v_mov_b32_dpp v18, v6 row_ror:1 row_mask:0xf bank_mask:0xf
	v_mov_b32_dpp v19, v7 row_ror:1 row_mask:0xf bank_mask:0xf
	v_pk_fma_f32 v[8:9], v[42:43], v[12:13], v[8:9]
	v_pk_mul_f32 v[4:5], v[10:11], v[4:5]
	v_cndmask_b32_e64 v21, v19, v87, s[12:13]
	v_cndmask_b32_e64 v20, v18, v84, s[12:13]
	v_pk_mul_f32 v[4:5], v[8:9], v[4:5]
	v_mov_b32_dpp v8, v16 row_ror:15 row_mask:0xf bank_mask:0xf
	v_mov_b32_dpp v9, v17 row_ror:15 row_mask:0xf bank_mask:0xf
	v_pk_fma_f32 v[20:21], v[52:53], v[20:21], v[64:65]
	v_mov_b32_dpp v13, v68 row_ror:1 row_mask:0xf bank_mask:0xf
	v_pk_fma_f32 v[6:7], v[56:57], v[6:7], v[20:21]
	v_cndmask_b32_e64 v21, v29, v9, s[16:17]
	v_cndmask_b32_e64 v20, v32, v8, s[16:17]
	v_pk_fma_f32 v[26:27], v[60:61], v[20:21], v[6:7]
	v_cndmask_b32_e64 v30, v13, v83, s[12:13]
	v_mul_f32_e32 v6, 0xbdd2d3e7, v27
	v_fmaak_f32 v6, v27, v6, 0xc0135761
	v_mul_f32_e32 v6, v27, v6
	v_exp_f32_e32 v21, v6
	v_mov_b32_dpp v20, v69 row_ror:1 row_mask:0xf bank_mask:0xf
	v_cndmask_b32_e64 v31, v20, v86, s[12:13]
	v_mov_b32_dpp v10, v66 row_ror:1 row_mask:0xf bank_mask:0xf
	v_add_f32_e32 v21, 1.0, v21
	v_rcp_f32_e32 v29, v21
	v_mul_f32_e32 v21, 0xbdd2d3e7, v26
	v_fmaak_f32 v21, v26, v21, 0xc0135761
	v_mul_f32_e32 v21, v26, v21
	v_mov_b32_dpp v11, v67 row_ror:1 row_mask:0xf bank_mask:0xf
	v_pk_fma_f32 v[30:31], v[36:37], v[30:31], v[48:49]
	v_exp_f32_e32 v21, v21
	v_cvt_pk_bf16_f32 v4, v4, v5
	v_cvt_pk_bf16_f32 v5, v2, v3
	v_pk_fma_f32 v[30:31], v[40:41], v[68:69], v[30:31]
	v_cndmask_b32_e64 v69, v11, v78, s[12:13]
	v_cndmask_b32_e64 v68, v10, v73, s[12:13]
	global_store_dwordx2 v[98:99], v[4:5], off offset:8
	v_mov_b32_dpp v4, v14 row_ror:15 row_mask:0xf bank_mask:0xf
	v_mov_b32_dpp v5, v15 row_ror:15 row_mask:0xf bank_mask:0xf
	v_pk_fma_f32 v[68:69], v[50:51], v[68:69], v[62:63]
	v_mov_b32_dpp v6, v24 row_ror:15 row_mask:0xf bank_mask:0xf
	v_pk_fma_f32 v[66:67], v[54:55], v[66:67], v[68:69]
	v_cndmask_b32_e64 v69, v82, v5, s[16:17]
	v_cndmask_b32_e64 v68, v76, v4, s[16:17]
	v_add_f32_e32 v21, 1.0, v21
	v_pk_fma_f32 v[66:67], v[58:59], v[68:69], v[66:67]
	v_cndmask_b32_e64 v32, v28, v6, s[16:17]
	v_rcp_f32_e32 v28, v21
	v_mul_f32_e32 v21, 0xbdd2d3e7, v67
	v_fmaak_f32 v21, v67, v21, 0xc0135761
	v_mul_f32_e32 v21, v67, v21
	v_exp_f32_e32 v21, v21
	v_pk_mul_f32 v[26:27], v[26:27], v[28:29]
	v_mov_b32_dpp v7, v25 row_ror:15 row_mask:0xf bank_mask:0xf
	v_cndmask_b32_e64 v33, v33, v7, s[16:17]
	v_add_f32_e32 v21, 1.0, v21
	v_rcp_f32_e32 v29, v21
	v_mul_f32_e32 v21, 0xbdd2d3e7, v66
	v_fmaak_f32 v21, v66, v21, 0xc0135761
	v_mul_f32_e32 v21, v66, v21
	v_exp_f32_e32 v21, v21
	v_mov_b32_dpp v0, v70 row_ror:1 row_mask:0xf bank_mask:0xf
	v_mov_b32_dpp v12, v71 row_ror:1 row_mask:0xf bank_mask:0xf
	v_pk_fma_f32 v[30:31], v[44:45], v[32:33], v[30:31]
	v_add_f32_e32 v21, 1.0, v21
	v_rcp_f32_e32 v28, v21
	v_pk_mul_f32 v[26:27], v[30:31], v[26:27]
	v_cndmask_b32_e64 v31, v12, v77, s[12:13]
	v_cndmask_b32_e64 v30, v0, v72, s[12:13]
	v_mov_b32_dpp v2, v22 row_ror:15 row_mask:0xf bank_mask:0xf
	v_mov_b32_dpp v3, v23 row_ror:15 row_mask:0xf bank_mask:0xf
	v_pk_fma_f32 v[30:31], v[34:35], v[30:31], v[46:47]
	v_cndmask_b32_e64 v33, v81, v3, s[16:17]
	v_pk_fma_f32 v[30:31], v[38:39], v[70:71], v[30:31]
	v_cndmask_b32_e64 v32, v75, v2, s[16:17]
	v_pk_fma_f32 v[30:31], v[42:43], v[32:33], v[30:31]
	v_pk_mul_f32 v[28:29], v[66:67], v[28:29]
	v_mov_b32_dpp v21, v22 row_ror:1 row_mask:0xf bank_mask:0xf
	v_pk_mul_f32 v[28:29], v[30:31], v[28:29]
	v_mov_b32_dpp v30, v16 row_ror:1 row_mask:0xf bank_mask:0xf
	v_cvt_pk_bf16_f32 v28, v28, v29
	v_cvt_pk_bf16_f32 v29, v26, v27
	global_store_dwordx2 v[100:101], v[28:29], off offset:8
	v_mov_b32_dpp v26, v14 row_ror:1 row_mask:0xf bank_mask:0xf
	v_mov_b32_dpp v28, v23 row_ror:1 row_mask:0xf bank_mask:0xf
	v_mov_b32_dpp v27, v15 row_ror:1 row_mask:0xf bank_mask:0xf
	v_mov_b32_dpp v29, v24 row_ror:1 row_mask:0xf bank_mask:0xf
	v_mov_b32_dpp v32, v25 row_ror:1 row_mask:0xf bank_mask:0xf
	v_mov_b32_dpp v31, v17 row_ror:1 row_mask:0xf bank_mask:0xf
	s_and_saveexec_b64 s[58:59], s[14:15]
	s_cbranch_execz .LBB0_576
; DI unsigned pack_bf16(float lo, float hi) { f32v2 f = {lo, hi}; bf16v2 b = __builtin_convertvector(f, bf16v2); return __builtin_bit_cast(unsigned, b); }
; DI float fexp2(float x) { return __builtin_amdgcn_exp2f(x); }
; DI float rotr1(float v) { return __int_as_float(__builtin_amdgcn_mov_dpp(__float_as_int(v), 0x121, 0xf, 0xf, false)); }
; DI float rotl1(float v) { return __int_as_float(__builtin_amdgcn_mov_dpp(__float_as_int(v), 0x12f, 0xf, 0xf, false)); }
; DI float gelu_tanh(float x) { const float t = x * (1.5957691216057308f + 0.0713548162726009f * x * x); return x * __builtin_amdgcn_rcpf(1.0f + fexp2(-LOG2E * t)); }
;     DI void operator()(const f32x4 (&acc)[2][2][4][2], const pg8::Unit& u, int wr, int wc, int fr, int fq, int ui) const {
;     ...
;                 for (int m = 0; m < 4; ++m) {
;                     float o[4];
; #pragma unroll
;                     for (int e = 0; e < 4; ++e) {
;                         const float pu_s = rotr1(U[m][e]), pg_s = rotr1(G[m][e]), nu_s = rotl1(U[m][e]), ng_s = rotl1(G[m][e]);
;                         const float pu_x = rotr1(U[m > 0 ? m - 1 : 0][e]), pg_x = rotr1(G[m > 0 ? m - 1 : 0][e]);
;                         const float nu_x = rotl1(U[m < 3 ? m + 1 : 3][e]), ng_x = rotl1(G[m < 3 ? m + 1 : 3][e]);
;                         const float pu = fr == 0 ? pu_x : pu_s, pg = fr == 0 ? pg_x : pg_s, nu = fr == 15 ? nu_x : nu_s, ng = fr == 15 ? ng_x : ng_s;
;                         const float yu = bu[e] + pu * wu[0][e] + U[m][e] * wu[1][e] + nu * wu[2][e];
;                         const float yg = bg[e] + pg * wg[0][e] + G[m][e] * wg[1][e] + ng * wg[2][e];
;                         o[e] = yu * gelu_tanh(yg);
;                     }
;                     const bool edge_row = (m == 0 && fr == 0) || (m == 3 && fr == 15);
;                     if (!edge_row) { u32x2 w; w.x = pack_bf16(o[0], o[1]); w.y = pack_bf16(o[2], o[3]); *(u32x2*)(O + (size_t)(rowb + m * 16 + fr) * FF + f0) = w; }
	v_cndmask_b32_e64 v19, v31, v19, s[12:13]
	v_cndmask_b32_e64 v18, v30, v18, s[12:13]
	v_pk_fma_f32 v[18:19], v[52:53], v[18:19], v[64:65]
	v_cndmask_b32_e64 v33, v32, v20, s[12:13]
	v_pk_fma_f32 v[16:17], v[56:57], v[16:17], v[18:19]
	v_cndmask_b32_e64 v32, v29, v13, s[12:13]
	v_pk_fma_f32 v[8:9], v[60:61], v[8:9], v[16:17]
	v_cndmask_b32_e64 v11, v27, v11, s[12:13]
	v_mul_f32_e32 v16, 0xbdd2d3e7, v9
	v_fmaak_f32 v16, v9, v16, 0xc0135761
	v_mul_f32_e32 v17, 0xbdd2d3e7, v8
	v_mul_f32_e32 v16, v9, v16
	v_fmaak_f32 v17, v8, v17, 0xc0135761
	v_mul_f32_e32 v17, v8, v17
	v_exp_f32_e32 v16, v16
	v_exp_f32_e32 v18, v17
	v_cndmask_b32_e64 v10, v26, v10, s[12:13]
	v_add_f32_e32 v13, 1.0, v16
	v_rcp_f32_e32 v17, v13
	v_add_f32_e32 v13, 1.0, v18
	v_rcp_f32_e32 v16, v13
	v_pk_fma_f32 v[18:19], v[36:37], v[32:33], v[48:49]
	v_pk_fma_f32 v[10:11], v[50:51], v[10:11], v[62:63]
	v_pk_fma_f32 v[18:19], v[40:41], v[24:25], v[18:19]
	v_pk_fma_f32 v[10:11], v[54:55], v[14:15], v[10:11]
	v_pk_fma_f32 v[6:7], v[44:45], v[6:7], v[18:19]
	v_pk_mul_f32 v[8:9], v[8:9], v[16:17]
	v_pk_fma_f32 v[4:5], v[58:59], v[4:5], v[10:11]
	v_pk_mul_f32 v[6:7], v[6:7], v[8:9]
	v_mul_f32_e32 v8, 0xbdd2d3e7, v5
	v_fmaak_f32 v8, v5, v8, 0xc0135761
	v_mul_f32_e32 v8, v5, v8
	v_exp_f32_e32 v10, v8
	v_mul_f32_e32 v8, 0xbdd2d3e7, v4
	v_fmaak_f32 v8, v4, v8, 0xc0135761
	v_mul_f32_e32 v8, v4, v8
	v_cndmask_b32_e64 v9, v28, v12, s[12:13]
	v_exp_f32_e32 v12, v8
	v_cndmask_b32_e64 v8, v21, v0, s[12:13]
	v_add_f32_e32 v0, 1.0, v10
	v_rcp_f32_e32 v11, v0
	v_add_f32_e32 v0, 1.0, v12
	v_rcp_f32_e32 v10, v0
	v_pk_fma_f32 v[8:9], v[34:35], v[8:9], v[46:47]
	v_pk_mul_f32 v[4:5], v[4:5], v[10:11]
	v_pk_fma_f32 v[8:9], v[38:39], v[22:23], v[8:9]
	s_nop 0
	v_pk_fma_f32 v[2:3], v[42:43], v[2:3], v[8:9]
	s_nop 0
	v_pk_mul_f32 v[2:3], v[2:3], v[4:5]
	v_mov_b64_e32 v[4:5], s[26:27]
	v_mad_i64_i32 v[4:5], s[70:71], v114, s57, v[4:5]
	v_cvt_pk_bf16_f32 v2, v2, v3
	v_cvt_pk_bf16_f32 v3, v6, v7
	v_lshl_add_u64 v[4:5], v[214:215], 1, v[4:5]
	global_store_dwordx2 v[4:5], v[2:3], off offset:8

; DI float fexp2(float x) { return __builtin_amdgcn_exp2f(x); }
; DI bf16x8 pack8(const float* v) { u32x4 w; w.x = pack_bf16(v[0], v[1]); w.y = pack_bf16(v[2], v[3]); w.z = pack_bf16(v[4], v[5]); w.w = pack_bf16(v[6], v[7]); return __builtin_bit_cast(bf16x8, w); }
; DI float gelu_tanh(float x) { const float t = x * (1.5957691216057308f + 0.0713548162726009f * x * x); return x * __builtin_amdgcn_rcpf(1.0f + fexp2(-LOG2E * t)); }
; DI void ffn_fix_phase(const bf16_t* __restrict__ edge, bf16_t* __restrict__ Oo, const float* __restrict__ cw, const float* __restrict__ cb, int T) {
;     ...
;         const int fc = it % NCH, rs = it / NCH, side = rs & 1, blk = rs >> 1, f0 = fc * 8;
;         const int t = blk * 64 + (side ? 63 : 0), ts = t & (SEQ - 1);
;         const int cu = 256 * (f0 >> 7) + (f0 & 127);
;         const bf16_t* eb = edge + (size_t)blk * 4 * F2 + cu;
;         const bf16_t* pp = side ? eb + 2 * F2 : eb - F2;
;         const bf16_t* cp = side ? eb + 3 * F2 : eb;
;         const bf16_t* np = side ? eb + 4 * F2 : eb + F2;
;         const bool pz = (side == 0 && ts == 0), nz = (side == 1 && ts == SEQ - 1);
;         float pu[8], pg[8], cu_[8], cg_[8], nu[8], ng[8];
;         if (pz) {
; #pragma unroll
;             for (int e = 0; e < 8; ++e) { pu[e] = 0.f; pg[e] = 0.f; }
;         } else { unpack8(*(const u32x4*)pp, pu); unpack8(*(const u32x4*)(pp + 128), pg); }
;         unpack8(*(const u32x4*)cp, cu_); unpack8(*(const u32x4*)(cp + 128), cg_);
;         if (nz) {
; #pragma unroll
;             for (int e = 0; e < 8; ++e) { nu[e] = 0.f; ng[e] = 0.f; }
;         } else { unpack8(*(const u32x4*)np, nu); unpack8(*(const u32x4*)(np + 128), ng); }
;         float o[8];
; #pragma unroll
;         for (int e = 0; e < 8; ++e) {
;             const float yu = cb[f0 + e] + pu[e] * cw[f0 + e] + cu_[e] * cw[F2 + f0 + e] + nu[e] * cw[2 * F2 + f0 + e];
;             const float yg = cb[FF + f0 + e] + pg[e] * cw[FF + f0 + e] + cg_[e] * cw[F2 + FF + f0 + e] + ng[e] * cw[2 * F2 + FF + f0 + e];
;             o[e] = yu * gelu_tanh(yg);
;         }
;         *(bf16x8*)(Oo + (size_t)t * FF + f0) = pack8(o);
.LBB0_633:
	s_or_b64 exec, exec, s[6:7]
	v_readlane_b32 s52, v254, 16
	v_readlane_b32 s60, v254, 24
	v_readlane_b32 s61, v254, 25
	v_ashrrev_i32_e32 v61, 31, v60
	v_readlane_b32 s62, v254, 26
	v_readlane_b32 s63, v254, 27
	s_mov_b64 s[24:25], s[60:61]
	v_or_b32_e32 v103, v15, v14
	s_waitcnt vmcnt(0)
	v_lshlrev_b32_e32 v14, 16, v2
	v_and_b32_e32 v15, 0xffff0000, v2
	v_lshlrev_b32_e32 v96, 16, v3
	v_and_b32_e32 v97, 0xffff0000, v3
	v_add_u32_e32 v0, 0xb00, v60
	v_lshlrev_b64 v[2:3], 2, v[60:61]
	s_mov_b64 s[26:27], s[62:63]
	v_lshl_add_u64 v[22:23], s[26:27], 0, v[2:3]
	v_lshl_add_u64 v[104:105], s[24:25], 0, v[2:3]
	v_lshlrev_b64 v[2:3], 2, v[0:1]
	v_lshlrev_b32_e32 v30, 16, v6
	v_and_b32_e32 v31, 0xffff0000, v6
	v_lshlrev_b32_e32 v92, 16, v7
	v_and_b32_e32 v93, 0xffff0000, v7
	v_lshl_add_u64 v[6:7], s[26:27], 0, v[2:3]
	v_lshlrev_b32_e32 v82, 16, v8
	v_and_b32_e32 v83, 0xffff0000, v8
	v_lshlrev_b32_e32 v84, 16, v4
	v_and_b32_e32 v85, 0xffff0000, v4
	v_lshlrev_b32_e32 v74, 16, v9
	v_and_b32_e32 v75, 0xffff0000, v9
	v_lshlrev_b32_e32 v76, 16, v5
	v_and_b32_e32 v77, 0xffff0000, v5
	v_lshl_add_u64 v[12:13], s[24:25], 0, v[2:3]
	global_load_dwordx4 v[2:5], v[6:7], off offset:16
	global_load_dwordx4 v[32:35], v[6:7], off
	s_nop 0
	global_load_dwordx4 v[6:9], v[12:13], off offset:16
	global_load_dwordx4 v[36:39], v[12:13], off
	s_mov_b64 s[4:5], 0x5800
	v_lshl_add_u64 v[28:29], v[104:105], 0, s[4:5]
	s_mov_b64 s[4:5], 0xb000
	v_lshl_add_u64 v[108:109], v[104:105], 0, s[4:5]
	s_mov_b64 s[4:5], 0x8400
	v_lshl_add_u64 v[16:17], v[104:105], 0, s[4:5]
	s_mov_b64 s[4:5], 0xdc00
	v_lshl_add_u64 v[20:21], v[104:105], 0, s[4:5]
	s_mov_b32 s4, 0x8000
	v_readlane_b32 s57, v254, 21
	s_movk_i32 s57, 0x1600
	v_add_u32_e32 v100, s20, v100
	v_add_u32_e32 v101, s0, v101
	v_add_u32_e32 v102, s1, v102
	v_readlane_b32 s53, v254, 17
	v_readlane_b32 s54, v254, 18
	v_readlane_b32 s55, v254, 19
	v_readlane_b32 s56, v254, 20
	v_readlane_b32 s58, v254, 22
	v_readlane_b32 s59, v254, 23
	v_readlane_b32 s64, v254, 28
	v_readlane_b32 s65, v254, 29
	v_readlane_b32 s66, v254, 30
	v_readlane_b32 s67, v254, 31
	s_waitcnt vmcnt(1)
	v_pk_fma_f32 v[2:3], v[68:69], v[6:7], v[2:3]
	s_waitcnt vmcnt(0)
	v_pk_fma_f32 v[24:25], v[10:11], v[36:37], v[32:33]
	v_add_co_u32_e32 v10, vcc, s4, v104
	s_mov_b32 s4, 0xd000
	s_nop 0
	v_addc_co_u32_e32 v11, vcc, 0, v105, vcc
	global_load_dwordx4 v[40:43], v[10:11], off offset:1024
	s_nop 0
	global_load_dwordx4 v[10:13], v[16:17], off offset:16
	v_pk_fma_f32 v[34:35], v[88:89], v[38:39], v[34:35]
	s_waitcnt vmcnt(1)
	v_pk_fma_f32 v[24:25], v[40:41], v[14:15], v[24:25]
	v_add_co_u32_e32 v14, vcc, s4, v104
	s_movk_i32 s4, 0x5000
	s_nop 0
	v_addc_co_u32_e32 v15, vcc, 0, v105, vcc
	global_load_dwordx4 v[44:47], v[14:15], off offset:3072
	s_nop 0
	global_load_dwordx4 v[14:17], v[20:21], off offset:16
	v_pk_fma_f32 v[34:35], v[42:43], v[96:97], v[34:35]
	s_waitcnt vmcnt(2)
	v_pk_fma_f32 v[2:3], v[10:11], v[84:85], v[2:3]
	s_waitcnt vmcnt(1)
	v_pk_fma_f32 v[36:37], v[18:19], v[44:45], v[24:25]
	global_load_dwordx4 v[18:21], v[22:23], off offset:16
	global_load_dwordx4 v[48:51], v[22:23], off
	s_nop 0
	global_load_dwordx4 v[22:25], v[104:105], off offset:16
	global_load_dwordx4 v[52:55], v[104:105], off
	v_mul_f32_e32 v0, 0xbdd2d3e7, v36
	v_fmaak_f32 v0, v36, v0, 0xc0135761
	v_mul_f32_e32 v0, v36, v0
	v_exp_f32_e32 v0, v0
	v_pk_fma_f32 v[34:35], v[94:95], v[46:47], v[34:35]
	s_waitcnt vmcnt(4)
	v_pk_fma_f32 v[2:3], v[80:81], v[14:15], v[2:3]
	v_add_f32_e32 v0, 1.0, v0
	v_rcp_f32_e32 v40, v0
	v_mul_f32_e32 v0, 0xbdd2d3e7, v37
	v_fmaak_f32 v0, v37, v0, 0xc0135761
	v_mul_f32_e32 v0, v37, v0
	v_exp_f32_e32 v0, v0
	s_waitcnt vmcnt(1)
	v_pk_fma_f32 v[10:11], v[66:67], v[22:23], v[18:19]
	s_waitcnt vmcnt(0)
	v_pk_fma_f32 v[32:33], v[26:27], v[52:53], v[48:49]
	v_add_co_u32_e32 v26, vcc, s4, v104
	s_mov_b32 s4, 0xb000
	s_nop 0
	v_addc_co_u32_e32 v27, vcc, 0, v105, vcc
	global_load_dwordx4 v[56:59], v[26:27], off offset:2048
	s_nop 0
	global_load_dwordx4 v[26:29], v[28:29], off offset:16
	v_add_f32_e32 v0, 1.0, v0
	v_rcp_f32_e32 v41, v0
	v_mul_f32_e32 v0, 0xbdd2d3e7, v34
	v_fmaak_f32 v0, v34, v0, 0xc0135761
	v_mul_f32_e32 v0, v34, v0
	v_exp_f32_e32 v0, v0
	v_pk_mul_f32 v[36:37], v[36:37], v[40:41]
	v_pk_fma_f32 v[40:41], v[86:87], v[54:55], v[50:51]
	v_add_f32_e32 v0, 1.0, v0
	v_rcp_f32_e32 v38, v0
	v_mul_f32_e32 v0, 0xbdd2d3e7, v35
	v_fmaak_f32 v0, v35, v0, 0xc0135761
	v_mul_f32_e32 v0, v35, v0
	v_exp_f32_e32 v0, v0
	s_waitcnt vmcnt(1)
	v_pk_fma_f32 v[44:45], v[56:57], v[30:31], v[32:33]
	v_add_co_u32_e32 v30, vcc, s4, v104
	v_add_f32_e32 v0, 1.0, v0
	s_nop 0
	v_addc_co_u32_e32 v31, vcc, 0, v105, vcc
	global_load_dwordx4 v[104:107], v[30:31], off
	s_nop 0
	global_load_dwordx4 v[30:33], v[108:109], off offset:16
	v_rcp_f32_e32 v39, v0
	v_mul_f32_e32 v0, 0xbdd2d3e7, v2
	v_fmaak_f32 v0, v2, v0, 0xc0135761
	v_mul_f32_e32 v0, v2, v0
	v_exp_f32_e32 v0, v0
	s_waitcnt vmcnt(2)
	v_pk_fma_f32 v[10:11], v[26:27], v[82:83], v[10:11]
	v_pk_fma_f32 v[40:41], v[58:59], v[92:93], v[40:41]
	v_pk_mul_f32 v[34:35], v[34:35], v[38:39]
	v_add_f32_e32 v0, 1.0, v0
	v_rcp_f32_e32 v6, v0
	v_mul_f32_e32 v0, 0xbdd2d3e7, v3
	v_fmaak_f32 v0, v3, v0, 0xc0135761
	v_mul_f32_e32 v0, v3, v0
	v_exp_f32_e32 v0, v0
	v_cmp_le_i32_e32 vcc, s21, v100
	s_or_b64 s[16:17], vcc, s[16:17]
	v_add_f32_e32 v0, 1.0, v0
	v_rcp_f32_e32 v7, v0
	s_waitcnt vmcnt(1)
	v_pk_fma_f32 v[44:45], v[98:99], v[104:105], v[44:45]
	s_waitcnt vmcnt(0)
	v_pk_fma_f32 v[10:11], v[78:79], v[30:31], v[10:11]
	v_pk_mul_f32 v[2:3], v[2:3], v[6:7]
	v_pk_fma_f32 v[40:41], v[90:91], v[106:107], v[40:41]
	v_pk_mul_f32 v[6:7], v[10:11], v[2:3]
	v_pk_fma_f32 v[2:3], v[64:65], v[8:9], v[4:5]
	v_pk_fma_f32 v[8:9], v[62:63], v[24:25], v[20:21]
	v_pk_fma_f32 v[2:3], v[12:13], v[76:77], v[2:3]
	v_pk_fma_f32 v[8:9], v[28:29], v[74:75], v[8:9]
	v_pk_fma_f32 v[2:3], v[72:73], v[16:17], v[2:3]
	v_pk_fma_f32 v[8:9], v[70:71], v[32:33], v[8:9]
	v_mul_f32_e32 v0, 0xbdd2d3e7, v2
	v_fmaak_f32 v0, v2, v0, 0xc0135761
	v_mul_f32_e32 v0, v2, v0
	v_exp_f32_e32 v0, v0
	v_pk_mul_f32 v[36:37], v[44:45], v[36:37]
	v_pk_mul_f32 v[34:35], v[40:41], v[34:35]
	v_add_f32_e32 v0, 1.0, v0
	v_rcp_f32_e32 v4, v0
	v_mul_f32_e32 v0, 0xbdd2d3e7, v3
	v_fmaak_f32 v0, v3, v0, 0xc0135761
	v_mul_f32_e32 v0, v3, v0
	v_exp_f32_e32 v0, v0
	s_nop 0
	v_add_f32_e32 v0, 1.0, v0
	v_rcp_f32_e32 v5, v0
	s_nop 0
	v_pk_mul_f32 v[2:3], v[2:3], v[4:5]
	v_cvt_pk_bf16_f32 v4, v6, v7
	v_mov_b64_e32 v[6:7], s[14:15]
	v_pk_mul_f32 v[8:9], v[8:9], v[2:3]
	v_mad_i64_i32 v[6:7], s[4:5], v103, s57, v[6:7]
	v_cvt_pk_bf16_f32 v2, v36, v37
	v_cvt_pk_bf16_f32 v3, v34, v35
	v_cvt_pk_bf16_f32 v5, v8, v9
	v_lshl_add_u64 v[6:7], v[60:61], 1, v[6:7]
	global_store_dwordx4 v[6:7], v[2:5], off
	s_andn2_b64 exec, exec, s[16:17]
	s_cbranch_execz .LBB0_638

; DI unsigned pack_bf16(float lo, float hi) { f32v2 f = {lo, hi}; bf16v2 b = __builtin_convertvector(f, bf16v2); return __builtin_bit_cast(unsigned, b); }
; DI float fexp2(float x) { return __builtin_amdgcn_exp2f(x); }
; DI float rotr1(float v) { return __int_as_float(__builtin_amdgcn_mov_dpp(__float_as_int(v), 0x121, 0xf, 0xf, false)); }
; DI float rotl1(float v) { return __int_as_float(__builtin_amdgcn_mov_dpp(__float_as_int(v), 0x12f, 0xf, 0xf, false)); }
; DI float gelu_tanh(float x) { const float t = x * (1.5957691216057308f + 0.0713548162726009f * x * x); return x * __builtin_amdgcn_rcpf(1.0f + fexp2(-LOG2E * t)); }
;     DI void operator()(const f32x4 (&acc)[2][2][4][2], const pg8::Unit& u, int wr, int wc, int fr, int fq, int ui) const {
;     ...
;                 for (int m = 0; m < 4; ++m) { const float s_ = tab[ai * 128 + m * 16]; U[m] = acc[ai][0][m][n] * s_; G[m] = acc[ai][1][m][n] * s_; }
;     ...
;                 for (int m = 0; m < 4; ++m) {
;                     float o[4];
; #pragma unroll
;                     for (int e = 0; e < 4; ++e) {
;                         const float pu_s = rotr1(U[m][e]), pg_s = rotr1(G[m][e]), nu_s = rotl1(U[m][e]), ng_s = rotl1(G[m][e]);
;                         const float pu_x = rotr1(U[m > 0 ? m - 1 : 0][e]), pg_x = rotr1(G[m > 0 ? m - 1 : 0][e]);
;                         const float nu_x = rotl1(U[m < 3 ? m + 1 : 3][e]), ng_x = rotl1(G[m < 3 ? m + 1 : 3][e]);
;                         const float pu = fr == 0 ? pu_x : pu_s, pg = fr == 0 ? pg_x : pg_s, nu = fr == 15 ? nu_x : nu_s, ng = fr == 15 ? ng_x : ng_s;
;                         const float yu = bu[e] + pu * wu[0][e] + U[m][e] * wu[1][e] + nu * wu[2][e];
;                         const float yg = bg[e] + pg * wg[0][e] + G[m][e] * wg[1][e] + ng * wg[2][e];
;                         o[e] = yu * gelu_tanh(yg);
;                     }
;                     const bool edge_row = (m == 0 && fr == 0) || (m == 3 && fr == 15);
;                     if (!edge_row) { u32x2 w; w.x = pack_bf16(o[0], o[1]); w.y = pack_bf16(o[2], o[3]); *(u32x2*)(O + (size_t)(rowb + m * 16 + fr) * FF + f0) = w; }
.LBB0_1148:
	s_or_b64 exec, exec, s[58:59]
	v_mov_b32_e32 v220, v217
	v_pk_mul_f32 v[176:177], v[176:177], v[220:221] op_sel_hi:[1,0]
	v_pk_mul_f32 v[174:175], v[174:175], v[220:221] op_sel_hi:[1,0]
	v_pk_mul_f32 v[172:173], v[172:173], v[220:221] op_sel_hi:[1,0]
	v_pk_mul_f32 v[170:171], v[170:171], v[220:221] op_sel_hi:[1,0]
	v_or_b32_e32 v239, s31, v204
	v_mov_b32_dpp v220, v190 row_ror:1 row_mask:0xf bank_mask:0xf
	v_mov_b32_dpp v222, v218 row_ror:1 row_mask:0xf bank_mask:0xf
	v_mov_b32_dpp v245, v190 row_ror:15 row_mask:0xf bank_mask:0xf
	v_mov_b32_dpp v243, v218 row_ror:15 row_mask:0xf bank_mask:0xf
	v_mov_b32_dpp v246, v174 row_ror:15 row_mask:0xf bank_mask:0xf
	v_mov_b32_dpp v244, v170 row_ror:15 row_mask:0xf bank_mask:0xf
	v_mov_b32_dpp v221, v191 row_ror:1 row_mask:0xf bank_mask:0xf
	v_mov_b32_dpp v223, v219 row_ror:1 row_mask:0xf bank_mask:0xf
	v_mov_b32_dpp v241, v191 row_ror:15 row_mask:0xf bank_mask:0xf
	v_mov_b32_dpp v247, v219 row_ror:15 row_mask:0xf bank_mask:0xf
	v_mov_b32_dpp v242, v175 row_ror:15 row_mask:0xf bank_mask:0xf
	v_mov_b32_dpp v248, v171 row_ror:15 row_mask:0xf bank_mask:0xf
	v_mov_b32_dpp v224, v192 row_ror:1 row_mask:0xf bank_mask:0xf
	v_mov_b32_dpp v226, v188 row_ror:1 row_mask:0xf bank_mask:0xf
	v_mov_b32_dpp v207, v192 row_ror:15 row_mask:0xf bank_mask:0xf
	v_mov_b32_dpp v251, v188 row_ror:15 row_mask:0xf bank_mask:0xf
	v_mov_b32_dpp v232, v176 row_ror:15 row_mask:0xf bank_mask:0xf
	v_mov_b32_dpp v252, v172 row_ror:15 row_mask:0xf bank_mask:0xf
	v_mov_b32_dpp v225, v193 row_ror:1 row_mask:0xf bank_mask:0xf
	v_mov_b32_dpp v227, v189 row_ror:1 row_mask:0xf bank_mask:0xf
	v_mov_b32_dpp v249, v193 row_ror:15 row_mask:0xf bank_mask:0xf
	v_mov_b32_dpp v253, v189 row_ror:15 row_mask:0xf bank_mask:0xf
	v_mov_b32_dpp v250, v177 row_ror:15 row_mask:0xf bank_mask:0xf
	v_mov_b32_dpp v231, v173 row_ror:15 row_mask:0xf bank_mask:0xf
	s_and_saveexec_b64 s[58:59], s[8:9]
	s_xor_b64 s[58:59], exec, s[58:59]
	s_cbranch_execz .LBB0_1150
	s_waitcnt vmcnt(0)
	v_pk_fma_f32 v[226:227], v[144:145], v[226:227], v[160:161]
	v_cndmask_b32_e64 v252, v251, v252, s[14:15]
	v_cndmask_b32_e64 v253, v253, v231, s[14:15]
	v_pk_fma_f32 v[226:227], v[152:153], v[188:189], v[226:227]
	v_cndmask_b32_e64 v234, v207, v232, s[14:15]
	v_pk_fma_f32 v[226:227], v[156:157], v[252:253], v[226:227]
	v_cndmask_b32_e64 v235, v249, v250, s[14:15]
	v_mul_f32_e32 v207, 0xbdd2d3e7, v227
	v_fmaak_f32 v207, v227, v207, 0xc0135761
	v_mul_f32_e32 v231, 0xbdd2d3e7, v226
	v_mul_f32_e32 v207, v227, v207
	v_fmaak_f32 v231, v226, v231, 0xc0135761
	v_mul_f32_e32 v231, v226, v231
	v_exp_f32_e32 v207, v207
	v_exp_f32_e32 v231, v231
	v_pk_fma_f32 v[224:225], v[132:133], v[224:225], v[148:149]
	v_add_f32_e32 v207, 1.0, v207
	v_rcp_f32_e32 v251, v207
	v_add_f32_e32 v207, 1.0, v231
	v_rcp_f32_e32 v250, v207
	v_pk_fma_f32 v[224:225], v[136:137], v[192:193], v[224:225]
	v_pk_fma_f32 v[222:223], v[142:143], v[222:223], v[158:159]
	v_pk_fma_f32 v[224:225], v[140:141], v[234:235], v[224:225]
	v_cndmask_b32_e64 v234, v243, v244, s[14:15]
	v_cndmask_b32_e64 v235, v247, v248, s[14:15]
	v_pk_fma_f32 v[222:223], v[150:151], v[218:219], v[222:223]
	v_pk_mul_f32 v[226:227], v[226:227], v[250:251]
	v_pk_fma_f32 v[222:223], v[154:155], v[234:235], v[222:223]
	v_pk_mul_f32 v[224:225], v[224:225], v[226:227]
	v_mul_f32_e32 v207, 0xbdd2d3e7, v223
	v_fmaak_f32 v207, v223, v207, 0xc0135761
	v_mul_f32_e32 v227, 0xbdd2d3e7, v222
	v_mul_f32_e32 v207, v223, v207
	v_fmaak_f32 v227, v222, v227, 0xc0135761
	v_mul_f32_e32 v227, v222, v227
	v_exp_f32_e32 v207, v207
	v_exp_f32_e32 v231, v227
	v_pk_fma_f32 v[220:221], v[130:131], v[220:221], v[146:147]
	v_add_f32_e32 v207, 1.0, v207
	v_rcp_f32_e32 v235, v207
	v_add_f32_e32 v207, 1.0, v231
	v_rcp_f32_e32 v234, v207
	v_cndmask_b32_e64 v226, v245, v246, s[14:15]
	v_cndmask_b32_e64 v227, v241, v242, s[14:15]
	v_pk_fma_f32 v[220:221], v[134:135], v[190:191], v[220:221]
	v_pk_mul_f32 v[222:223], v[222:223], v[234:235]
	v_pk_fma_f32 v[220:221], v[138:139], v[226:227], v[220:221]
	s_nop 0
	v_pk_mul_f32 v[220:221], v[220:221], v[222:223]
	v_mov_b64_e32 v[222:223], s[24:25]
	v_mad_i64_i32 v[222:223], s[70:71], v239, s57, v[222:223]
	v_cvt_pk_bf16_f32 v220, v220, v221
	v_cvt_pk_bf16_f32 v221, v224, v225
	v_lshl_add_u64 v[222:223], v[214:215], 1, v[222:223]
	global_store_dwordx2 v[222:223], v[220:221], off
; DI unsigned pack_bf16(float lo, float hi) { f32v2 f = {lo, hi}; bf16v2 b = __builtin_convertvector(f, bf16v2); return __builtin_bit_cast(unsigned, b); }
; DI float fexp2(float x) { return __builtin_amdgcn_exp2f(x); }
; DI float rotr1(float v) { return __int_as_float(__builtin_amdgcn_mov_dpp(__float_as_int(v), 0x121, 0xf, 0xf, false)); }
; DI float rotl1(float v) { return __int_as_float(__builtin_amdgcn_mov_dpp(__float_as_int(v), 0x12f, 0xf, 0xf, false)); }
; DI float gelu_tanh(float x) { const float t = x * (1.5957691216057308f + 0.0713548162726009f * x * x); return x * __builtin_amdgcn_rcpf(1.0f + fexp2(-LOG2E * t)); }
;     DI void operator()(const f32x4 (&acc)[2][2][4][2], const pg8::Unit& u, int wr, int wc, int fr, int fq, int ui) const {
;     ...
;                 for (int m = 0; m < 4; ++m) {
;                     float o[4];
; #pragma unroll
;                     for (int e = 0; e < 4; ++e) {
;                         const float pu_s = rotr1(U[m][e]), pg_s = rotr1(G[m][e]), nu_s = rotl1(U[m][e]), ng_s = rotl1(G[m][e]);
;                         const float pu_x = rotr1(U[m > 0 ? m - 1 : 0][e]), pg_x = rotr1(G[m > 0 ? m - 1 : 0][e]);
;                         const float nu_x = rotl1(U[m < 3 ? m + 1 : 3][e]), ng_x = rotl1(G[m < 3 ? m + 1 : 3][e]);
;                         const float pu = fr == 0 ? pu_x : pu_s, pg = fr == 0 ? pg_x : pg_s, nu = fr == 15 ? nu_x : nu_s, ng = fr == 15 ? ng_x : ng_s;
;                         const float yu = bu[e] + pu * wu[0][e] + U[m][e] * wu[1][e] + nu * wu[2][e];
;                         const float yg = bg[e] + pg * wg[0][e] + G[m][e] * wg[1][e] + ng * wg[2][e];
;                         o[e] = yu * gelu_tanh(yg);
;                     }
;                     const bool edge_row = (m == 0 && fr == 0) || (m == 3 && fr == 15);
;                     if (!edge_row) { u32x2 w; w.x = pack_bf16(o[0], o[1]); w.y = pack_bf16(o[2], o[3]); *(u32x2*)(O + (size_t)(rowb + m * 16 + fr) * FF + f0) = w; }
.LBB0_1150:
	s_andn2_saveexec_b64 s[58:59], s[58:59]
	s_or_b64 exec, exec, s[58:59]
	v_pk_mul_f32 v[224:225], v[162:163], v[186:187] op_sel_hi:[1,0]
	v_mov_b32_dpp v243, v172 row_ror:1 row_mask:0xf bank_mask:0xf
	v_mov_b32_dpp v162, v188 row_ror:1 row_mask:0xf bank_mask:0xf
	v_mov_b32_dpp v251, v173 row_ror:1 row_mask:0xf bank_mask:0xf
	v_mov_b32_dpp v163, v189 row_ror:1 row_mask:0xf bank_mask:0xf
	v_pk_mul_f32 v[222:223], v[164:165], v[186:187] op_sel_hi:[1,0]
	v_cndmask_b32_e64 v163, v251, v163, s[10:11]
	v_cndmask_b32_e64 v162, v243, v162, s[10:11]
	v_mov_b32_dpp v164, v172 row_ror:15 row_mask:0xf bank_mask:0xf
	v_mov_b32_dpp v249, v222 row_ror:15 row_mask:0xf bank_mask:0xf
	v_mov_b32_dpp v165, v173 row_ror:15 row_mask:0xf bank_mask:0xf
	v_mov_b32_dpp v252, v223 row_ror:15 row_mask:0xf bank_mask:0xf
	s_waitcnt vmcnt(0)
	v_pk_fma_f32 v[162:163], v[144:145], v[162:163], v[160:161]
	v_cndmask_b32_e64 v165, v165, v252, s[14:15]
	v_pk_fma_f32 v[162:163], v[152:153], v[172:173], v[162:163]
	v_cndmask_b32_e64 v164, v164, v249, s[14:15]
	v_pk_fma_f32 v[162:163], v[156:157], v[164:165], v[162:163]
	v_pk_mul_f32 v[220:221], v[168:169], v[186:187] op_sel_hi:[1,0]
	v_mul_f32_e32 v164, 0xbdd2d3e7, v163
	v_fmaak_f32 v164, v163, v164, 0xc0135761
	v_mul_f32_e32 v164, v163, v164
	v_exp_f32_e32 v164, v164
	v_mov_b32_dpp v242, v176 row_ror:1 row_mask:0xf bank_mask:0xf
	v_mov_b32_dpp v168, v192 row_ror:1 row_mask:0xf bank_mask:0xf
	v_mov_b32_dpp v250, v177 row_ror:1 row_mask:0xf bank_mask:0xf
	v_add_f32_e32 v164, 1.0, v164
	v_rcp_f32_e32 v165, v164
	v_mul_f32_e32 v164, 0xbdd2d3e7, v162
	v_fmaak_f32 v164, v162, v164, 0xc0135761
	v_mul_f32_e32 v164, v162, v164
	v_mov_b32_dpp v169, v193 row_ror:1 row_mask:0xf bank_mask:0xf
	v_exp_f32_e32 v164, v164
	v_cndmask_b32_e64 v169, v250, v169, s[10:11]
	v_cndmask_b32_e64 v168, v242, v168, s[10:11]
	v_mov_b32_dpp v231, v170 row_ror:1 row_mask:0xf bank_mask:0xf
	v_mov_b32_dpp v218, v218 row_ror:1 row_mask:0xf bank_mask:0xf
	v_mov_b32_dpp v244, v171 row_ror:1 row_mask:0xf bank_mask:0xf
	v_mov_b32_dpp v219, v219 row_ror:1 row_mask:0xf bank_mask:0xf
	v_pk_fma_f32 v[168:169], v[132:133], v[168:169], v[148:149]
	v_mov_b32_dpp v245, v176 row_ror:15 row_mask:0xf bank_mask:0xf
	v_mov_b32_dpp v172, v177 row_ror:15 row_mask:0xf bank_mask:0xf
	v_pk_fma_f32 v[168:169], v[136:137], v[176:177], v[168:169]
	v_cndmask_b32_e64 v177, v244, v219, s[10:11]
	v_cndmask_b32_e64 v176, v231, v218, s[10:11]
	v_mov_b32_dpp v227, v170 row_ror:15 row_mask:0xf bank_mask:0xf
	v_mov_b32_dpp v241, v224 row_ror:15 row_mask:0xf bank_mask:0xf
	v_mov_b32_dpp v235, v171 row_ror:15 row_mask:0xf bank_mask:0xf
	v_mov_b32_dpp v248, v225 row_ror:15 row_mask:0xf bank_mask:0xf
	v_add_f32_e32 v164, 1.0, v164
	v_pk_fma_f32 v[176:177], v[142:143], v[176:177], v[158:159]
	v_rcp_f32_e32 v164, v164
	v_pk_fma_f32 v[170:171], v[150:151], v[170:171], v[176:177]
	v_cndmask_b32_e64 v177, v235, v248, s[14:15]
	v_cndmask_b32_e64 v176, v227, v241, s[14:15]
	v_pk_fma_f32 v[170:171], v[154:155], v[176:177], v[170:171]
	v_mov_b32_dpp v188, v220 row_ror:15 row_mask:0xf bank_mask:0xf
	v_mov_b32_dpp v253, v221 row_ror:15 row_mask:0xf bank_mask:0xf
	v_mul_f32_e32 v176, 0xbdd2d3e7, v171
	v_cndmask_b32_e64 v173, v172, v253, s[14:15]
	v_cndmask_b32_e64 v172, v245, v188, s[14:15]
	v_fmaak_f32 v176, v171, v176, 0xc0135761
	v_mov_b32_dpp v207, v174 row_ror:1 row_mask:0xf bank_mask:0xf
	v_mov_b32_dpp v190, v190 row_ror:1 row_mask:0xf bank_mask:0xf
	v_mov_b32_dpp v246, v175 row_ror:1 row_mask:0xf bank_mask:0xf
	v_mov_b32_dpp v191, v191 row_ror:1 row_mask:0xf bank_mask:0xf
	v_mul_f32_e32 v176, v171, v176
	v_pk_fma_f32 v[168:169], v[140:141], v[172:173], v[168:169]
	v_pk_mul_f32 v[162:163], v[162:163], v[164:165]
	v_pk_mul_f32 v[166:167], v[166:167], v[186:187] op_sel_hi:[1,0]
	v_pk_mul_f32 v[162:163], v[168:169], v[162:163]
	v_cndmask_b32_e64 v169, v246, v191, s[10:11]
	v_cndmask_b32_e64 v168, v207, v190, s[10:11]
	v_mov_b32_dpp v226, v174 row_ror:15 row_mask:0xf bank_mask:0xf
	v_mov_b32_dpp v232, v166 row_ror:15 row_mask:0xf bank_mask:0xf
	v_mov_b32_dpp v234, v175 row_ror:15 row_mask:0xf bank_mask:0xf
	v_mov_b32_dpp v247, v167 row_ror:15 row_mask:0xf bank_mask:0xf
	v_exp_f32_e32 v176, v176
	v_pk_fma_f32 v[168:169], v[130:131], v[168:169], v[146:147]
	v_cndmask_b32_e64 v173, v234, v247, s[14:15]
	v_pk_fma_f32 v[168:169], v[134:135], v[174:175], v[168:169]
	v_cndmask_b32_e64 v172, v226, v232, s[14:15]
	v_mov_b32_dpp v192, v222 row_ror:1 row_mask:0xf bank_mask:0xf
	v_mov_b32_dpp v193, v223 row_ror:1 row_mask:0xf bank_mask:0xf
	v_pk_fma_f32 v[168:169], v[138:139], v[172:173], v[168:169]
	v_cndmask_b32_e64 v173, v193, v251, s[10:11]
	v_cndmask_b32_e64 v172, v192, v243, s[10:11]
	v_mov_b32_dpp v174, v180 row_ror:15 row_mask:0xf bank_mask:0xf
	v_mov_b32_dpp v175, v181 row_ror:15 row_mask:0xf bank_mask:0xf
	v_pk_fma_f32 v[172:173], v[144:145], v[172:173], v[160:161]
	v_add_f32_e32 v164, 1.0, v176
	v_pk_fma_f32 v[172:173], v[152:153], v[222:223], v[172:173]
	v_cndmask_b32_e64 v219, v252, v175, s[14:15]
	v_cndmask_b32_e64 v218, v249, v174, s[14:15]
	v_rcp_f32_e32 v165, v164
	v_mul_f32_e32 v164, 0xbdd2d3e7, v170
	v_pk_fma_f32 v[222:223], v[156:157], v[218:219], v[172:173]
	v_fmaak_f32 v164, v170, v164, 0xc0135761
	v_mul_f32_e32 v172, 0xbdd2d3e7, v223
	v_mul_f32_e32 v164, v170, v164
	v_fmaak_f32 v172, v223, v172, 0xc0135761
	v_mul_f32_e32 v172, v223, v172
	v_exp_f32_e32 v164, v164
	v_exp_f32_e32 v219, v172
	v_mov_b64_e32 v[226:227], s[24:25]
	v_add_f32_e32 v164, 1.0, v164
	v_rcp_f32_e32 v164, v164
	v_add_f32_e32 v219, 1.0, v219
	v_rcp_f32_e32 v235, v219
	v_mul_f32_e32 v219, 0xbdd2d3e7, v222
; DI unsigned pack_bf16(float lo, float hi) { f32v2 f = {lo, hi}; bf16v2 b = __builtin_convertvector(f, bf16v2); return __builtin_bit_cast(unsigned, b); }
; DI float fexp2(float x) { return __builtin_amdgcn_exp2f(x); }
; DI float rotr1(float v) { return __int_as_float(__builtin_amdgcn_mov_dpp(__float_as_int(v), 0x121, 0xf, 0xf, false)); }
; DI float rotl1(float v) { return __int_as_float(__builtin_amdgcn_mov_dpp(__float_as_int(v), 0x12f, 0xf, 0xf, false)); }
; DI float gelu_tanh(float x) { const float t = x * (1.5957691216057308f + 0.0713548162726009f * x * x); return x * __builtin_amdgcn_rcpf(1.0f + fexp2(-LOG2E * t)); }
;     DI void operator()(const f32x4 (&acc)[2][2][4][2], const pg8::Unit& u, int wr, int wc, int fr, int fq, int ui) const {
;     ...
;                 for (int m = 0; m < 4; ++m) {
;                     float o[4];
; #pragma unroll
;                     for (int e = 0; e < 4; ++e) {
;                         const float pu_s = rotr1(U[m][e]), pg_s = rotr1(G[m][e]), nu_s = rotl1(U[m][e]), ng_s = rotl1(G[m][e]);
;                         const float pu_x = rotr1(U[m > 0 ? m - 1 : 0][e]), pg_x = rotr1(G[m > 0 ? m - 1 : 0][e]);
;                         const float nu_x = rotl1(U[m < 3 ? m + 1 : 3][e]), ng_x = rotl1(G[m < 3 ? m + 1 : 3][e]);
;                         const float pu = fr == 0 ? pu_x : pu_s, pg = fr == 0 ? pg_x : pg_s, nu = fr == 15 ? nu_x : nu_s, ng = fr == 15 ? ng_x : ng_s;
;                         const float yu = bu[e] + pu * wu[0][e] + U[m][e] * wu[1][e] + nu * wu[2][e];
;                         const float yg = bg[e] + pg * wg[0][e] + G[m][e] * wg[1][e] + ng * wg[2][e];
;                         o[e] = yu * gelu_tanh(yg);
;                     }
;                     const bool edge_row = (m == 0 && fr == 0) || (m == 3 && fr == 15);
;                     if (!edge_row) { u32x2 w; w.x = pack_bf16(o[0], o[1]); w.y = pack_bf16(o[2], o[3]); *(u32x2*)(O + (size_t)(rowb + m * 16 + fr) * FF + f0) = w; }
	v_fmaak_f32 v219, v222, v219, 0xc0135761
	v_mul_f32_e32 v219, v222, v219
	v_pk_mul_f32 v[164:165], v[170:171], v[164:165]
	v_cvt_pk_bf16_f32 v171, v162, v163
	v_or_b32_e32 v162, 16, v239
	v_pk_mul_f32 v[164:165], v[168:169], v[164:165]
	v_mad_i64_i32 v[162:163], s[58:59], v162, s57, v[226:227]
	v_lshlrev_b64 v[168:169], 1, v[214:215]
	v_mov_b32_dpp v177, v224 row_ror:1 row_mask:0xf bank_mask:0xf
	v_mov_b32_dpp v189, v225 row_ror:1 row_mask:0xf bank_mask:0xf
	v_exp_f32_e32 v219, v219
	v_cvt_pk_bf16_f32 v170, v164, v165
	v_lshl_add_u64 v[164:165], v[162:163], 0, v[168:169]
	v_mov_b32_dpp v191, v220 row_ror:1 row_mask:0xf bank_mask:0xf
	v_mov_b32_dpp v218, v221 row_ror:1 row_mask:0xf bank_mask:0xf
	v_cndmask_b32_e64 v245, v189, v244, s[10:11]
	v_cndmask_b32_e64 v244, v177, v231, s[10:11]
	global_store_dwordx2 v[164:165], v[170:171], off
	v_mov_b32_dpp v170, v178 row_ror:15 row_mask:0xf bank_mask:0xf
	v_mov_b32_dpp v171, v179 row_ror:15 row_mask:0xf bank_mask:0xf
	v_cndmask_b32_e64 v243, v218, v250, s[10:11]
	v_cndmask_b32_e64 v242, v191, v242, s[10:11]
	v_pk_fma_f32 v[244:245], v[142:143], v[244:245], v[158:159]
	v_mov_b32_dpp v172, v184 row_ror:15 row_mask:0xf bank_mask:0xf
	v_pk_fma_f32 v[242:243], v[132:133], v[242:243], v[148:149]
	v_pk_fma_f32 v[224:225], v[150:151], v[224:225], v[244:245]
	v_cndmask_b32_e64 v245, v248, v171, s[14:15]
	v_cndmask_b32_e64 v244, v241, v170, s[14:15]
	v_pk_fma_f32 v[220:221], v[136:137], v[220:221], v[242:243]
	v_cndmask_b32_e64 v242, v188, v172, s[14:15]
	v_add_f32_e32 v188, 1.0, v219
	v_pk_fma_f32 v[224:225], v[154:155], v[244:245], v[224:225]
	v_rcp_f32_e32 v234, v188
	v_mul_f32_e32 v188, 0xbdd2d3e7, v225
	v_fmaak_f32 v188, v225, v188, 0xc0135761
	v_mul_f32_e32 v188, v225, v188
	v_exp_f32_e32 v188, v188
	v_mov_b32_dpp v173, v185 row_ror:15 row_mask:0xf bank_mask:0xf
	v_cndmask_b32_e64 v243, v253, v173, s[14:15]
	v_pk_fma_f32 v[220:221], v[140:141], v[242:243], v[220:221]
	v_pk_mul_f32 v[222:223], v[222:223], v[234:235]
	v_add_f32_e32 v188, 1.0, v188
	v_pk_mul_f32 v[220:221], v[220:221], v[222:223]
	v_rcp_f32_e32 v223, v188
	v_mul_f32_e32 v188, 0xbdd2d3e7, v224
	v_fmaak_f32 v188, v224, v188, 0xc0135761
	v_mul_f32_e32 v188, v224, v188
	v_exp_f32_e32 v188, v188
	v_mov_b32_dpp v176, v166 row_ror:1 row_mask:0xf bank_mask:0xf
	v_mov_b32_dpp v190, v167 row_ror:1 row_mask:0xf bank_mask:0xf
	v_cndmask_b32_e64 v235, v190, v246, s[10:11]
	v_add_f32_e32 v188, 1.0, v188
	v_rcp_f32_e32 v222, v188
	v_cndmask_b32_e64 v234, v176, v207, s[10:11]
	v_mov_b32_dpp v162, v182 row_ror:15 row_mask:0xf bank_mask:0xf
	v_mov_b32_dpp v163, v183 row_ror:15 row_mask:0xf bank_mask:0xf
	v_pk_fma_f32 v[234:235], v[130:131], v[234:235], v[146:147]
	v_pk_mul_f32 v[222:223], v[224:225], v[222:223]
	v_pk_fma_f32 v[166:167], v[134:135], v[166:167], v[234:235]
	v_cndmask_b32_e64 v235, v247, v163, s[14:15]
	v_cndmask_b32_e64 v234, v232, v162, s[14:15]
	v_pk_fma_f32 v[166:167], v[138:139], v[234:235], v[166:167]
	v_mov_b32_dpp v219, v182 row_ror:1 row_mask:0xf bank_mask:0xf
	v_pk_mul_f32 v[166:167], v[166:167], v[222:223]
	v_cvt_pk_bf16_f32 v223, v220, v221
	v_cvt_pk_bf16_f32 v222, v166, v167
	v_or_b32_e32 v166, 32, v239
	v_mad_i64_i32 v[166:167], s[58:59], v166, s57, v[226:227]
	v_lshl_add_u64 v[166:167], v[166:167], 0, v[168:169]
	global_store_dwordx2 v[166:167], v[222:223], off
	v_mov_b32_dpp v220, v178 row_ror:1 row_mask:0xf bank_mask:0xf
	v_mov_b32_dpp v222, v183 row_ror:1 row_mask:0xf bank_mask:0xf
	v_mov_b32_dpp v221, v179 row_ror:1 row_mask:0xf bank_mask:0xf
	v_mov_b32_dpp v207, v184 row_ror:1 row_mask:0xf bank_mask:0xf
	v_mov_b32_dpp v223, v180 row_ror:1 row_mask:0xf bank_mask:0xf
	v_mov_b32_dpp v225, v185 row_ror:1 row_mask:0xf bank_mask:0xf
	v_mov_b32_dpp v224, v181 row_ror:1 row_mask:0xf bank_mask:0xf
	v_or_b32_e32 v188, 48, v239
	s_and_saveexec_b64 s[58:59], s[12:13]
	s_cbranch_execz .LBB0_1152
	v_cndmask_b32_e64 v193, v224, v193, s[10:11]
	v_cndmask_b32_e64 v192, v223, v192, s[10:11]
	v_pk_fma_f32 v[192:193], v[144:145], v[192:193], v[160:161]
	v_cndmask_b32_e64 v225, v225, v218, s[10:11]
	v_pk_fma_f32 v[180:181], v[152:153], v[180:181], v[192:193]
	v_cndmask_b32_e64 v224, v207, v191, s[10:11]
	v_pk_fma_f32 v[174:175], v[156:157], v[174:175], v[180:181]
	s_nop 0
	v_mul_f32_e32 v180, 0xbdd2d3e7, v175
	v_fmaak_f32 v180, v175, v180, 0xc0135761
	v_mul_f32_e32 v181, 0xbdd2d3e7, v174
	v_mul_f32_e32 v180, v175, v180
	v_fmaak_f32 v181, v174, v181, 0xc0135761
	v_mul_f32_e32 v181, v174, v181
	v_exp_f32_e32 v180, v180
	v_exp_f32_e32 v192, v181
	v_add_f32_e32 v180, 1.0, v180
	v_rcp_f32_e32 v181, v180
	v_add_f32_e32 v180, 1.0, v192
	v_rcp_f32_e32 v180, v180
	v_pk_fma_f32 v[192:193], v[132:133], v[224:225], v[148:149]
	v_pk_mul_f32 v[174:175], v[174:175], v[180:181]
	v_cndmask_b32_e64 v181, v221, v189, s[10:11]
	v_cndmask_b32_e64 v180, v220, v177, s[10:11]
	v_pk_fma_f32 v[180:181], v[142:143], v[180:181], v[158:159]
	v_pk_fma_f32 v[184:185], v[136:137], v[184:185], v[192:193]
	v_pk_fma_f32 v[178:179], v[150:151], v[178:179], v[180:181]
	v_pk_fma_f32 v[172:173], v[140:141], v[172:173], v[184:185]
	v_pk_fma_f32 v[170:171], v[154:155], v[170:171], v[178:179]
	v_pk_mul_f32 v[172:173], v[172:173], v[174:175]
	v_mul_f32_e32 v174, 0xbdd2d3e7, v171
	v_fmaak_f32 v174, v171, v174, 0xc0135761
	v_mul_f32_e32 v174, v171, v174
	v_exp_f32_e32 v177, v174
	v_mul_f32_e32 v174, 0xbdd2d3e7, v170
	v_fmaak_f32 v174, v170, v174, 0xc0135761
	v_mul_f32_e32 v174, v170, v174
	v_exp_f32_e32 v178, v174
	v_cndmask_b32_e64 v174, v219, v176, s[10:11]
	v_add_f32_e32 v176, 1.0, v177
	v_rcp_f32_e32 v177, v176
	v_add_f32_e32 v176, 1.0, v178
	v_rcp_f32_e32 v176, v176
	v_cndmask_b32_e64 v175, v222, v190, s[10:11]
	v_pk_fma_f32 v[174:175], v[130:131], v[174:175], v[146:147]
	v_pk_mul_f32 v[170:171], v[170:171], v[176:177]
	v_pk_fma_f32 v[174:175], v[134:135], v[182:183], v[174:175]
	s_nop 0
	v_pk_fma_f32 v[162:163], v[138:139], v[162:163], v[174:175]
	s_nop 0
	v_pk_mul_f32 v[162:163], v[162:163], v[170:171]
	v_mov_b64_e32 v[170:171], s[24:25]
	v_mad_i64_i32 v[170:171], s[70:71], v188, s57, v[170:171]
	v_cvt_pk_bf16_f32 v162, v162, v163
	v_cvt_pk_bf16_f32 v163, v172, v173
	v_lshl_add_u64 v[170:171], v[214:215], 1, v[170:171]
	global_store_dwordx2 v[170:171], v[162:163], off

; DI unsigned pack_bf16(float lo, float hi) { f32v2 f = {lo, hi}; bf16v2 b = __builtin_convertvector(f, bf16v2); return __builtin_bit_cast(unsigned, b); }
; DI float fexp2(float x) { return __builtin_amdgcn_exp2f(x); }
; DI float rotr1(float v) { return __int_as_float(__builtin_amdgcn_mov_dpp(__float_as_int(v), 0x121, 0xf, 0xf, false)); }
; DI float rotl1(float v) { return __int_as_float(__builtin_amdgcn_mov_dpp(__float_as_int(v), 0x12f, 0xf, 0xf, false)); }
; DI float gelu_tanh(float x) { const float t = x * (1.5957691216057308f + 0.0713548162726009f * x * x); return x * __builtin_amdgcn_rcpf(1.0f + fexp2(-LOG2E * t)); }
;     DI void operator()(const f32x4 (&acc)[2][2][4][2], const pg8::Unit& u, int wr, int wc, int fr, int fq, int ui) const {
;     ...
;                 for (int m = 0; m < 4; ++m) { const float s_ = tab[ai * 128 + m * 16]; U[m] = acc[ai][0][m][n] * s_; G[m] = acc[ai][1][m][n] * s_; }
;     ...
;                 for (int m = 0; m < 4; ++m) {
;                     float o[4];
; #pragma unroll
;                     for (int e = 0; e < 4; ++e) {
;                         const float pu_s = rotr1(U[m][e]), pg_s = rotr1(G[m][e]), nu_s = rotl1(U[m][e]), ng_s = rotl1(G[m][e]);
;                         const float pu_x = rotr1(U[m > 0 ? m - 1 : 0][e]), pg_x = rotr1(G[m > 0 ? m - 1 : 0][e]);
;                         const float nu_x = rotl1(U[m < 3 ? m + 1 : 3][e]), ng_x = rotl1(G[m < 3 ? m + 1 : 3][e]);
;                         const float pu = fr == 0 ? pu_x : pu_s, pg = fr == 0 ? pg_x : pg_s, nu = fr == 15 ? nu_x : nu_s, ng = fr == 15 ? ng_x : ng_s;
;                         const float yu = bu[e] + pu * wu[0][e] + U[m][e] * wu[1][e] + nu * wu[2][e];
;                         const float yg = bg[e] + pg * wg[0][e] + G[m][e] * wg[1][e] + ng * wg[2][e];
;                         o[e] = yu * gelu_tanh(yg);
;                     }
;                     const bool edge_row = (m == 0 && fr == 0) || (m == 3 && fr == 15);
;                     if (!edge_row) { u32x2 w; w.x = pack_bf16(o[0], o[1]); w.y = pack_bf16(o[2], o[3]); *(u32x2*)(O + (size_t)(rowb + m * 16 + fr) * FF + f0) = w; }
.LBB0_1156:
	s_or_b64 exec, exec, s[58:59]
	v_mov_b32_e32 v172, v163
	v_pk_mul_f32 v[116:117], v[116:117], v[172:173] op_sel_hi:[1,0]
	v_pk_mul_f32 v[114:115], v[114:115], v[172:173] op_sel_hi:[1,0]
	v_pk_mul_f32 v[108:109], v[108:109], v[172:173] op_sel_hi:[1,0]
	v_pk_mul_f32 v[106:107], v[106:107], v[172:173] op_sel_hi:[1,0]
	v_or_b32_e32 v180, s35, v204
	v_mov_b32_dpp v172, v126 row_ror:1 row_mask:0xf bank_mask:0xf
	v_mov_b32_dpp v174, v170 row_ror:1 row_mask:0xf bank_mask:0xf
	v_mov_b32_dpp v185, v126 row_ror:15 row_mask:0xf bank_mask:0xf
	v_mov_b32_dpp v183, v170 row_ror:15 row_mask:0xf bank_mask:0xf
	v_mov_b32_dpp v189, v114 row_ror:15 row_mask:0xf bank_mask:0xf
	v_mov_b32_dpp v184, v106 row_ror:15 row_mask:0xf bank_mask:0xf
	v_mov_b32_dpp v173, v127 row_ror:1 row_mask:0xf bank_mask:0xf
	v_mov_b32_dpp v175, v171 row_ror:1 row_mask:0xf bank_mask:0xf
	v_mov_b32_dpp v181, v127 row_ror:15 row_mask:0xf bank_mask:0xf
	v_mov_b32_dpp v190, v171 row_ror:15 row_mask:0xf bank_mask:0xf
	v_mov_b32_dpp v182, v115 row_ror:15 row_mask:0xf bank_mask:0xf
	v_mov_b32_dpp v191, v107 row_ror:15 row_mask:0xf bank_mask:0xf
	v_mov_b32_dpp v176, v128 row_ror:1 row_mask:0xf bank_mask:0xf
	v_mov_b32_dpp v178, v124 row_ror:1 row_mask:0xf bank_mask:0xf
	v_mov_b32_dpp v220, v128 row_ror:15 row_mask:0xf bank_mask:0xf
	v_mov_b32_dpp v207, v124 row_ror:15 row_mask:0xf bank_mask:0xf
	v_mov_b32_dpp v222, v116 row_ror:15 row_mask:0xf bank_mask:0xf
	v_mov_b32_dpp v218, v108 row_ror:15 row_mask:0xf bank_mask:0xf
	v_mov_b32_dpp v177, v129 row_ror:1 row_mask:0xf bank_mask:0xf
	v_mov_b32_dpp v179, v125 row_ror:1 row_mask:0xf bank_mask:0xf
	v_mov_b32_dpp v192, v129 row_ror:15 row_mask:0xf bank_mask:0xf
	v_mov_b32_dpp v219, v125 row_ror:15 row_mask:0xf bank_mask:0xf
	v_mov_b32_dpp v193, v117 row_ror:15 row_mask:0xf bank_mask:0xf
	v_mov_b32_dpp v221, v109 row_ror:15 row_mask:0xf bank_mask:0xf
	s_and_saveexec_b64 s[58:59], s[8:9]
	s_cbranch_execz .LBB0_1158
	v_pk_fma_f32 v[178:179], v[144:145], v[178:179], v[160:161]
	v_cndmask_b32_e64 v218, v207, v218, s[14:15]
	v_cndmask_b32_e64 v219, v219, v221, s[14:15]
	v_pk_fma_f32 v[178:179], v[152:153], v[124:125], v[178:179]
	v_cndmask_b32_e64 v221, v192, v193, s[14:15]
	v_pk_fma_f32 v[178:179], v[156:157], v[218:219], v[178:179]
	v_pk_fma_f32 v[176:177], v[132:133], v[176:177], v[148:149]
	v_mul_f32_e32 v207, 0xbdd2d3e7, v179
	v_fmaak_f32 v207, v179, v207, 0xc0135761
	v_mul_f32_e32 v218, 0xbdd2d3e7, v178
	v_mul_f32_e32 v207, v179, v207
	v_fmaak_f32 v218, v178, v218, 0xc0135761
	v_mul_f32_e32 v218, v178, v218
	v_exp_f32_e32 v207, v207
	v_exp_f32_e32 v218, v218
	v_cndmask_b32_e64 v220, v220, v222, s[14:15]
	v_add_f32_e32 v192, 1.0, v207
	v_rcp_f32_e32 v193, v192
	v_add_f32_e32 v192, 1.0, v218
	v_rcp_f32_e32 v192, v192
	v_pk_fma_f32 v[176:177], v[136:137], v[128:129], v[176:177]
	v_pk_fma_f32 v[174:175], v[142:143], v[174:175], v[158:159]
	v_pk_fma_f32 v[176:177], v[140:141], v[220:221], v[176:177]
	v_pk_mul_f32 v[178:179], v[178:179], v[192:193]
	v_cndmask_b32_e64 v184, v183, v184, s[14:15]
	v_pk_mul_f32 v[176:177], v[176:177], v[178:179]
	v_cndmask_b32_e64 v178, v185, v189, s[14:15]
	v_cndmask_b32_e64 v185, v190, v191, s[14:15]
	v_pk_fma_f32 v[174:175], v[150:151], v[170:171], v[174:175]
	v_pk_fma_f32 v[172:173], v[130:131], v[172:173], v[146:147]
	v_pk_fma_f32 v[174:175], v[154:155], v[184:185], v[174:175]
	v_pk_fma_f32 v[172:173], v[134:135], v[126:127], v[172:173]
	v_mul_f32_e32 v179, 0xbdd2d3e7, v175
	v_fmaak_f32 v179, v175, v179, 0xc0135761
	v_mul_f32_e32 v179, v175, v179
	v_exp_f32_e32 v183, v179
	v_mul_f32_e32 v179, 0xbdd2d3e7, v174
	v_fmaak_f32 v179, v174, v179, 0xc0135761
	v_mul_f32_e32 v179, v174, v179
	v_exp_f32_e32 v184, v179
	v_cndmask_b32_e64 v179, v181, v182, s[14:15]
	v_add_f32_e32 v181, 1.0, v183
	v_rcp_f32_e32 v183, v181
	v_add_f32_e32 v181, 1.0, v184
	v_rcp_f32_e32 v182, v181
	v_pk_fma_f32 v[172:173], v[138:139], v[178:179], v[172:173]
	v_pk_mul_f32 v[174:175], v[174:175], v[182:183]
	s_nop 0
	v_pk_mul_f32 v[172:173], v[172:173], v[174:175]
	v_mov_b64_e32 v[174:175], s[24:25]
	v_mad_i64_i32 v[174:175], s[70:71], v180, s57, v[174:175]
	v_cvt_pk_bf16_f32 v172, v172, v173
	v_cvt_pk_bf16_f32 v173, v176, v177
	v_lshl_add_u64 v[174:175], v[214:215], 1, v[174:175]
	global_store_dwordx2 v[174:175], v[172:173], off
; DI unsigned pack_bf16(float lo, float hi) { f32v2 f = {lo, hi}; bf16v2 b = __builtin_convertvector(f, bf16v2); return __builtin_bit_cast(unsigned, b); }
; DI float fexp2(float x) { return __builtin_amdgcn_exp2f(x); }
; DI float rotr1(float v) { return __int_as_float(__builtin_amdgcn_mov_dpp(__float_as_int(v), 0x121, 0xf, 0xf, false)); }
; DI float rotl1(float v) { return __int_as_float(__builtin_amdgcn_mov_dpp(__float_as_int(v), 0x12f, 0xf, 0xf, false)); }
; DI float gelu_tanh(float x) { const float t = x * (1.5957691216057308f + 0.0713548162726009f * x * x); return x * __builtin_amdgcn_rcpf(1.0f + fexp2(-LOG2E * t)); }
;     DI void operator()(const f32x4 (&acc)[2][2][4][2], const pg8::Unit& u, int wr, int wc, int fr, int fq, int ui) const {
;     ...
;                 for (int m = 0; m < 4; ++m) {
;                     float o[4];
; #pragma unroll
;                     for (int e = 0; e < 4; ++e) {
;                         const float pu_s = rotr1(U[m][e]), pg_s = rotr1(G[m][e]), nu_s = rotl1(U[m][e]), ng_s = rotl1(G[m][e]);
;                         const float pu_x = rotr1(U[m > 0 ? m - 1 : 0][e]), pg_x = rotr1(G[m > 0 ? m - 1 : 0][e]);
;                         const float nu_x = rotl1(U[m < 3 ? m + 1 : 3][e]), ng_x = rotl1(G[m < 3 ? m + 1 : 3][e]);
;                         const float pu = fr == 0 ? pu_x : pu_s, pg = fr == 0 ? pg_x : pg_s, nu = fr == 15 ? nu_x : nu_s, ng = fr == 15 ? ng_x : ng_s;
;                         const float yu = bu[e] + pu * wu[0][e] + U[m][e] * wu[1][e] + nu * wu[2][e];
;                         const float yg = bg[e] + pg * wg[0][e] + G[m][e] * wg[1][e] + ng * wg[2][e];
;                         o[e] = yu * gelu_tanh(yg);
;                     }
;                     const bool edge_row = (m == 0 && fr == 0) || (m == 3 && fr == 15);
;                     if (!edge_row) { u32x2 w; w.x = pack_bf16(o[0], o[1]); w.y = pack_bf16(o[2], o[3]); *(u32x2*)(O + (size_t)(rowb + m * 16 + fr) * FF + f0) = w; }
.LBB0_1158:
	s_or_b64 exec, exec, s[58:59]
	v_pk_mul_f32 v[176:177], v[98:99], v[122:123] op_sel_hi:[1,0]
	v_mov_b32_dpp v218, v108 row_ror:1 row_mask:0xf bank_mask:0xf
	v_mov_b32_dpp v98, v124 row_ror:1 row_mask:0xf bank_mask:0xf
	v_mov_b32_dpp v222, v109 row_ror:1 row_mask:0xf bank_mask:0xf
	v_mov_b32_dpp v99, v125 row_ror:1 row_mask:0xf bank_mask:0xf
	v_pk_mul_f32 v[100:101], v[100:101], v[122:123] op_sel_hi:[1,0]
	v_cndmask_b32_e64 v99, v222, v99, s[10:11]
	v_cndmask_b32_e64 v98, v218, v98, s[10:11]
	v_pk_mul_f32 v[172:173], v[104:105], v[122:123] op_sel_hi:[1,0]
	v_pk_mul_f32 v[174:175], v[102:103], v[122:123] op_sel_hi:[1,0]
	v_mov_b32_dpp v102, v108 row_ror:15 row_mask:0xf bank_mask:0xf
	v_mov_b32_dpp v104, v128 row_ror:1 row_mask:0xf bank_mask:0xf
	v_mov_b32_dpp v128, v100 row_ror:15 row_mask:0xf bank_mask:0xf
	v_mov_b32_dpp v103, v109 row_ror:15 row_mask:0xf bank_mask:0xf
	v_mov_b32_dpp v223, v101 row_ror:15 row_mask:0xf bank_mask:0xf
	v_pk_fma_f32 v[98:99], v[144:145], v[98:99], v[160:161]
	v_cndmask_b32_e64 v103, v103, v223, s[14:15]
	v_pk_fma_f32 v[98:99], v[152:153], v[108:109], v[98:99]
	v_cndmask_b32_e64 v102, v102, v128, s[14:15]
	v_pk_fma_f32 v[98:99], v[156:157], v[102:103], v[98:99]
	v_mov_b32_dpp v207, v116 row_ror:1 row_mask:0xf bank_mask:0xf
	v_mul_f32_e32 v102, 0xbdd2d3e7, v99
	v_fmaak_f32 v102, v99, v102, 0xc0135761
	v_mul_f32_e32 v102, v99, v102
	v_exp_f32_e32 v102, v102
	v_mov_b32_dpp v221, v117 row_ror:1 row_mask:0xf bank_mask:0xf
	v_mov_b32_dpp v105, v129 row_ror:1 row_mask:0xf bank_mask:0xf
	v_cndmask_b32_e64 v105, v221, v105, s[10:11]
	v_add_f32_e32 v102, 1.0, v102
	v_cndmask_b32_e64 v104, v207, v104, s[10:11]
	v_mov_b32_dpp v184, v106 row_ror:1 row_mask:0xf bank_mask:0xf
	v_mov_b32_dpp v170, v170 row_ror:1 row_mask:0xf bank_mask:0xf
	v_mov_b32_dpp v185, v107 row_ror:1 row_mask:0xf bank_mask:0xf
	v_mov_b32_dpp v171, v171 row_ror:1 row_mask:0xf bank_mask:0xf
	v_rcp_f32_e32 v103, v102
	v_pk_fma_f32 v[104:105], v[132:133], v[104:105], v[148:149]
	v_mul_f32_e32 v102, 0xbdd2d3e7, v98
	v_mov_b32_dpp v219, v116 row_ror:15 row_mask:0xf bank_mask:0xf
	v_mov_b32_dpp v108, v117 row_ror:15 row_mask:0xf bank_mask:0xf
	v_fmaak_f32 v102, v98, v102, 0xc0135761
	v_pk_fma_f32 v[104:105], v[136:137], v[116:117], v[104:105]
	v_cndmask_b32_e64 v117, v185, v171, s[10:11]
	v_cndmask_b32_e64 v116, v184, v170, s[10:11]
	v_mov_b32_dpp v179, v106 row_ror:15 row_mask:0xf bank_mask:0xf
	v_mov_b32_dpp v190, v176 row_ror:15 row_mask:0xf bank_mask:0xf
	v_mov_b32_dpp v183, v107 row_ror:15 row_mask:0xf bank_mask:0xf
	v_mov_b32_dpp v193, v177 row_ror:15 row_mask:0xf bank_mask:0xf
	v_mul_f32_e32 v102, v98, v102
	v_pk_fma_f32 v[116:117], v[142:143], v[116:117], v[158:159]
	v_pk_fma_f32 v[106:107], v[150:151], v[106:107], v[116:117]
	v_cndmask_b32_e64 v117, v183, v193, s[14:15]
	v_cndmask_b32_e64 v116, v179, v190, s[14:15]
	v_exp_f32_e32 v102, v102
	v_pk_fma_f32 v[106:107], v[154:155], v[116:117], v[106:107]
	v_mov_b32_dpp v220, v172 row_ror:15 row_mask:0xf bank_mask:0xf
	v_mul_f32_e32 v116, 0xbdd2d3e7, v107
	v_fmaak_f32 v116, v107, v116, 0xc0135761
	v_mul_f32_e32 v116, v107, v116
	v_add_f32_e32 v102, 1.0, v102
	v_rcp_f32_e32 v102, v102
	v_exp_f32_e32 v116, v116
	v_mov_b32_dpp v129, v173 row_ror:15 row_mask:0xf bank_mask:0xf
	v_cndmask_b32_e64 v109, v108, v129, s[14:15]
	v_pk_mul_f32 v[98:99], v[98:99], v[102:103]
	v_add_f32_e32 v102, 1.0, v116
	v_rcp_f32_e32 v103, v102
	v_mul_f32_e32 v102, 0xbdd2d3e7, v106
	v_fmaak_f32 v102, v106, v102, 0xc0135761
	v_mul_f32_e32 v102, v106, v102
	v_exp_f32_e32 v102, v102
	v_cndmask_b32_e64 v108, v219, v220, s[14:15]
	v_mov_b32_dpp v181, v114 row_ror:1 row_mask:0xf bank_mask:0xf
	v_mov_b32_dpp v126, v126 row_ror:1 row_mask:0xf bank_mask:0xf
	v_add_f32_e32 v102, 1.0, v102
	v_rcp_f32_e32 v102, v102
	v_mov_b32_dpp v191, v115 row_ror:1 row_mask:0xf bank_mask:0xf
	v_mov_b32_dpp v127, v127 row_ror:1 row_mask:0xf bank_mask:0xf
	v_pk_fma_f32 v[104:105], v[140:141], v[108:109], v[104:105]
	v_mov_b32_dpp v178, v114 row_ror:15 row_mask:0xf bank_mask:0xf
	v_pk_mul_f32 v[98:99], v[104:105], v[98:99]
	v_cndmask_b32_e64 v105, v191, v127, s[10:11]
	v_cndmask_b32_e64 v104, v181, v126, s[10:11]
	v_mov_b32_dpp v189, v174 row_ror:15 row_mask:0xf bank_mask:0xf
	v_mov_b32_dpp v182, v115 row_ror:15 row_mask:0xf bank_mask:0xf
	v_mov_b32_dpp v192, v175 row_ror:15 row_mask:0xf bank_mask:0xf
	v_pk_fma_f32 v[104:105], v[130:131], v[104:105], v[146:147]
	v_mov_b32_dpp v126, v100 row_ror:1 row_mask:0xf bank_mask:0xf
	v_mov_b32_dpp v127, v101 row_ror:1 row_mask:0xf bank_mask:0xf
	v_pk_fma_f32 v[104:105], v[134:135], v[114:115], v[104:105]
	v_cndmask_b32_e64 v109, v182, v192, s[14:15]
	v_cndmask_b32_e64 v108, v178, v189, s[14:15]
	v_pk_mul_f32 v[102:103], v[106:107], v[102:103]
	v_cndmask_b32_e64 v107, v127, v222, s[10:11]
	v_cndmask_b32_e64 v106, v126, v218, s[10:11]
	v_pk_fma_f32 v[104:105], v[138:139], v[108:109], v[104:105]
	v_mov_b32_dpp v108, v112 row_ror:15 row_mask:0xf bank_mask:0xf
	v_mov_b32_dpp v109, v113 row_ror:15 row_mask:0xf bank_mask:0xf
	v_pk_fma_f32 v[106:107], v[144:145], v[106:107], v[160:161]
	v_mov_b32_dpp v116, v176 row_ror:1 row_mask:0xf bank_mask:0xf
	v_pk_fma_f32 v[100:101], v[152:153], v[100:101], v[106:107]
	v_cndmask_b32_e64 v107, v223, v109, s[14:15]
	v_cndmask_b32_e64 v106, v128, v108, s[14:15]
	v_pk_fma_f32 v[100:101], v[156:157], v[106:107], v[100:101]
	v_mov_b32_dpp v117, v177 row_ror:1 row_mask:0xf bank_mask:0xf
	v_mul_f32_e32 v106, 0xbdd2d3e7, v101
	v_fmaak_f32 v106, v101, v106, 0xc0135761
	v_mul_f32_e32 v106, v101, v106
	v_exp_f32_e32 v114, v106
	v_cndmask_b32_e64 v185, v117, v185, s[10:11]
; DI unsigned pack_bf16(float lo, float hi) { f32v2 f = {lo, hi}; bf16v2 b = __builtin_convertvector(f, bf16v2); return __builtin_bit_cast(unsigned, b); }
; DI float fexp2(float x) { return __builtin_amdgcn_exp2f(x); }
; DI float rotr1(float v) { return __int_as_float(__builtin_amdgcn_mov_dpp(__float_as_int(v), 0x121, 0xf, 0xf, false)); }
; DI float rotl1(float v) { return __int_as_float(__builtin_amdgcn_mov_dpp(__float_as_int(v), 0x12f, 0xf, 0xf, false)); }
; DI float gelu_tanh(float x) { const float t = x * (1.5957691216057308f + 0.0713548162726009f * x * x); return x * __builtin_amdgcn_rcpf(1.0f + fexp2(-LOG2E * t)); }
;     DI void operator()(const f32x4 (&acc)[2][2][4][2], const pg8::Unit& u, int wr, int wc, int fr, int fq, int ui) const {
;     ...
;                 for (int m = 0; m < 4; ++m) {
;                     float o[4];
; #pragma unroll
;                     for (int e = 0; e < 4; ++e) {
;                         const float pu_s = rotr1(U[m][e]), pg_s = rotr1(G[m][e]), nu_s = rotl1(U[m][e]), ng_s = rotl1(G[m][e]);
;                         const float pu_x = rotr1(U[m > 0 ? m - 1 : 0][e]), pg_x = rotr1(G[m > 0 ? m - 1 : 0][e]);
;                         const float nu_x = rotl1(U[m < 3 ? m + 1 : 3][e]), ng_x = rotl1(G[m < 3 ? m + 1 : 3][e]);
;                         const float pu = fr == 0 ? pu_x : pu_s, pg = fr == 0 ? pg_x : pg_s, nu = fr == 15 ? nu_x : nu_s, ng = fr == 15 ? ng_x : ng_s;
;                         const float yu = bu[e] + pu * wu[0][e] + U[m][e] * wu[1][e] + nu * wu[2][e];
;                         const float yg = bg[e] + pg * wg[0][e] + G[m][e] * wg[1][e] + ng * wg[2][e];
;                         o[e] = yu * gelu_tanh(yg);
;                     }
;                     const bool edge_row = (m == 0 && fr == 0) || (m == 3 && fr == 15);
;                     if (!edge_row) { u32x2 w; w.x = pack_bf16(o[0], o[1]); w.y = pack_bf16(o[2], o[3]); *(u32x2*)(O + (size_t)(rowb + m * 16 + fr) * FF + f0) = w; }
	v_cndmask_b32_e64 v184, v116, v184, s[10:11]
	v_pk_mul_f32 v[102:103], v[104:105], v[102:103]
	v_add_f32_e32 v114, 1.0, v114
	v_rcp_f32_e32 v179, v114
	v_mul_f32_e32 v114, 0xbdd2d3e7, v100
	v_fmaak_f32 v114, v100, v114, 0xc0135761
	v_mul_f32_e32 v114, v100, v114
	v_exp_f32_e32 v114, v114
	v_mov_b32_dpp v104, v110 row_ror:15 row_mask:0xf bank_mask:0xf
	v_mov_b32_dpp v105, v111 row_ror:15 row_mask:0xf bank_mask:0xf
	v_pk_fma_f32 v[184:185], v[142:143], v[184:185], v[158:159]
	v_add_f32_e32 v114, 1.0, v114
	v_pk_fma_f32 v[176:177], v[150:151], v[176:177], v[184:185]
	v_cndmask_b32_e64 v185, v193, v105, s[14:15]
	v_cndmask_b32_e64 v184, v190, v104, s[14:15]
	v_pk_fma_f32 v[176:177], v[154:155], v[184:185], v[176:177]
	v_rcp_f32_e32 v178, v114
	v_mul_f32_e32 v114, 0xbdd2d3e7, v177
	v_fmaak_f32 v114, v177, v114, 0xc0135761
	v_mul_f32_e32 v114, v177, v114
	v_mov_b32_dpp v125, v172 row_ror:1 row_mask:0xf bank_mask:0xf
	v_mov_b32_dpp v128, v173 row_ror:1 row_mask:0xf bank_mask:0xf
	v_exp_f32_e32 v114, v114
	v_cndmask_b32_e64 v183, v128, v221, s[10:11]
	v_cndmask_b32_e64 v182, v125, v207, s[10:11]
	v_mov_b32_dpp v106, v120 row_ror:15 row_mask:0xf bank_mask:0xf
	v_mov_b32_dpp v107, v121 row_ror:15 row_mask:0xf bank_mask:0xf
	v_pk_fma_f32 v[182:183], v[132:133], v[182:183], v[148:149]
	v_pk_mul_f32 v[100:101], v[100:101], v[178:179]
	v_pk_fma_f32 v[172:173], v[136:137], v[172:173], v[182:183]
	v_cndmask_b32_e64 v183, v129, v107, s[14:15]
	v_cndmask_b32_e64 v182, v220, v106, s[14:15]
	v_pk_fma_f32 v[172:173], v[140:141], v[182:183], v[172:173]
	v_add_f32_e32 v114, 1.0, v114
	v_pk_mul_f32 v[100:101], v[172:173], v[100:101]
	v_rcp_f32_e32 v173, v114
	v_mul_f32_e32 v114, 0xbdd2d3e7, v176
	v_fmaak_f32 v114, v176, v114, 0xc0135761
	v_mul_f32_e32 v114, v176, v114
	v_exp_f32_e32 v114, v114
	v_cvt_pk_bf16_f32 v102, v102, v103
	v_cvt_pk_bf16_f32 v103, v98, v99
	v_or_b32_e32 v98, 16, v180
	v_mov_b64_e32 v[170:171], s[24:25]
	v_add_f32_e32 v114, 1.0, v114
	v_mad_i64_i32 v[98:99], s[58:59], v98, s57, v[170:171]
	v_mov_b32_dpp v115, v174 row_ror:1 row_mask:0xf bank_mask:0xf
	v_mov_b32_dpp v124, v175 row_ror:1 row_mask:0xf bank_mask:0xf
	v_rcp_f32_e32 v172, v114
	v_lshl_add_u64 v[98:99], v[98:99], 0, v[168:169]
	v_cndmask_b32_e64 v179, v124, v191, s[10:11]
	v_cndmask_b32_e64 v178, v115, v181, s[10:11]
	global_store_dwordx2 v[98:99], v[102:103], off
	v_mov_b32_dpp v102, v118 row_ror:15 row_mask:0xf bank_mask:0xf
	v_mov_b32_dpp v103, v119 row_ror:15 row_mask:0xf bank_mask:0xf
	v_pk_fma_f32 v[178:179], v[130:131], v[178:179], v[146:147]
	v_pk_mul_f32 v[172:173], v[176:177], v[172:173]
	v_pk_fma_f32 v[174:175], v[134:135], v[174:175], v[178:179]
	v_cndmask_b32_e64 v179, v192, v103, s[14:15]
	v_cndmask_b32_e64 v178, v189, v102, s[14:15]
	v_pk_fma_f32 v[174:175], v[138:139], v[178:179], v[174:175]
	v_mov_b32_dpp v129, v118 row_ror:1 row_mask:0xf bank_mask:0xf
	v_pk_mul_f32 v[172:173], v[174:175], v[172:173]
	v_mov_b32_dpp v174, v121 row_ror:1 row_mask:0xf bank_mask:0xf
	v_cvt_pk_bf16_f32 v172, v172, v173
	v_cvt_pk_bf16_f32 v173, v100, v101
	v_or_b32_e32 v100, 32, v180
	v_mad_i64_i32 v[100:101], s[58:59], v100, s57, v[170:171]
	v_lshl_add_u64 v[100:101], v[100:101], 0, v[168:169]
	global_store_dwordx2 v[100:101], v[172:173], off
	v_mov_b32_dpp v168, v110 row_ror:1 row_mask:0xf bank_mask:0xf
	v_mov_b32_dpp v170, v119 row_ror:1 row_mask:0xf bank_mask:0xf
	v_mov_b32_dpp v169, v111 row_ror:1 row_mask:0xf bank_mask:0xf
	v_mov_b32_dpp v171, v120 row_ror:1 row_mask:0xf bank_mask:0xf
	v_mov_b32_dpp v172, v112 row_ror:1 row_mask:0xf bank_mask:0xf
	v_mov_b32_dpp v173, v113 row_ror:1 row_mask:0xf bank_mask:0xf
	v_or_b32_e32 v114, 48, v180
	s_and_saveexec_b64 s[58:59], s[12:13]
	s_cbranch_execz .LBB0_1160
	v_cndmask_b32_e64 v127, v173, v127, s[10:11]
	v_cndmask_b32_e64 v126, v172, v126, s[10:11]
	v_pk_fma_f32 v[126:127], v[144:145], v[126:127], v[160:161]
	v_cndmask_b32_e64 v175, v174, v128, s[10:11]
	v_pk_fma_f32 v[112:113], v[152:153], v[112:113], v[126:127]
	v_cndmask_b32_e64 v174, v171, v125, s[10:11]
	v_pk_fma_f32 v[108:109], v[156:157], v[108:109], v[112:113]
	s_nop 0
	v_mul_f32_e32 v112, 0xbdd2d3e7, v109
	v_fmaak_f32 v112, v109, v112, 0xc0135761
	v_mul_f32_e32 v113, 0xbdd2d3e7, v108
	v_mul_f32_e32 v112, v109, v112
	v_fmaak_f32 v113, v108, v113, 0xc0135761
	v_mul_f32_e32 v113, v108, v113
	v_exp_f32_e32 v112, v112
	v_exp_f32_e32 v126, v113
	v_add_f32_e32 v112, 1.0, v112
	v_rcp_f32_e32 v113, v112
	v_add_f32_e32 v112, 1.0, v126
	v_rcp_f32_e32 v112, v112
	v_pk_fma_f32 v[126:127], v[132:133], v[174:175], v[148:149]
	v_pk_mul_f32 v[108:109], v[108:109], v[112:113]
	v_cndmask_b32_e64 v113, v169, v117, s[10:11]
	v_cndmask_b32_e64 v112, v168, v116, s[10:11]
	v_pk_fma_f32 v[112:113], v[142:143], v[112:113], v[158:159]
	v_pk_fma_f32 v[120:121], v[136:137], v[120:121], v[126:127]
	v_pk_fma_f32 v[110:111], v[150:151], v[110:111], v[112:113]
	v_pk_fma_f32 v[106:107], v[140:141], v[106:107], v[120:121]
	v_pk_fma_f32 v[104:105], v[154:155], v[104:105], v[110:111]
	v_pk_mul_f32 v[106:107], v[106:107], v[108:109]
	v_mul_f32_e32 v108, 0xbdd2d3e7, v105
	v_fmaak_f32 v108, v105, v108, 0xc0135761
	v_mul_f32_e32 v108, v105, v108
	v_exp_f32_e32 v110, v108
	v_mul_f32_e32 v108, 0xbdd2d3e7, v104
	v_fmaak_f32 v108, v104, v108, 0xc0135761
	v_mul_f32_e32 v108, v104, v108
	v_exp_f32_e32 v112, v108
	v_add_f32_e32 v110, 1.0, v110
	v_rcp_f32_e32 v111, v110
	v_cndmask_b32_e64 v109, v170, v124, s[10:11]
	v_add_f32_e32 v110, 1.0, v112
	v_rcp_f32_e32 v110, v110
	v_cndmask_b32_e64 v108, v129, v115, s[10:11]
	v_pk_fma_f32 v[108:109], v[130:131], v[108:109], v[146:147]
	v_pk_mul_f32 v[104:105], v[104:105], v[110:111]
	v_pk_fma_f32 v[108:109], v[134:135], v[118:119], v[108:109]
	s_nop 0
	v_pk_fma_f32 v[102:103], v[138:139], v[102:103], v[108:109]
	s_nop 0
	v_pk_mul_f32 v[102:103], v[102:103], v[104:105]
	v_mov_b64_e32 v[104:105], s[24:25]
	v_mad_i64_i32 v[104:105], s[70:71], v114, s57, v[104:105]
	v_cvt_pk_bf16_f32 v102, v102, v103
	v_cvt_pk_bf16_f32 v103, v106, v107
	v_lshl_add_u64 v[104:105], v[214:215], 1, v[104:105]
	global_store_dwordx2 v[104:105], v[102:103], off

; DI unsigned pack_bf16(float lo, float hi) { f32v2 f = {lo, hi}; bf16v2 b = __builtin_convertvector(f, bf16v2); return __builtin_bit_cast(unsigned, b); }
; DI float fexp2(float x) { return __builtin_amdgcn_exp2f(x); }
; DI float rotr1(float v) { return __int_as_float(__builtin_amdgcn_mov_dpp(__float_as_int(v), 0x121, 0xf, 0xf, false)); }
; DI float rotl1(float v) { return __int_as_float(__builtin_amdgcn_mov_dpp(__float_as_int(v), 0x12f, 0xf, 0xf, false)); }
; DI float gelu_tanh(float x) { const float t = x * (1.5957691216057308f + 0.0713548162726009f * x * x); return x * __builtin_amdgcn_rcpf(1.0f + fexp2(-LOG2E * t)); }
;     DI void operator()(const f32x4 (&acc)[2][2][4][2], const pg8::Unit& u, int wr, int wc, int fr, int fq, int ui) const {
;     ...
;                 for (int m = 0; m < 4; ++m) { const float s_ = tab[ai * 128 + m * 16]; U[m] = acc[ai][0][m][n] * s_; G[m] = acc[ai][1][m][n] * s_; }
;     ...
;                 for (int m = 0; m < 4; ++m) {
;                     float o[4];
; #pragma unroll
;                     for (int e = 0; e < 4; ++e) {
;                         const float pu_s = rotr1(U[m][e]), pg_s = rotr1(G[m][e]), nu_s = rotl1(U[m][e]), ng_s = rotl1(G[m][e]);
;                         const float pu_x = rotr1(U[m > 0 ? m - 1 : 0][e]), pg_x = rotr1(G[m > 0 ? m - 1 : 0][e]);
;                         const float nu_x = rotl1(U[m < 3 ? m + 1 : 3][e]), ng_x = rotl1(G[m < 3 ? m + 1 : 3][e]);
;                         const float pu = fr == 0 ? pu_x : pu_s, pg = fr == 0 ? pg_x : pg_s, nu = fr == 15 ? nu_x : nu_s, ng = fr == 15 ? ng_x : ng_s;
;                         const float yu = bu[e] + pu * wu[0][e] + U[m][e] * wu[1][e] + nu * wu[2][e];
;                         const float yg = bg[e] + pg * wg[0][e] + G[m][e] * wg[1][e] + ng * wg[2][e];
;                         o[e] = yu * gelu_tanh(yg);
;                     }
;                     const bool edge_row = (m == 0 && fr == 0) || (m == 3 && fr == 15);
;                     if (!edge_row) { u32x2 w; w.x = pack_bf16(o[0], o[1]); w.y = pack_bf16(o[2], o[3]); *(u32x2*)(O + (size_t)(rowb + m * 16 + fr) * FF + f0) = w; }
.LBB0_1164:
	s_or_b64 exec, exec, s[58:59]
	v_mov_b32_e32 v216, v217
	v_mov_b32_e32 v102, v217
	v_mov_b32_e32 v103, v217
	v_pk_mul_f32 v[84:85], v[84:85], v[102:103]
	v_pk_mul_f32 v[82:83], v[82:83], v[216:217]
	v_pk_mul_f32 v[76:77], v[76:77], v[102:103]
	v_pk_mul_f32 v[74:75], v[74:75], v[216:217]
	v_mov_b32_dpp v102, v94 row_ror:1 row_mask:0xf bank_mask:0xf
	v_mov_b32_dpp v104, v90 row_ror:1 row_mask:0xf bank_mask:0xf
	v_mov_b32_dpp v115, v94 row_ror:15 row_mask:0xf bank_mask:0xf
	v_mov_b32_dpp v112, v90 row_ror:15 row_mask:0xf bank_mask:0xf
	v_mov_b32_dpp v116, v82 row_ror:15 row_mask:0xf bank_mask:0xf
	v_mov_b32_dpp v113, v74 row_ror:15 row_mask:0xf bank_mask:0xf
	v_mov_b32_dpp v103, v95 row_ror:1 row_mask:0xf bank_mask:0xf
	v_mov_b32_dpp v105, v91 row_ror:1 row_mask:0xf bank_mask:0xf
	v_mov_b32_dpp v110, v95 row_ror:15 row_mask:0xf bank_mask:0xf
	v_mov_b32_dpp v117, v91 row_ror:15 row_mask:0xf bank_mask:0xf
	v_mov_b32_dpp v111, v83 row_ror:15 row_mask:0xf bank_mask:0xf
	v_mov_b32_dpp v118, v75 row_ror:15 row_mask:0xf bank_mask:0xf
	v_mov_b32_dpp v106, v96 row_ror:1 row_mask:0xf bank_mask:0xf
	v_mov_b32_dpp v108, v92 row_ror:1 row_mask:0xf bank_mask:0xf
	v_mov_b32_dpp v126, v96 row_ror:15 row_mask:0xf bank_mask:0xf
	v_mov_b32_dpp v121, v92 row_ror:15 row_mask:0xf bank_mask:0xf
	v_mov_b32_dpp v128, v84 row_ror:15 row_mask:0xf bank_mask:0xf
	v_mov_b32_dpp v124, v76 row_ror:15 row_mask:0xf bank_mask:0xf
	v_mov_b32_dpp v107, v97 row_ror:1 row_mask:0xf bank_mask:0xf
	v_mov_b32_dpp v109, v93 row_ror:1 row_mask:0xf bank_mask:0xf
	v_mov_b32_dpp v119, v97 row_ror:15 row_mask:0xf bank_mask:0xf
	v_mov_b32_dpp v125, v93 row_ror:15 row_mask:0xf bank_mask:0xf
	v_mov_b32_dpp v120, v85 row_ror:15 row_mask:0xf bank_mask:0xf
	v_mov_b32_dpp v127, v77 row_ror:15 row_mask:0xf bank_mask:0xf
	s_and_saveexec_b64 s[58:59], s[8:9]
	s_xor_b64 s[58:59], exec, s[58:59]
	s_cbranch_execz .LBB0_1166
	v_pk_fma_f32 v[108:109], v[48:49], v[108:109], v[64:65]
	v_cndmask_b32_e64 v124, v121, v124, s[14:15]
	v_cndmask_b32_e64 v125, v125, v127, s[14:15]
	v_pk_fma_f32 v[108:109], v[56:57], v[92:93], v[108:109]
	v_cndmask_b32_e64 v127, v119, v120, s[14:15]
	v_pk_fma_f32 v[108:109], v[60:61], v[124:125], v[108:109]
	v_pk_fma_f32 v[106:107], v[36:37], v[106:107], v[52:53]
	v_mul_f32_e32 v121, 0xbdd2d3e7, v109
	v_fmaak_f32 v121, v109, v121, 0xc0135761
	v_mul_f32_e32 v124, 0xbdd2d3e7, v108
	v_mul_f32_e32 v121, v109, v121
	v_fmaak_f32 v124, v108, v124, 0xc0135761
	v_mul_f32_e32 v124, v108, v124
	v_exp_f32_e32 v121, v121
	v_exp_f32_e32 v124, v124
	v_pk_fma_f32 v[104:105], v[46:47], v[104:105], v[62:63]
	v_add_f32_e32 v119, 1.0, v121
	v_rcp_f32_e32 v121, v119
	v_add_f32_e32 v119, 1.0, v124
	v_rcp_f32_e32 v120, v119
	v_cndmask_b32_e64 v126, v126, v128, s[14:15]
	v_pk_fma_f32 v[106:107], v[40:41], v[96:97], v[106:107]
	v_cndmask_b32_e64 v112, v112, v113, s[14:15]
	v_cndmask_b32_e64 v113, v117, v118, s[14:15]
	v_pk_fma_f32 v[104:105], v[54:55], v[90:91], v[104:105]
	v_pk_fma_f32 v[106:107], v[44:45], v[126:127], v[106:107]
	v_pk_mul_f32 v[108:109], v[108:109], v[120:121]
	v_pk_fma_f32 v[104:105], v[58:59], v[112:113], v[104:105]
	v_pk_mul_f32 v[106:107], v[106:107], v[108:109]
	v_mul_f32_e32 v109, 0xbdd2d3e7, v105
	v_fmaak_f32 v109, v105, v109, 0xc0135761
	v_mul_f32_e32 v109, v105, v109
	v_exp_f32_e32 v112, v109
	v_mul_f32_e32 v109, 0xbdd2d3e7, v104
	v_fmaak_f32 v109, v104, v109, 0xc0135761
	v_mul_f32_e32 v109, v104, v109
	v_exp_f32_e32 v113, v109
	v_cndmask_b32_e64 v109, v110, v111, s[14:15]
	v_add_f32_e32 v110, 1.0, v112
	v_rcp_f32_e32 v111, v110
	v_add_f32_e32 v110, 1.0, v113
	v_rcp_f32_e32 v110, v110
	v_pk_fma_f32 v[102:103], v[34:35], v[102:103], v[50:51]
	v_cndmask_b32_e64 v108, v115, v116, s[14:15]
	v_pk_fma_f32 v[102:103], v[38:39], v[94:95], v[102:103]
	v_pk_mul_f32 v[104:105], v[104:105], v[110:111]
	v_pk_fma_f32 v[102:103], v[42:43], v[108:109], v[102:103]
	s_nop 0
	v_pk_mul_f32 v[102:103], v[102:103], v[104:105]
	v_mov_b64_e32 v[104:105], s[24:25]
	v_mad_i64_i32 v[104:105], s[70:71], v239, s57, v[104:105]
	v_cvt_pk_bf16_f32 v102, v102, v103
	v_cvt_pk_bf16_f32 v103, v106, v107
	v_lshl_add_u64 v[104:105], v[214:215], 1, v[104:105]
	global_store_dwordx2 v[104:105], v[102:103], off offset:8
; DI unsigned pack_bf16(float lo, float hi) { f32v2 f = {lo, hi}; bf16v2 b = __builtin_convertvector(f, bf16v2); return __builtin_bit_cast(unsigned, b); }
; DI float fexp2(float x) { return __builtin_amdgcn_exp2f(x); }
; DI float rotr1(float v) { return __int_as_float(__builtin_amdgcn_mov_dpp(__float_as_int(v), 0x121, 0xf, 0xf, false)); }
; DI float rotl1(float v) { return __int_as_float(__builtin_amdgcn_mov_dpp(__float_as_int(v), 0x12f, 0xf, 0xf, false)); }
; DI float gelu_tanh(float x) { const float t = x * (1.5957691216057308f + 0.0713548162726009f * x * x); return x * __builtin_amdgcn_rcpf(1.0f + fexp2(-LOG2E * t)); }
;     DI void operator()(const f32x4 (&acc)[2][2][4][2], const pg8::Unit& u, int wr, int wc, int fr, int fq, int ui) const {
;     ...
;                 for (int m = 0; m < 4; ++m) { const float s_ = tab[ai * 128 + m * 16]; U[m] = acc[ai][0][m][n] * s_; G[m] = acc[ai][1][m][n] * s_; }
;     ...
;                 for (int m = 0; m < 4; ++m) {
;                     float o[4];
; #pragma unroll
;                     for (int e = 0; e < 4; ++e) {
;                         const float pu_s = rotr1(U[m][e]), pg_s = rotr1(G[m][e]), nu_s = rotl1(U[m][e]), ng_s = rotl1(G[m][e]);
;                         const float pu_x = rotr1(U[m > 0 ? m - 1 : 0][e]), pg_x = rotr1(G[m > 0 ? m - 1 : 0][e]);
;                         const float nu_x = rotl1(U[m < 3 ? m + 1 : 3][e]), ng_x = rotl1(G[m < 3 ? m + 1 : 3][e]);
;                         const float pu = fr == 0 ? pu_x : pu_s, pg = fr == 0 ? pg_x : pg_s, nu = fr == 15 ? nu_x : nu_s, ng = fr == 15 ? ng_x : ng_s;
;                         const float yu = bu[e] + pu * wu[0][e] + U[m][e] * wu[1][e] + nu * wu[2][e];
;                         const float yg = bg[e] + pg * wg[0][e] + G[m][e] * wg[1][e] + ng * wg[2][e];
;                         o[e] = yu * gelu_tanh(yg);
;                     }
;                     const bool edge_row = (m == 0 && fr == 0) || (m == 3 && fr == 15);
;                     if (!edge_row) { u32x2 w; w.x = pack_bf16(o[0], o[1]); w.y = pack_bf16(o[2], o[3]); *(u32x2*)(O + (size_t)(rowb + m * 16 + fr) * FF + f0) = w; }
.LBB0_1166:
	s_andn2_saveexec_b64 s[58:59], s[58:59]
	s_or_b64 exec, exec, s[58:59]
	v_mov_b32_e32 v187, v186
	v_mov_b32_e32 v102, v186
	v_mov_b32_e32 v103, v186
	v_pk_mul_f32 v[104:105], v[72:73], v[102:103]
	v_pk_mul_f32 v[72:73], v[68:69], v[102:103]
	v_pk_mul_f32 v[102:103], v[66:67], v[186:187]
	v_mov_b32_dpp v120, v76 row_ror:1 row_mask:0xf bank_mask:0xf
	v_mov_b32_dpp v66, v92 row_ror:1 row_mask:0xf bank_mask:0xf
	v_mov_b32_dpp v92, v77 row_ror:1 row_mask:0xf bank_mask:0xf
	v_mov_b32_dpp v67, v93 row_ror:1 row_mask:0xf bank_mask:0xf
	v_cndmask_b32_e64 v67, v92, v67, s[10:11]
	v_cndmask_b32_e64 v66, v120, v66, s[10:11]
	v_mov_b32_dpp v68, v76 row_ror:15 row_mask:0xf bank_mask:0xf
	v_mov_b32_dpp v125, v72 row_ror:15 row_mask:0xf bank_mask:0xf
	v_mov_b32_dpp v69, v77 row_ror:15 row_mask:0xf bank_mask:0xf
	v_mov_b32_dpp v127, v73 row_ror:15 row_mask:0xf bank_mask:0xf
	v_pk_fma_f32 v[66:67], v[48:49], v[66:67], v[64:65]
	v_cndmask_b32_e64 v69, v69, v127, s[14:15]
	v_pk_fma_f32 v[66:67], v[56:57], v[76:77], v[66:67]
	v_cndmask_b32_e64 v68, v68, v125, s[14:15]
	v_pk_fma_f32 v[66:67], v[60:61], v[68:69], v[66:67]
	v_mov_b32_dpp v106, v74 row_ror:1 row_mask:0xf bank_mask:0xf
	v_mul_f32_e32 v68, 0xbdd2d3e7, v67
	v_fmaak_f32 v68, v67, v68, 0xc0135761
	v_mul_f32_e32 v68, v67, v68
	v_exp_f32_e32 v68, v68
	v_mov_b32_dpp v90, v90 row_ror:1 row_mask:0xf bank_mask:0xf
	v_mov_b32_dpp v113, v75 row_ror:1 row_mask:0xf bank_mask:0xf
	v_mov_b32_dpp v91, v91 row_ror:1 row_mask:0xf bank_mask:0xf
	v_add_f32_e32 v68, 1.0, v68
	v_rcp_f32_e32 v69, v68
	v_mul_f32_e32 v68, 0xbdd2d3e7, v66
	v_fmaak_f32 v68, v66, v68, 0xc0135761
	v_cndmask_b32_e64 v91, v113, v91, s[10:11]
	v_cndmask_b32_e64 v90, v106, v90, s[10:11]
	v_mov_b32_dpp v109, v74 row_ror:15 row_mask:0xf bank_mask:0xf
	v_mov_b32_dpp v111, v102 row_ror:15 row_mask:0xf bank_mask:0xf
	v_mov_b32_dpp v116, v75 row_ror:15 row_mask:0xf bank_mask:0xf
	v_mov_b32_dpp v118, v103 row_ror:15 row_mask:0xf bank_mask:0xf
	v_mul_f32_e32 v68, v66, v68
	v_pk_fma_f32 v[90:91], v[46:47], v[90:91], v[62:63]
	v_pk_fma_f32 v[74:75], v[54:55], v[74:75], v[90:91]
	v_cndmask_b32_e64 v91, v116, v118, s[14:15]
	v_cndmask_b32_e64 v90, v109, v111, s[14:15]
	v_exp_f32_e32 v68, v68
	v_pk_fma_f32 v[74:75], v[58:59], v[90:91], v[74:75]
	v_mov_b32_dpp v119, v84 row_ror:1 row_mask:0xf bank_mask:0xf
	v_mul_f32_e32 v90, 0xbdd2d3e7, v75
	v_fmaak_f32 v90, v75, v90, 0xc0135761
	v_mul_f32_e32 v90, v75, v90
	v_add_f32_e32 v68, 1.0, v68
	v_rcp_f32_e32 v68, v68
	v_exp_f32_e32 v90, v90
	v_mov_b32_dpp v96, v96 row_ror:1 row_mask:0xf bank_mask:0xf
	v_mov_b32_dpp v126, v85 row_ror:1 row_mask:0xf bank_mask:0xf
	v_pk_mul_f32 v[66:67], v[66:67], v[68:69]
	v_add_f32_e32 v68, 1.0, v90
	v_rcp_f32_e32 v69, v68
	v_mul_f32_e32 v68, 0xbdd2d3e7, v74
	v_fmaak_f32 v68, v74, v68, 0xc0135761
	v_mul_f32_e32 v68, v74, v68
	v_exp_f32_e32 v68, v68
	v_mov_b32_dpp v76, v97 row_ror:1 row_mask:0xf bank_mask:0xf
	v_cndmask_b32_e64 v77, v126, v76, s[10:11]
	v_cndmask_b32_e64 v76, v119, v96, s[10:11]
	v_add_f32_e32 v68, 1.0, v68
	v_mov_b32_dpp v121, v84 row_ror:15 row_mask:0xf bank_mask:0xf
	v_mov_b32_dpp v124, v104 row_ror:15 row_mask:0xf bank_mask:0xf
	v_mov_b32_dpp v93, v85 row_ror:15 row_mask:0xf bank_mask:0xf
	v_mov_b32_dpp v128, v105 row_ror:15 row_mask:0xf bank_mask:0xf
	v_pk_fma_f32 v[76:77], v[36:37], v[76:77], v[52:53]
	v_rcp_f32_e32 v68, v68
	v_pk_fma_f32 v[76:77], v[40:41], v[84:85], v[76:77]
	v_cndmask_b32_e64 v85, v93, v128, s[14:15]
	v_cndmask_b32_e64 v84, v121, v124, s[14:15]
	v_pk_fma_f32 v[76:77], v[44:45], v[84:85], v[76:77]
	v_mov_b32_dpp v85, v72 row_ror:1 row_mask:0xf bank_mask:0xf
	v_mov_b32_dpp v90, v73 row_ror:1 row_mask:0xf bank_mask:0xf
	v_cndmask_b32_e64 v93, v90, v92, s[10:11]
	v_cndmask_b32_e64 v92, v85, v120, s[10:11]
	v_pk_mul_f32 v[68:69], v[74:75], v[68:69]
	v_mov_b32_dpp v74, v80 row_ror:15 row_mask:0xf bank_mask:0xf
	v_mov_b32_dpp v75, v81 row_ror:15 row_mask:0xf bank_mask:0xf
	v_pk_fma_f32 v[92:93], v[48:49], v[92:93], v[64:65]
	v_mov_b32_dpp v108, v82 row_ror:1 row_mask:0xf bank_mask:0xf
	v_pk_fma_f32 v[72:73], v[56:57], v[72:73], v[92:93]
	v_cndmask_b32_e64 v93, v127, v75, s[14:15]
	v_cndmask_b32_e64 v92, v125, v74, s[14:15]
	v_pk_fma_f32 v[92:93], v[60:61], v[92:93], v[72:73]
	v_mov_b32_dpp v94, v94 row_ror:1 row_mask:0xf bank_mask:0xf
	v_mul_f32_e32 v72, 0xbdd2d3e7, v93
	v_fmaak_f32 v72, v93, v72, 0xc0135761
	v_mul_f32_e32 v72, v93, v72
	v_mov_b32_dpp v112, v83 row_ror:1 row_mask:0xf bank_mask:0xf
	v_mov_b32_dpp v95, v95 row_ror:1 row_mask:0xf bank_mask:0xf
	v_pk_mul_f32 v[66:67], v[76:77], v[66:67]
	v_cndmask_b32_e64 v76, v108, v94, s[10:11]
	v_exp_f32_e32 v94, v72
	v_pk_mul_f32 v[70:71], v[70:71], v[186:187]
	v_cndmask_b32_e64 v77, v112, v95, s[10:11]
	v_mov_b32_dpp v107, v82 row_ror:15 row_mask:0xf bank_mask:0xf
	v_mov_b32_dpp v110, v70 row_ror:15 row_mask:0xf bank_mask:0xf
	v_mov_b32_dpp v115, v83 row_ror:15 row_mask:0xf bank_mask:0xf
	v_mov_b32_dpp v117, v71 row_ror:15 row_mask:0xf bank_mask:0xf
	v_pk_fma_f32 v[76:77], v[34:35], v[76:77], v[50:51]
	v_add_f32_e32 v94, 1.0, v94
	v_pk_fma_f32 v[76:77], v[38:39], v[82:83], v[76:77]
	v_cndmask_b32_e64 v83, v115, v117, s[14:15]
	v_cndmask_b32_e64 v82, v107, v110, s[14:15]
	v_pk_fma_f32 v[76:77], v[42:43], v[82:83], v[76:77]
	v_rcp_f32_e32 v95, v94
	v_pk_mul_f32 v[68:69], v[76:77], v[68:69]
	v_mov_b32_dpp v77, v102 row_ror:1 row_mask:0xf bank_mask:0xf
; DI unsigned pack_bf16(float lo, float hi) { f32v2 f = {lo, hi}; bf16v2 b = __builtin_convertvector(f, bf16v2); return __builtin_bit_cast(unsigned, b); }
; DI float fexp2(float x) { return __builtin_amdgcn_exp2f(x); }
; DI float rotr1(float v) { return __int_as_float(__builtin_amdgcn_mov_dpp(__float_as_int(v), 0x121, 0xf, 0xf, false)); }
; DI float rotl1(float v) { return __int_as_float(__builtin_amdgcn_mov_dpp(__float_as_int(v), 0x12f, 0xf, 0xf, false)); }
; DI float gelu_tanh(float x) { const float t = x * (1.5957691216057308f + 0.0713548162726009f * x * x); return x * __builtin_amdgcn_rcpf(1.0f + fexp2(-LOG2E * t)); }
;     DI void operator()(const f32x4 (&acc)[2][2][4][2], const pg8::Unit& u, int wr, int wc, int fr, int fq, int ui) const {
;     ...
;                 for (int m = 0; m < 4; ++m) {
;                     float o[4];
; #pragma unroll
;                     for (int e = 0; e < 4; ++e) {
;                         const float pu_s = rotr1(U[m][e]), pg_s = rotr1(G[m][e]), nu_s = rotl1(U[m][e]), ng_s = rotl1(G[m][e]);
;                         const float pu_x = rotr1(U[m > 0 ? m - 1 : 0][e]), pg_x = rotr1(G[m > 0 ? m - 1 : 0][e]);
;                         const float nu_x = rotl1(U[m < 3 ? m + 1 : 3][e]), ng_x = rotl1(G[m < 3 ? m + 1 : 3][e]);
;                         const float pu = fr == 0 ? pu_x : pu_s, pg = fr == 0 ? pg_x : pg_s, nu = fr == 15 ? nu_x : nu_s, ng = fr == 15 ? ng_x : ng_s;
;                         const float yu = bu[e] + pu * wu[0][e] + U[m][e] * wu[1][e] + nu * wu[2][e];
;                         const float yg = bg[e] + pg * wg[0][e] + G[m][e] * wg[1][e] + ng * wg[2][e];
;                         o[e] = yu * gelu_tanh(yg);
;                     }
;                     const bool edge_row = (m == 0 && fr == 0) || (m == 3 && fr == 15);
;                     if (!edge_row) { u32x2 w; w.x = pack_bf16(o[0], o[1]); w.y = pack_bf16(o[2], o[3]); *(u32x2*)(O + (size_t)(rowb + m * 16 + fr) * FF + f0) = w; }
	v_mov_b32_dpp v82, v103 row_ror:1 row_mask:0xf bank_mask:0xf
	v_mul_f32_e32 v94, 0xbdd2d3e7, v92
	v_cvt_pk_bf16_f32 v68, v68, v69
	v_cvt_pk_bf16_f32 v69, v66, v67
	v_fmaak_f32 v94, v92, v94, 0xc0135761
	v_cndmask_b32_e64 v107, v82, v113, s[10:11]
	v_cndmask_b32_e64 v106, v77, v106, s[10:11]
	global_store_dwordx2 v[164:165], v[68:69], off offset:8
	v_mov_b32_dpp v68, v78 row_ror:15 row_mask:0xf bank_mask:0xf
	v_mov_b32_dpp v69, v79 row_ror:15 row_mask:0xf bank_mask:0xf
	v_mul_f32_e32 v94, v92, v94
	v_pk_fma_f32 v[106:107], v[46:47], v[106:107], v[62:63]
	v_pk_fma_f32 v[102:103], v[54:55], v[102:103], v[106:107]
	v_cndmask_b32_e64 v107, v118, v69, s[14:15]
	v_cndmask_b32_e64 v106, v111, v68, s[14:15]
	v_exp_f32_e32 v94, v94
	v_pk_fma_f32 v[102:103], v[58:59], v[106:107], v[102:103]
	v_mov_b32_dpp v84, v104 row_ror:1 row_mask:0xf bank_mask:0xf
	v_mul_f32_e32 v106, 0xbdd2d3e7, v103
	v_fmaak_f32 v106, v103, v106, 0xc0135761
	v_mul_f32_e32 v106, v103, v106
	v_add_f32_e32 v94, 1.0, v94
	v_rcp_f32_e32 v94, v94
	v_exp_f32_e32 v106, v106
	v_mov_b32_dpp v91, v105 row_ror:1 row_mask:0xf bank_mask:0xf
	v_cndmask_b32_e64 v97, v91, v126, s[10:11]
	v_pk_mul_f32 v[92:93], v[92:93], v[94:95]
	v_add_f32_e32 v94, 1.0, v106
	v_rcp_f32_e32 v95, v94
	v_mul_f32_e32 v94, 0xbdd2d3e7, v102
	v_fmaak_f32 v94, v102, v94, 0xc0135761
	v_mul_f32_e32 v94, v102, v94
	v_exp_f32_e32 v94, v94
	v_cndmask_b32_e64 v96, v84, v119, s[10:11]
	v_mov_b32_dpp v72, v88 row_ror:15 row_mask:0xf bank_mask:0xf
	v_mov_b32_dpp v73, v89 row_ror:15 row_mask:0xf bank_mask:0xf
	v_pk_fma_f32 v[96:97], v[36:37], v[96:97], v[52:53]
	v_add_f32_e32 v94, 1.0, v94
	v_pk_fma_f32 v[96:97], v[40:41], v[104:105], v[96:97]
	v_cndmask_b32_e64 v105, v128, v73, s[14:15]
	v_cndmask_b32_e64 v104, v124, v72, s[14:15]
	v_mov_b32_dpp v76, v70 row_ror:1 row_mask:0xf bank_mask:0xf
	v_mov_b32_dpp v83, v71 row_ror:1 row_mask:0xf bank_mask:0xf
	v_pk_fma_f32 v[96:97], v[44:45], v[104:105], v[96:97]
	v_rcp_f32_e32 v94, v94
	v_pk_mul_f32 v[92:93], v[96:97], v[92:93]
	v_cndmask_b32_e64 v97, v83, v112, s[10:11]
	v_cndmask_b32_e64 v96, v76, v108, s[10:11]
	v_mov_b32_dpp v66, v86 row_ror:15 row_mask:0xf bank_mask:0xf
	v_mov_b32_dpp v67, v87 row_ror:15 row_mask:0xf bank_mask:0xf
	v_pk_fma_f32 v[96:97], v[34:35], v[96:97], v[50:51]
	v_pk_mul_f32 v[94:95], v[102:103], v[94:95]
	v_pk_fma_f32 v[70:71], v[38:39], v[70:71], v[96:97]
	v_cndmask_b32_e64 v97, v117, v67, s[14:15]
	v_cndmask_b32_e64 v96, v110, v66, s[14:15]
	v_pk_fma_f32 v[70:71], v[42:43], v[96:97], v[70:71]
	v_mov_b32_dpp v97, v89 row_ror:1 row_mask:0xf bank_mask:0xf
	v_pk_mul_f32 v[70:71], v[70:71], v[94:95]
	v_mov_b32_dpp v94, v88 row_ror:1 row_mask:0xf bank_mask:0xf
	v_cvt_pk_bf16_f32 v70, v70, v71
	v_cvt_pk_bf16_f32 v71, v92, v93
	global_store_dwordx2 v[166:167], v[70:71], off offset:8
	v_mov_b32_dpp v70, v86 row_ror:1 row_mask:0xf bank_mask:0xf
	v_mov_b32_dpp v71, v78 row_ror:1 row_mask:0xf bank_mask:0xf
	v_mov_b32_dpp v93, v87 row_ror:1 row_mask:0xf bank_mask:0xf
	v_mov_b32_dpp v92, v79 row_ror:1 row_mask:0xf bank_mask:0xf
	v_mov_b32_dpp v95, v80 row_ror:1 row_mask:0xf bank_mask:0xf
	v_mov_b32_dpp v96, v81 row_ror:1 row_mask:0xf bank_mask:0xf
	s_and_saveexec_b64 s[58:59], s[12:13]
	s_cbranch_execz .LBB0_1168
	v_cndmask_b32_e64 v91, v97, v91, s[10:11]
	v_cndmask_b32_e64 v97, v96, v90, s[10:11]
	v_cndmask_b32_e64 v96, v95, v85, s[10:11]
	v_pk_fma_f32 v[96:97], v[48:49], v[96:97], v[64:65]
	v_cndmask_b32_e64 v90, v94, v84, s[10:11]
	v_pk_fma_f32 v[80:81], v[56:57], v[80:81], v[96:97]
	s_nop 0
	v_pk_fma_f32 v[74:75], v[60:61], v[74:75], v[80:81]
	s_nop 0
	v_mul_f32_e32 v80, 0xbdd2d3e7, v75
	v_fmaak_f32 v80, v75, v80, 0xc0135761
	v_mul_f32_e32 v81, 0xbdd2d3e7, v74
	v_mul_f32_e32 v80, v75, v80
	v_fmaak_f32 v81, v74, v81, 0xc0135761
	v_mul_f32_e32 v81, v74, v81
	v_exp_f32_e32 v80, v80
	v_exp_f32_e32 v85, v81
	v_add_f32_e32 v80, 1.0, v80
	v_rcp_f32_e32 v81, v80
	v_add_f32_e32 v80, 1.0, v85
	v_rcp_f32_e32 v80, v80
	v_pk_fma_f32 v[84:85], v[36:37], v[90:91], v[52:53]
	v_pk_mul_f32 v[74:75], v[74:75], v[80:81]
	v_cndmask_b32_e64 v81, v92, v82, s[10:11]
	v_cndmask_b32_e64 v80, v71, v77, s[10:11]
	v_pk_fma_f32 v[80:81], v[46:47], v[80:81], v[62:63]
	v_pk_fma_f32 v[84:85], v[40:41], v[88:89], v[84:85]
	v_pk_fma_f32 v[78:79], v[54:55], v[78:79], v[80:81]
	v_pk_fma_f32 v[72:73], v[44:45], v[72:73], v[84:85]
	v_pk_fma_f32 v[68:69], v[58:59], v[68:69], v[78:79]
	v_pk_mul_f32 v[72:73], v[72:73], v[74:75]
	v_mul_f32_e32 v71, 0xbdd2d3e7, v69
	v_fmaak_f32 v71, v69, v71, 0xc0135761
	v_mul_f32_e32 v74, 0xbdd2d3e7, v68
	v_mul_f32_e32 v71, v69, v71
	v_fmaak_f32 v74, v68, v74, 0xc0135761
	v_mul_f32_e32 v74, v68, v74
	v_exp_f32_e32 v71, v71
	v_exp_f32_e32 v77, v74
	v_cndmask_b32_e64 v74, v70, v76, s[10:11]
	v_add_f32_e32 v70, 1.0, v71
	v_rcp_f32_e32 v71, v70
	v_add_f32_e32 v70, 1.0, v77
	v_rcp_f32_e32 v70, v70
	v_cndmask_b32_e64 v75, v93, v83, s[10:11]
	v_pk_fma_f32 v[74:75], v[34:35], v[74:75], v[50:51]
	v_pk_mul_f32 v[68:69], v[68:69], v[70:71]
	v_pk_fma_f32 v[74:75], v[38:39], v[86:87], v[74:75]
	s_nop 0
	v_pk_fma_f32 v[66:67], v[42:43], v[66:67], v[74:75]
	s_nop 0
	v_pk_mul_f32 v[66:67], v[66:67], v[68:69]
	v_mov_b64_e32 v[68:69], s[24:25]
	v_mad_i64_i32 v[68:69], s[70:71], v188, s57, v[68:69]
	v_cvt_pk_bf16_f32 v66, v66, v67
	v_cvt_pk_bf16_f32 v67, v72, v73
	v_lshl_add_u64 v[68:69], v[214:215], 1, v[68:69]
	global_store_dwordx2 v[68:69], v[66:67], off offset:8

; DI float rotr1(float v) { return __int_as_float(__builtin_amdgcn_mov_dpp(__float_as_int(v), 0x121, 0xf, 0xf, false)); }
;     DI void operator()(const f32x4 (&acc)[2][2][4][2], const pg8::Unit& u, int wr, int wc, int fr, int fq, int ui) const {
;     ...
;                 for (int m = 0; m < 4; ++m) { const float s_ = tab[ai * 128 + m * 16]; U[m] = acc[ai][0][m][n] * s_; G[m] = acc[ai][1][m][n] * s_; }
;                 if (fr < 2) { bf16_t* ep = edge + ((size_t)(rowb >> 6) * 4 + fr) * F2 + u.pn * 256 + wc * 32 + 8 * fq + 4 * n;
;                     u32x2 a; a.x = pack_bf16(U[0][0], U[0][1]); a.y = pack_bf16(U[0][2], U[0][3]); *(u32x2*)ep = a;
;                     u32x2 c; c.x = pack_bf16(G[0][0], G[0][1]); c.y = pack_bf16(G[0][2], G[0][3]); *(u32x2*)(ep + 128) = c; }
;                 if (fr >= 14) { bf16_t* ep = edge + ((size_t)(rowb >> 6) * 4 + (fr - 12)) * F2 + u.pn * 256 + wc * 32 + 8 * fq + 4 * n;
;                     u32x2 a; a.x = pack_bf16(U[3][0], U[3][1]); a.y = pack_bf16(U[3][2], U[3][3]); *(u32x2*)ep = a;
;                     u32x2 c; c.x = pack_bf16(G[3][0], G[3][1]); c.y = pack_bf16(G[3][2], G[3][3]); *(u32x2*)(ep + 128) = c; }
; #pragma unroll
;                 for (int m = 0; m < 4; ++m) {
;                     float o[4];
; #pragma unroll
;                     for (int e = 0; e < 4; ++e) {
;                         const float pu_s = rotr1(U[m][e]), pg_s = rotr1(G[m][e]), nu_s = rotl1(U[m][e]), ng_s = rotl1(G[m][e]);
;                         const float pu_x = rotr1(U[m > 0 ? m - 1 : 0][e]), pg_x = rotr1(G[m > 0 ? m - 1 : 0][e]);
;                         const float nu_x = rotl1(U[m < 3 ? m + 1 : 3][e]), ng_x = rotl1(G[m < 3 ? m + 1 : 3][e]);
;                         const float pu = fr == 0 ? pu_x : pu_s, pg = fr == 0 ? pg_x : pg_s, nu = fr == 15 ? nu_x : nu_s, ng = fr == 15 ? ng_x : ng_s;
;                         const float yu = bu[e] + pu * wu[0][e] + U[m][e] * wu[1][e] + nu * wu[2][e];
;                         const float yg = bg[e] + pg * wg[0][e] + G[m][e] * wg[1][e] + ng * wg[2][e];
;                         o[e] = yu * gelu_tanh(yg);
;                     }
;                     const bool edge_row = (m == 0 && fr == 0) || (m == 3 && fr == 15);
;                     if (!edge_row) { u32x2 w; w.x = pack_bf16(o[0], o[1]); w.y = pack_bf16(o[2], o[3]); *(u32x2*)(O + (size_t)(rowb + m * 16 + fr) * FF + f0) = w; }
.LBB0_1172:
	s_or_b64 exec, exec, s[58:59]
	v_mov_b32_e32 v162, v163
	v_mov_b32_e32 v66, v163
	v_mov_b32_e32 v67, v163
	v_pk_mul_f32 v[20:21], v[20:21], v[66:67]
	v_pk_mul_f32 v[18:19], v[18:19], v[162:163]
	v_pk_mul_f32 v[12:13], v[12:13], v[66:67]
	v_pk_mul_f32 v[10:11], v[10:11], v[162:163]
	v_mov_b32_dpp v66, v30 row_ror:1 row_mask:0xf bank_mask:0xf
	v_mov_b32_dpp v68, v26 row_ror:1 row_mask:0xf bank_mask:0xf
	v_mov_b32_dpp v77, v30 row_ror:15 row_mask:0xf bank_mask:0xf
	v_mov_b32_dpp v75, v26 row_ror:15 row_mask:0xf bank_mask:0xf
	v_mov_b32_dpp v78, v18 row_ror:15 row_mask:0xf bank_mask:0xf
	v_mov_b32_dpp v76, v10 row_ror:15 row_mask:0xf bank_mask:0xf
	v_mov_b32_dpp v67, v31 row_ror:1 row_mask:0xf bank_mask:0xf
	v_mov_b32_dpp v69, v27 row_ror:1 row_mask:0xf bank_mask:0xf
	v_mov_b32_dpp v0, v31 row_ror:15 row_mask:0xf bank_mask:0xf
	v_mov_b32_dpp v79, v27 row_ror:15 row_mask:0xf bank_mask:0xf
	v_mov_b32_dpp v74, v19 row_ror:15 row_mask:0xf bank_mask:0xf
	v_mov_b32_dpp v80, v11 row_ror:15 row_mask:0xf bank_mask:0xf
	v_mov_b32_dpp v70, v32 row_ror:1 row_mask:0xf bank_mask:0xf
	v_mov_b32_dpp v72, v28 row_ror:1 row_mask:0xf bank_mask:0xf
	v_mov_b32_dpp v86, v32 row_ror:15 row_mask:0xf bank_mask:0xf
	v_mov_b32_dpp v83, v28 row_ror:15 row_mask:0xf bank_mask:0xf
	v_mov_b32_dpp v88, v20 row_ror:15 row_mask:0xf bank_mask:0xf
	v_mov_b32_dpp v84, v12 row_ror:15 row_mask:0xf bank_mask:0xf
	v_mov_b32_dpp v71, v33 row_ror:1 row_mask:0xf bank_mask:0xf
	v_mov_b32_dpp v73, v29 row_ror:1 row_mask:0xf bank_mask:0xf
	v_mov_b32_dpp v81, v33 row_ror:15 row_mask:0xf bank_mask:0xf
	v_mov_b32_dpp v85, v29 row_ror:15 row_mask:0xf bank_mask:0xf
	v_mov_b32_dpp v82, v21 row_ror:15 row_mask:0xf bank_mask:0xf
	v_mov_b32_dpp v87, v13 row_ror:15 row_mask:0xf bank_mask:0xf
	s_and_saveexec_b64 s[40:41], s[8:9]
	s_cbranch_execz .LBB0_1174
	v_pk_fma_f32 v[72:73], v[48:49], v[72:73], v[64:65]
	v_cndmask_b32_e64 v84, v83, v84, s[14:15]
	v_cndmask_b32_e64 v85, v85, v87, s[14:15]
	v_pk_fma_f32 v[72:73], v[56:57], v[28:29], v[72:73]
	v_cndmask_b32_e64 v87, v81, v82, s[14:15]
	v_pk_fma_f32 v[72:73], v[60:61], v[84:85], v[72:73]
	v_pk_fma_f32 v[70:71], v[36:37], v[70:71], v[52:53]
	v_mul_f32_e32 v83, 0xbdd2d3e7, v73
	v_fmaak_f32 v83, v73, v83, 0xc0135761
	v_mul_f32_e32 v84, 0xbdd2d3e7, v72
	v_mul_f32_e32 v83, v73, v83
	v_fmaak_f32 v84, v72, v84, 0xc0135761
	v_mul_f32_e32 v84, v72, v84
	v_exp_f32_e32 v83, v83
	v_exp_f32_e32 v84, v84
	v_cndmask_b32_e64 v86, v86, v88, s[14:15]
	v_add_f32_e32 v81, 1.0, v83
	v_rcp_f32_e32 v83, v81
	v_add_f32_e32 v81, 1.0, v84
	v_rcp_f32_e32 v82, v81
	v_pk_fma_f32 v[70:71], v[40:41], v[32:33], v[70:71]
	v_pk_fma_f32 v[68:69], v[46:47], v[68:69], v[62:63]
	v_pk_fma_f32 v[70:71], v[44:45], v[86:87], v[70:71]
	v_pk_mul_f32 v[72:73], v[72:73], v[82:83]
	v_cndmask_b32_e64 v76, v75, v76, s[14:15]
	v_pk_mul_f32 v[70:71], v[70:71], v[72:73]
	v_cndmask_b32_e64 v72, v77, v78, s[14:15]
	v_cndmask_b32_e64 v77, v79, v80, s[14:15]
	v_pk_fma_f32 v[68:69], v[54:55], v[26:27], v[68:69]
	v_pk_fma_f32 v[66:67], v[34:35], v[66:67], v[50:51]
	v_pk_fma_f32 v[68:69], v[58:59], v[76:77], v[68:69]
	v_pk_fma_f32 v[66:67], v[38:39], v[30:31], v[66:67]
	v_mul_f32_e32 v73, 0xbdd2d3e7, v69
	v_fmaak_f32 v73, v69, v73, 0xc0135761
	v_mul_f32_e32 v73, v69, v73
	v_exp_f32_e32 v75, v73
	v_mul_f32_e32 v73, 0xbdd2d3e7, v68
	v_fmaak_f32 v73, v68, v73, 0xc0135761
	v_mul_f32_e32 v73, v68, v73
	v_exp_f32_e32 v76, v73
	v_cndmask_b32_e64 v73, v0, v74, s[14:15]
	v_add_f32_e32 v0, 1.0, v75
	v_rcp_f32_e32 v75, v0
	v_add_f32_e32 v0, 1.0, v76
	v_rcp_f32_e32 v74, v0
	v_pk_fma_f32 v[66:67], v[42:43], v[72:73], v[66:67]
	v_pk_mul_f32 v[68:69], v[68:69], v[74:75]
	s_nop 0
	v_pk_mul_f32 v[66:67], v[66:67], v[68:69]
	v_mov_b64_e32 v[68:69], s[24:25]
	v_mad_i64_i32 v[68:69], s[58:59], v180, s57, v[68:69]
	v_cvt_pk_bf16_f32 v66, v66, v67
	v_cvt_pk_bf16_f32 v67, v70, v71
	v_lshl_add_u64 v[68:69], v[214:215], 1, v[68:69]
	global_store_dwordx2 v[68:69], v[66:67], off offset:8
.LBB0_1174:
	s_or_b64 exec, exec, s[40:41]
	v_mov_b32_e32 v123, v122
	v_mov_b32_e32 v66, v122
	v_mov_b32_e32 v67, v122
	v_pk_mul_f32 v[68:69], v[8:9], v[66:67]
	v_pk_mul_f32 v[70:71], v[6:7], v[122:123]
	v_pk_mul_f32 v[6:7], v[4:5], v[66:67]
	v_pk_mul_f32 v[66:67], v[2:3], v[122:123]
	v_mov_b32_dpp v84, v12 row_ror:1 row_mask:0xf bank_mask:0xf
	v_mov_b32_dpp v2, v28 row_ror:1 row_mask:0xf bank_mask:0xf
	v_mov_b32_dpp v87, v13 row_ror:1 row_mask:0xf bank_mask:0xf
	v_mov_b32_dpp v3, v29 row_ror:1 row_mask:0xf bank_mask:0xf
	v_cndmask_b32_e64 v3, v87, v3, s[10:11]
	v_cndmask_b32_e64 v2, v84, v2, s[10:11]
	v_mov_b32_dpp v4, v12 row_ror:15 row_mask:0xf bank_mask:0xf
	v_mov_b32_dpp v8, v32 row_ror:1 row_mask:0xf bank_mask:0xf
	v_mov_b32_dpp v32, v6 row_ror:15 row_mask:0xf bank_mask:0xf
	v_mov_b32_dpp v5, v13 row_ror:15 row_mask:0xf bank_mask:0xf
	v_mov_b32_dpp v29, v7 row_ror:15 row_mask:0xf bank_mask:0xf
	v_pk_fma_f32 v[2:3], v[48:49], v[2:3], v[64:65]
	v_cndmask_b32_e64 v5, v5, v29, s[14:15]
	v_pk_fma_f32 v[2:3], v[56:57], v[12:13], v[2:3]
	v_cndmask_b32_e64 v4, v4, v32, s[14:15]
	v_pk_fma_f32 v[2:3], v[60:61], v[4:5], v[2:3]
	v_mov_b32_dpp v83, v20 row_ror:1 row_mask:0xf bank_mask:0xf
	v_mul_f32_e32 v4, 0xbdd2d3e7, v3
	v_fmaak_f32 v4, v3, v4, 0xc0135761
	v_mul_f32_e32 v4, v3, v4
	v_exp_f32_e32 v4, v4
	v_mov_b32_dpp v86, v21 row_ror:1 row_mask:0xf bank_mask:0xf
	v_mov_b32_dpp v9, v33 row_ror:1 row_mask:0xf bank_mask:0xf
	v_cndmask_b32_e64 v9, v86, v9, s[10:11]
	v_add_f32_e32 v4, 1.0, v4
	v_cndmask_b32_e64 v8, v83, v8, s[10:11]
	v_mov_b32_dpp v73, v10 row_ror:1 row_mask:0xf bank_mask:0xf
	v_mov_b32_dpp v26, v26 row_ror:1 row_mask:0xf bank_mask:0xf
; DI unsigned pack_bf16(float lo, float hi) { f32v2 f = {lo, hi}; bf16v2 b = __builtin_convertvector(f, bf16v2); return __builtin_bit_cast(unsigned, b); }
; DI float gelu_tanh(float x) { const float t = x * (1.5957691216057308f + 0.0713548162726009f * x * x); return x * __builtin_amdgcn_rcpf(1.0f + fexp2(-LOG2E * t)); }
; DI float rotr1(float v) { return __int_as_float(__builtin_amdgcn_mov_dpp(__float_as_int(v), 0x121, 0xf, 0xf, false)); }
; DI float rotl1(float v) { return __int_as_float(__builtin_amdgcn_mov_dpp(__float_as_int(v), 0x12f, 0xf, 0xf, false)); }
;     DI void operator()(const f32x4 (&acc)[2][2][4][2], const pg8::Unit& u, int wr, int wc, int fr, int fq, int ui) const {
;     ...
;                 for (int m = 0; m < 4; ++m) {
;                     float o[4];
; #pragma unroll
;                     for (int e = 0; e < 4; ++e) {
;                         const float pu_s = rotr1(U[m][e]), pg_s = rotr1(G[m][e]), nu_s = rotl1(U[m][e]), ng_s = rotl1(G[m][e]);
;                         const float pu_x = rotr1(U[m > 0 ? m - 1 : 0][e]), pg_x = rotr1(G[m > 0 ? m - 1 : 0][e]);
;                         const float nu_x = rotl1(U[m < 3 ? m + 1 : 3][e]), ng_x = rotl1(G[m < 3 ? m + 1 : 3][e]);
;                         const float pu = fr == 0 ? pu_x : pu_s, pg = fr == 0 ? pg_x : pg_s, nu = fr == 15 ? nu_x : nu_s, ng = fr == 15 ? ng_x : ng_s;
;                         const float yu = bu[e] + pu * wu[0][e] + U[m][e] * wu[1][e] + nu * wu[2][e];
;                         const float yg = bg[e] + pg * wg[0][e] + G[m][e] * wg[1][e] + ng * wg[2][e];
;                         o[e] = yu * gelu_tanh(yg);
;                     }
;                     const bool edge_row = (m == 0 && fr == 0) || (m == 3 && fr == 15);
;                     if (!edge_row) { u32x2 w; w.x = pack_bf16(o[0], o[1]); w.y = pack_bf16(o[2], o[3]); *(u32x2*)(O + (size_t)(rowb + m * 16 + fr) * FF + f0) = w; }
	v_mov_b32_dpp v78, v11 row_ror:1 row_mask:0xf bank_mask:0xf
	v_mov_b32_dpp v27, v27 row_ror:1 row_mask:0xf bank_mask:0xf
	v_rcp_f32_e32 v5, v4
	v_pk_fma_f32 v[8:9], v[36:37], v[8:9], v[52:53]
	v_mul_f32_e32 v4, 0xbdd2d3e7, v2
	v_mov_b32_dpp v85, v20 row_ror:15 row_mask:0xf bank_mask:0xf
	v_mov_b32_dpp v12, v21 row_ror:15 row_mask:0xf bank_mask:0xf
	v_fmaak_f32 v4, v2, v4, 0xc0135761
	v_pk_fma_f32 v[8:9], v[40:41], v[20:21], v[8:9]
	v_cndmask_b32_e64 v21, v78, v27, s[10:11]
	v_cndmask_b32_e64 v20, v73, v26, s[10:11]
	v_mov_b32_dpp v74, v10 row_ror:15 row_mask:0xf bank_mask:0xf
	v_mov_b32_dpp v76, v66 row_ror:15 row_mask:0xf bank_mask:0xf
	v_mov_b32_dpp v80, v11 row_ror:15 row_mask:0xf bank_mask:0xf
	v_mov_b32_dpp v82, v67 row_ror:15 row_mask:0xf bank_mask:0xf
	v_mul_f32_e32 v4, v2, v4
	v_pk_fma_f32 v[20:21], v[46:47], v[20:21], v[62:63]
	v_pk_fma_f32 v[10:11], v[54:55], v[10:11], v[20:21]
	v_cndmask_b32_e64 v21, v80, v82, s[14:15]
	v_cndmask_b32_e64 v20, v74, v76, s[14:15]
	v_exp_f32_e32 v4, v4
	v_pk_fma_f32 v[10:11], v[58:59], v[20:21], v[10:11]
	v_mov_b32_dpp v28, v68 row_ror:15 row_mask:0xf bank_mask:0xf
	v_mul_f32_e32 v20, 0xbdd2d3e7, v11
	v_fmaak_f32 v20, v11, v20, 0xc0135761
	v_mul_f32_e32 v20, v11, v20
	v_add_f32_e32 v4, 1.0, v4
	v_rcp_f32_e32 v4, v4
	v_exp_f32_e32 v20, v20
	v_mov_b32_dpp v33, v69 row_ror:15 row_mask:0xf bank_mask:0xf
	v_cndmask_b32_e64 v13, v12, v33, s[14:15]
	v_pk_mul_f32 v[2:3], v[2:3], v[4:5]
	v_add_f32_e32 v4, 1.0, v20
	v_rcp_f32_e32 v5, v4
	v_mul_f32_e32 v4, 0xbdd2d3e7, v10
	v_fmaak_f32 v4, v10, v4, 0xc0135761
	v_mul_f32_e32 v4, v10, v4
	v_exp_f32_e32 v4, v4
	v_cndmask_b32_e64 v12, v85, v28, s[14:15]
	v_mov_b32_dpp v72, v18 row_ror:1 row_mask:0xf bank_mask:0xf
	v_mov_b32_dpp v30, v30 row_ror:1 row_mask:0xf bank_mask:0xf
	v_add_f32_e32 v4, 1.0, v4
	v_mov_b32_dpp v77, v19 row_ror:1 row_mask:0xf bank_mask:0xf
	v_mov_b32_dpp v31, v31 row_ror:1 row_mask:0xf bank_mask:0xf
	v_pk_fma_f32 v[8:9], v[44:45], v[12:13], v[8:9]
	v_rcp_f32_e32 v4, v4
	v_pk_mul_f32 v[2:3], v[8:9], v[2:3]
	v_cndmask_b32_e64 v9, v77, v31, s[10:11]
	v_cndmask_b32_e64 v8, v72, v30, s[10:11]
	v_mov_b32_dpp v0, v18 row_ror:15 row_mask:0xf bank_mask:0xf
	v_mov_b32_dpp v75, v70 row_ror:15 row_mask:0xf bank_mask:0xf
	v_mov_b32_dpp v79, v19 row_ror:15 row_mask:0xf bank_mask:0xf
	v_mov_b32_dpp v81, v71 row_ror:15 row_mask:0xf bank_mask:0xf
	v_pk_fma_f32 v[8:9], v[34:35], v[8:9], v[50:51]
	v_cndmask_b32_e64 v13, v79, v81, s[14:15]
	v_pk_fma_f32 v[8:9], v[38:39], v[18:19], v[8:9]
	v_cndmask_b32_e64 v12, v0, v75, s[14:15]
	v_mov_b32_dpp v18, v6 row_ror:1 row_mask:0xf bank_mask:0xf
	v_mov_b32_dpp v19, v7 row_ror:1 row_mask:0xf bank_mask:0xf
	v_pk_fma_f32 v[8:9], v[42:43], v[12:13], v[8:9]
	v_pk_mul_f32 v[4:5], v[10:11], v[4:5]
	v_cndmask_b32_e64 v21, v19, v87, s[10:11]
	v_cndmask_b32_e64 v20, v18, v84, s[10:11]
	v_pk_mul_f32 v[4:5], v[8:9], v[4:5]
	v_mov_b32_dpp v8, v16 row_ror:15 row_mask:0xf bank_mask:0xf
	v_mov_b32_dpp v9, v17 row_ror:15 row_mask:0xf bank_mask:0xf
	v_pk_fma_f32 v[20:21], v[48:49], v[20:21], v[64:65]
	v_mov_b32_dpp v13, v68 row_ror:1 row_mask:0xf bank_mask:0xf
	v_pk_fma_f32 v[6:7], v[56:57], v[6:7], v[20:21]
	v_cndmask_b32_e64 v21, v29, v9, s[14:15]
	v_cndmask_b32_e64 v20, v32, v8, s[14:15]
	v_pk_fma_f32 v[26:27], v[60:61], v[20:21], v[6:7]
	v_cndmask_b32_e64 v30, v13, v83, s[10:11]
	v_mul_f32_e32 v6, 0xbdd2d3e7, v27
	v_fmaak_f32 v6, v27, v6, 0xc0135761
	v_mul_f32_e32 v6, v27, v6
	v_exp_f32_e32 v21, v6
	v_mov_b32_dpp v20, v69 row_ror:1 row_mask:0xf bank_mask:0xf
	v_cndmask_b32_e64 v31, v20, v86, s[10:11]
	v_mov_b32_dpp v10, v66 row_ror:1 row_mask:0xf bank_mask:0xf
	v_add_f32_e32 v21, 1.0, v21
	v_rcp_f32_e32 v29, v21
	v_mul_f32_e32 v21, 0xbdd2d3e7, v26
	v_fmaak_f32 v21, v26, v21, 0xc0135761
	v_mul_f32_e32 v21, v26, v21
	v_mov_b32_dpp v11, v67 row_ror:1 row_mask:0xf bank_mask:0xf
	v_pk_fma_f32 v[30:31], v[36:37], v[30:31], v[52:53]
	v_exp_f32_e32 v21, v21
	v_cvt_pk_bf16_f32 v4, v4, v5
	v_cvt_pk_bf16_f32 v5, v2, v3
	v_pk_fma_f32 v[30:31], v[40:41], v[68:69], v[30:31]
	v_cndmask_b32_e64 v69, v11, v78, s[10:11]
	v_cndmask_b32_e64 v68, v10, v73, s[10:11]
	global_store_dwordx2 v[98:99], v[4:5], off offset:8
	v_mov_b32_dpp v4, v14 row_ror:15 row_mask:0xf bank_mask:0xf
	v_mov_b32_dpp v5, v15 row_ror:15 row_mask:0xf bank_mask:0xf
	v_pk_fma_f32 v[68:69], v[46:47], v[68:69], v[62:63]
	v_mov_b32_dpp v6, v24 row_ror:15 row_mask:0xf bank_mask:0xf
	v_pk_fma_f32 v[66:67], v[54:55], v[66:67], v[68:69]
	v_cndmask_b32_e64 v69, v82, v5, s[14:15]
	v_cndmask_b32_e64 v68, v76, v4, s[14:15]
	v_add_f32_e32 v21, 1.0, v21
	v_pk_fma_f32 v[66:67], v[58:59], v[68:69], v[66:67]
	v_cndmask_b32_e64 v32, v28, v6, s[14:15]
	v_rcp_f32_e32 v28, v21
	v_mul_f32_e32 v21, 0xbdd2d3e7, v67
	v_fmaak_f32 v21, v67, v21, 0xc0135761
	v_mul_f32_e32 v21, v67, v21
	v_exp_f32_e32 v21, v21
	v_pk_mul_f32 v[26:27], v[26:27], v[28:29]
	v_mov_b32_dpp v7, v25 row_ror:15 row_mask:0xf bank_mask:0xf
	v_cndmask_b32_e64 v33, v33, v7, s[14:15]
	v_add_f32_e32 v21, 1.0, v21
	v_rcp_f32_e32 v29, v21
	v_mul_f32_e32 v21, 0xbdd2d3e7, v66
	v_fmaak_f32 v21, v66, v21, 0xc0135761
	v_mul_f32_e32 v21, v66, v21
	v_exp_f32_e32 v21, v21
	v_mov_b32_dpp v0, v70 row_ror:1 row_mask:0xf bank_mask:0xf
	v_mov_b32_dpp v12, v71 row_ror:1 row_mask:0xf bank_mask:0xf
	v_pk_fma_f32 v[30:31], v[44:45], v[32:33], v[30:31]
	v_add_f32_e32 v21, 1.0, v21
	v_rcp_f32_e32 v28, v21
	v_pk_mul_f32 v[26:27], v[30:31], v[26:27]
	v_cndmask_b32_e64 v31, v12, v77, s[10:11]
	v_cndmask_b32_e64 v30, v0, v72, s[10:11]
	v_mov_b32_dpp v2, v22 row_ror:15 row_mask:0xf bank_mask:0xf
	v_mov_b32_dpp v3, v23 row_ror:15 row_mask:0xf bank_mask:0xf
	v_pk_fma_f32 v[30:31], v[34:35], v[30:31], v[50:51]
	v_cndmask_b32_e64 v33, v81, v3, s[14:15]
	v_pk_fma_f32 v[30:31], v[38:39], v[70:71], v[30:31]
	v_cndmask_b32_e64 v32, v75, v2, s[14:15]
	v_pk_fma_f32 v[30:31], v[42:43], v[32:33], v[30:31]
	v_pk_mul_f32 v[28:29], v[66:67], v[28:29]
	v_mov_b32_dpp v21, v22 row_ror:1 row_mask:0xf bank_mask:0xf
	v_pk_mul_f32 v[28:29], v[30:31], v[28:29]
	v_mov_b32_dpp v30, v16 row_ror:1 row_mask:0xf bank_mask:0xf
	v_cvt_pk_bf16_f32 v28, v28, v29
	v_cvt_pk_bf16_f32 v29, v26, v27
	global_store_dwordx2 v[100:101], v[28:29], off offset:8
	v_mov_b32_dpp v26, v14 row_ror:1 row_mask:0xf bank_mask:0xf
	v_mov_b32_dpp v28, v23 row_ror:1 row_mask:0xf bank_mask:0xf
	v_mov_b32_dpp v27, v15 row_ror:1 row_mask:0xf bank_mask:0xf
	v_mov_b32_dpp v29, v24 row_ror:1 row_mask:0xf bank_mask:0xf
	v_mov_b32_dpp v32, v25 row_ror:1 row_mask:0xf bank_mask:0xf
	v_mov_b32_dpp v31, v17 row_ror:1 row_mask:0xf bank_mask:0xf
	s_and_saveexec_b64 s[40:41], s[12:13]
	s_cbranch_execz .LBB0_1176
; DI unsigned pack_bf16(float lo, float hi) { f32v2 f = {lo, hi}; bf16v2 b = __builtin_convertvector(f, bf16v2); return __builtin_bit_cast(unsigned, b); }
; DI float gelu_tanh(float x) { const float t = x * (1.5957691216057308f + 0.0713548162726009f * x * x); return x * __builtin_amdgcn_rcpf(1.0f + fexp2(-LOG2E * t)); }
; DI float rotr1(float v) { return __int_as_float(__builtin_amdgcn_mov_dpp(__float_as_int(v), 0x121, 0xf, 0xf, false)); }
; DI float rotl1(float v) { return __int_as_float(__builtin_amdgcn_mov_dpp(__float_as_int(v), 0x12f, 0xf, 0xf, false)); }
;     DI void operator()(const f32x4 (&acc)[2][2][4][2], const pg8::Unit& u, int wr, int wc, int fr, int fq, int ui) const {
;     ...
;                 for (int m = 0; m < 4; ++m) {
;                     float o[4];
; #pragma unroll
;                     for (int e = 0; e < 4; ++e) {
;                         const float pu_s = rotr1(U[m][e]), pg_s = rotr1(G[m][e]), nu_s = rotl1(U[m][e]), ng_s = rotl1(G[m][e]);
;                         const float pu_x = rotr1(U[m > 0 ? m - 1 : 0][e]), pg_x = rotr1(G[m > 0 ? m - 1 : 0][e]);
;                         const float nu_x = rotl1(U[m < 3 ? m + 1 : 3][e]), ng_x = rotl1(G[m < 3 ? m + 1 : 3][e]);
;                         const float pu = fr == 0 ? pu_x : pu_s, pg = fr == 0 ? pg_x : pg_s, nu = fr == 15 ? nu_x : nu_s, ng = fr == 15 ? ng_x : ng_s;
;                         const float yu = bu[e] + pu * wu[0][e] + U[m][e] * wu[1][e] + nu * wu[2][e];
;                         const float yg = bg[e] + pg * wg[0][e] + G[m][e] * wg[1][e] + ng * wg[2][e];
;                         o[e] = yu * gelu_tanh(yg);
;                     }
;                     const bool edge_row = (m == 0 && fr == 0) || (m == 3 && fr == 15);
;                     if (!edge_row) { u32x2 w; w.x = pack_bf16(o[0], o[1]); w.y = pack_bf16(o[2], o[3]); *(u32x2*)(O + (size_t)(rowb + m * 16 + fr) * FF + f0) = w; }
	v_cndmask_b32_e64 v19, v31, v19, s[10:11]
	v_cndmask_b32_e64 v18, v30, v18, s[10:11]
	v_pk_fma_f32 v[18:19], v[48:49], v[18:19], v[64:65]
	v_cndmask_b32_e64 v33, v32, v20, s[10:11]
	v_pk_fma_f32 v[16:17], v[56:57], v[16:17], v[18:19]
	v_cndmask_b32_e64 v32, v29, v13, s[10:11]
	v_pk_fma_f32 v[8:9], v[60:61], v[8:9], v[16:17]
	v_cndmask_b32_e64 v11, v27, v11, s[10:11]
	v_mul_f32_e32 v16, 0xbdd2d3e7, v9
	v_fmaak_f32 v16, v9, v16, 0xc0135761
	v_mul_f32_e32 v17, 0xbdd2d3e7, v8
	v_mul_f32_e32 v16, v9, v16
	v_fmaak_f32 v17, v8, v17, 0xc0135761
	v_mul_f32_e32 v17, v8, v17
	v_exp_f32_e32 v16, v16
	v_exp_f32_e32 v18, v17
	v_cndmask_b32_e64 v10, v26, v10, s[10:11]
	v_add_f32_e32 v13, 1.0, v16
	v_rcp_f32_e32 v17, v13
	v_add_f32_e32 v13, 1.0, v18
	v_rcp_f32_e32 v16, v13
	v_pk_fma_f32 v[18:19], v[36:37], v[32:33], v[52:53]
	v_pk_fma_f32 v[10:11], v[46:47], v[10:11], v[62:63]
	v_pk_fma_f32 v[18:19], v[40:41], v[24:25], v[18:19]
	v_pk_fma_f32 v[10:11], v[54:55], v[14:15], v[10:11]
	v_pk_fma_f32 v[6:7], v[44:45], v[6:7], v[18:19]
	v_pk_mul_f32 v[8:9], v[8:9], v[16:17]
	v_pk_fma_f32 v[4:5], v[58:59], v[4:5], v[10:11]
	v_pk_mul_f32 v[6:7], v[6:7], v[8:9]
	v_mul_f32_e32 v8, 0xbdd2d3e7, v5
	v_fmaak_f32 v8, v5, v8, 0xc0135761
	v_mul_f32_e32 v8, v5, v8
	v_exp_f32_e32 v10, v8
	v_mul_f32_e32 v8, 0xbdd2d3e7, v4
	v_fmaak_f32 v8, v4, v8, 0xc0135761
	v_mul_f32_e32 v8, v4, v8
	v_cndmask_b32_e64 v9, v28, v12, s[10:11]
	v_exp_f32_e32 v12, v8
	v_cndmask_b32_e64 v8, v21, v0, s[10:11]
	v_add_f32_e32 v0, 1.0, v10
	v_rcp_f32_e32 v11, v0
	v_add_f32_e32 v0, 1.0, v12
	v_rcp_f32_e32 v10, v0
	v_pk_fma_f32 v[8:9], v[34:35], v[8:9], v[50:51]
	v_pk_mul_f32 v[4:5], v[4:5], v[10:11]
	v_pk_fma_f32 v[8:9], v[38:39], v[22:23], v[8:9]
	s_nop 0
	v_pk_fma_f32 v[2:3], v[42:43], v[2:3], v[8:9]
	s_nop 0
	v_pk_mul_f32 v[2:3], v[2:3], v[4:5]
	v_mov_b64_e32 v[4:5], s[24:25]
	v_mad_i64_i32 v[4:5], s[58:59], v114, s57, v[4:5]
	v_cvt_pk_bf16_f32 v2, v2, v3
	v_cvt_pk_bf16_f32 v3, v6, v7
	v_lshl_add_u64 v[4:5], v[214:215], 1, v[4:5]
	global_store_dwordx2 v[4:5], v[2:3], off offset:8

; DI int otid() { int t = raw_tid(); asm volatile("" : "+v"(t)); return t; }
; DI float gelu_tanh(float x) { const float t = x * (1.5957691216057308f + 0.0713548162726009f * x * x); return x * __builtin_amdgcn_rcpf(1.0f + fexp2(-LOG2E * t)); }
; DI void ffn_fix_phase(const bf16_t* __restrict__ edge, bf16_t* __restrict__ Oo, const float* __restrict__ cw, const float* __restrict__ cb, int T) {
;     ...
;     for (int it = blockIdx.x * NTHR + otid(); it < total; it += gridDim.x * NTHR) {
;         const int fc = it % NCH, rs = it / NCH, side = rs & 1, blk = rs >> 1, f0 = fc * 8;
;         const int t = blk * 64 + (side ? 63 : 0), ts = t & (SEQ - 1);
;         const int cu = 256 * (f0 >> 7) + (f0 & 127);
;         const bf16_t* eb = edge + (size_t)blk * 4 * F2 + cu;
;         const bf16_t* pp = side ? eb + 2 * F2 : eb - F2;
;         const bf16_t* cp = side ? eb + 3 * F2 : eb;
;         const bf16_t* np = side ? eb + 4 * F2 : eb + F2;
;         const bool pz = (side == 0 && ts == 0), nz = (side == 1 && ts == SEQ - 1);
;         float pu[8], pg[8], cu_[8], cg_[8], nu[8], ng[8];
;         if (pz) {
; #pragma unroll
;             for (int e = 0; e < 8; ++e) { pu[e] = 0.f; pg[e] = 0.f; }
;         } else { unpack8(*(const u32x4*)pp, pu); unpack8(*(const u32x4*)(pp + 128), pg); }
;         unpack8(*(const u32x4*)cp, cu_); unpack8(*(const u32x4*)(cp + 128), cg_);
;         if (nz) {
; #pragma unroll
;             for (int e = 0; e < 8; ++e) { nu[e] = 0.f; ng[e] = 0.f; }
;         } else { unpack8(*(const u32x4*)np, nu); unpack8(*(const u32x4*)(np + 128), ng); }
;         float o[8];
; #pragma unroll
;         for (int e = 0; e < 8; ++e) {
;             const float yu = cb[f0 + e] + pu[e] * cw[f0 + e] + cu_[e] * cw[F2 + f0 + e] + nu[e] * cw[2 * F2 + f0 + e];
;             const float yg = cb[FF + f0 + e] + pg[e] * cw[FF + f0 + e] + cg_[e] * cw[F2 + FF + f0 + e] + ng[e] * cw[2 * F2 + FF + f0 + e];
;             o[e] = yu * gelu_tanh(yg);
.LBB0_1233:
	s_or_b64 exec, exec, s[4:5]
	v_add_u32_e32 v0, -6, v22
	v_readlane_b32 s6, v255, 0
	v_readlane_b32 s4, v254, 62
	v_readlane_b32 s7, v255, 1
	v_readlane_b32 s5, v254, 63
	v_lshlrev_b64 v[12:13], 2, v[0:1]
	v_lshl_add_u64 v[16:17], s[6:7], 0, v[12:13]
	v_lshl_add_u64 v[12:13], s[4:5], 0, v[12:13]
	global_load_dwordx2 v[16:17], v[16:17], off
	s_nop 0
	global_load_dwordx2 v[12:13], v[12:13], off
	v_ashrrev_i32_e32 v19, 31, v18
	v_or_b32_e32 v69, v15, v14
	s_waitcnt vmcnt(2)
	v_lshlrev_b32_e32 v14, 16, v2
	v_and_b32_e32 v15, 0xffff0000, v2
	v_lshlrev_b32_e32 v58, 16, v3
	v_and_b32_e32 v59, 0xffff0000, v3
	v_lshlrev_b64 v[2:3], 2, v[18:19]
	v_lshlrev_b32_e32 v64, 16, v6
	v_and_b32_e32 v65, 0xffff0000, v6
	v_lshlrev_b32_e32 v54, 16, v7
	v_and_b32_e32 v55, 0xffff0000, v7
	v_lshl_add_u64 v[6:7], s[4:5], 0, v[2:3]
	s_mov_b64 s[16:17], 0x5800
	v_lshlrev_b32_e32 v48, 16, v4
	v_and_b32_e32 v49, 0xffff0000, v4
	v_lshlrev_b32_e32 v36, 16, v5
	v_and_b32_e32 v37, 0xffff0000, v5
	v_lshl_add_u64 v[4:5], s[6:7], 0, v[2:3]
	v_lshl_add_u64 v[2:3], v[6:7], 0, s[16:17]
	s_mov_b64 s[16:17], 0xb000
	v_lshlrev_b32_e32 v44, 16, v8
	v_and_b32_e32 v45, 0xffff0000, v8
	v_lshlrev_b32_e32 v30, 16, v9
	v_and_b32_e32 v31, 0xffff0000, v9
	v_lshl_add_u64 v[8:9], v[6:7], 0, s[16:17]
	s_mov_b64 s[16:17], 0x8400
	v_lshl_add_u64 v[74:75], v[6:7], 0, s[16:17]
	s_mov_b64 s[16:17], 0xdc00
	v_lshl_add_u64 v[78:79], v[6:7], 0, s[16:17]
	s_mov_b32 s16, 0x8000
	v_mov_b32_e32 v23, v1
	v_add_u32_e32 v66, s20, v66
	v_add_u32_e32 v67, s0, v67
	v_add_u32_e32 v68, s1, v68
	s_waitcnt vmcnt(0)
	v_pk_fma_f32 v[16:17], v[10:11], v[12:13], v[16:17]
	v_add_co_u32_e32 v10, vcc, s16, v6
	s_mov_b32 s16, 0xd000
	s_nop 0
	v_addc_co_u32_e32 v11, vcc, 0, v7, vcc
	global_load_dwordx4 v[70:73], v[10:11], off offset:1024
	s_nop 0
	global_load_dwordx4 v[10:13], v[74:75], off offset:16
	s_waitcnt vmcnt(1)
	v_pk_fma_f32 v[70:71], v[70:71], v[14:15], v[16:17]
	v_add_co_u32_e32 v14, vcc, s16, v6
	s_movk_i32 s16, 0x5000
	s_nop 0
	v_addc_co_u32_e32 v15, vcc, 0, v7, vcc
	global_load_dwordx4 v[74:77], v[14:15], off offset:3072
	s_nop 0
	global_load_dwordx4 v[14:17], v[78:79], off offset:16
	s_waitcnt vmcnt(1)
	v_pk_fma_f32 v[60:61], v[60:61], v[74:75], v[70:71]
	global_load_dwordx2 v[4:5], v[4:5], off
	s_nop 0
	global_load_dwordx2 v[74:75], v[6:7], off
	v_mul_f32_e32 v0, 0xbdd2d3e7, v60
	v_fmaak_f32 v0, v60, v0, 0xc0135761
	v_mul_f32_e32 v0, v60, v0
	v_exp_f32_e32 v0, v0
	s_waitcnt vmcnt(0)
	v_pk_fma_f32 v[26:27], v[26:27], v[74:75], v[4:5]
	v_add_co_u32_e32 v4, vcc, s16, v6
	v_add_f32_e32 v0, 1.0, v0
	s_nop 0
	v_addc_co_u32_e32 v5, vcc, 0, v7, vcc
	global_load_dwordx4 v[78:81], v[4:5], off offset:2048
	s_nop 0
	global_load_dwordx4 v[2:5], v[2:3], off offset:16
	v_rcp_f32_e32 v70, v0
	v_mul_f32_e32 v0, 0xbdd2d3e7, v61
	v_fmaak_f32 v0, v61, v0, 0xc0135761
	v_mul_f32_e32 v0, v61, v0
	v_exp_f32_e32 v0, v0
	s_mov_b32 s16, 0xb000
	v_add_co_u32_e32 v6, vcc, s16, v6
	v_add_f32_e32 v0, 1.0, v0
	v_rcp_f32_e32 v71, v0
	v_addc_co_u32_e32 v7, vcc, 0, v7, vcc
	global_load_dwordx4 v[82:85], v[6:7], off
	s_nop 0
	global_load_dwordx4 v[6:9], v[8:9], off offset:16
	v_add_u32_e32 v0, -4, v22
	v_pk_mul_f32 v[60:61], v[60:61], v[70:71]
	v_cmp_le_i32_e32 vcc, s60, v66
	s_or_b64 s[14:15], vcc, s[14:15]
	s_waitcnt vmcnt(3)
	v_pk_fma_f32 v[26:27], v[78:79], v[64:65], v[26:27]
	v_lshlrev_b64 v[64:65], 2, v[0:1]
	v_lshl_add_u64 v[70:71], s[6:7], 0, v[64:65]
	v_lshl_add_u64 v[64:65], s[4:5], 0, v[64:65]
	global_load_dwordx2 v[70:71], v[70:71], off
	s_nop 0
	global_load_dwordx2 v[64:65], v[64:65], off
	s_waitcnt vmcnt(3)
	v_pk_fma_f32 v[26:27], v[62:63], v[82:83], v[26:27]
	s_nop 0
	v_pk_mul_f32 v[26:27], v[26:27], v[60:61]
	v_add_u32_e32 v60, 0xfffff4fc, v22
	v_ashrrev_i32_e32 v61, 31, v60
	v_lshlrev_b64 v[60:61], 2, v[60:61]
	v_lshl_add_u64 v[62:63], s[6:7], 0, v[60:61]
	v_lshl_add_u64 v[60:61], s[4:5], 0, v[60:61]
	s_waitcnt vmcnt(0)
; DI bf16x8 pack8(const float* v) { u32x4 w; w.x = pack_bf16(v[0], v[1]); w.y = pack_bf16(v[2], v[3]); w.z = pack_bf16(v[4], v[5]); w.w = pack_bf16(v[6], v[7]); return __builtin_bit_cast(bf16x8, w); }
; DI float gelu_tanh(float x) { const float t = x * (1.5957691216057308f + 0.0713548162726009f * x * x); return x * __builtin_amdgcn_rcpf(1.0f + fexp2(-LOG2E * t)); }
; DI void ffn_fix_phase(const bf16_t* __restrict__ edge, bf16_t* __restrict__ Oo, const float* __restrict__ cw, const float* __restrict__ cb, int T) {
;     ...
;         for (int e = 0; e < 8; ++e) {
;             const float yu = cb[f0 + e] + pu[e] * cw[f0 + e] + cu_[e] * cw[F2 + f0 + e] + nu[e] * cw[2 * F2 + f0 + e];
;             const float yg = cb[FF + f0 + e] + pg[e] * cw[FF + f0 + e] + cg_[e] * cw[F2 + FF + f0 + e] + ng[e] * cw[2 * F2 + FF + f0 + e];
;             o[e] = yu * gelu_tanh(yg);
;         }
;         *(bf16x8*)(Oo + (size_t)t * FF + f0) = pack8(o);
	v_pk_fma_f32 v[52:53], v[52:53], v[64:65], v[70:71]
	s_nop 0
	v_pk_fma_f32 v[52:53], v[72:73], v[58:59], v[52:53]
	global_load_dwordx2 v[58:59], v[62:63], off
	s_nop 0
	global_load_dwordx2 v[60:61], v[60:61], off
	v_pk_fma_f32 v[52:53], v[56:57], v[76:77], v[52:53]
	s_waitcnt vmcnt(0)
	v_pk_fma_f32 v[38:39], v[38:39], v[60:61], v[58:59]
	v_mul_f32_e32 v0, 0xbdd2d3e7, v52
	v_fmaak_f32 v0, v52, v0, 0xc0135761
	v_mul_f32_e32 v0, v52, v0
	v_exp_f32_e32 v0, v0
	v_pk_fma_f32 v[38:39], v[80:81], v[54:55], v[38:39]
	v_add_f32_e32 v0, 1.0, v0
	v_rcp_f32_e32 v56, v0
	v_mul_f32_e32 v0, 0xbdd2d3e7, v53
	v_fmaak_f32 v0, v53, v0, 0xc0135761
	v_mul_f32_e32 v0, v53, v0
	v_exp_f32_e32 v0, v0
	v_pk_fma_f32 v[38:39], v[50:51], v[84:85], v[38:39]
	v_add_f32_e32 v0, 1.0, v0
	v_rcp_f32_e32 v57, v0
	v_add_u32_e32 v0, -2, v22
	v_lshlrev_b64 v[54:55], 2, v[0:1]
	v_pk_mul_f32 v[50:51], v[52:53], v[56:57]
	v_lshl_add_u64 v[56:57], s[6:7], 0, v[54:55]
	v_lshl_add_u64 v[54:55], s[4:5], 0, v[54:55]
	global_load_dwordx2 v[56:57], v[56:57], off
	s_nop 0
	global_load_dwordx2 v[54:55], v[54:55], off
	v_pk_mul_f32 v[38:39], v[38:39], v[50:51]
	v_add_u32_e32 v50, 0xfffff4fe, v22
	v_ashrrev_i32_e32 v51, 31, v50
	v_lshlrev_b64 v[50:51], 2, v[50:51]
	v_lshl_add_u64 v[52:53], s[6:7], 0, v[50:51]
	v_lshl_add_u64 v[50:51], s[4:5], 0, v[50:51]
	s_waitcnt vmcnt(0)
	v_pk_fma_f32 v[42:43], v[42:43], v[54:55], v[56:57]
	s_nop 0
	v_pk_fma_f32 v[10:11], v[10:11], v[48:49], v[42:43]
	s_nop 0
	v_pk_fma_f32 v[10:11], v[46:47], v[14:15], v[10:11]
	global_load_dwordx2 v[42:43], v[52:53], off
	global_load_dwordx2 v[46:47], v[50:51], off
	v_mul_f32_e32 v0, 0xbdd2d3e7, v10
	v_fmaak_f32 v0, v10, v0, 0xc0135761
	v_mul_f32_e32 v0, v10, v0
	v_exp_f32_e32 v0, v0
	s_waitcnt vmcnt(0)
	v_pk_fma_f32 v[34:35], v[34:35], v[46:47], v[42:43]
	v_add_f32_e32 v0, 1.0, v0
	v_rcp_f32_e32 v14, v0
	v_mul_f32_e32 v0, 0xbdd2d3e7, v11
	v_fmaak_f32 v0, v11, v0, 0xc0135761
	v_mul_f32_e32 v0, v11, v0
	v_exp_f32_e32 v0, v0
	v_pk_fma_f32 v[2:3], v[2:3], v[44:45], v[34:35]
	v_add_f32_e32 v0, 1.0, v0
	v_rcp_f32_e32 v15, v0
	v_pk_fma_f32 v[2:3], v[40:41], v[6:7], v[2:3]
	v_pk_mul_f32 v[6:7], v[10:11], v[14:15]
	s_nop 0
	v_pk_mul_f32 v[2:3], v[2:3], v[6:7]
	v_add_u32_e32 v6, 0xfffff500, v22
	v_ashrrev_i32_e32 v7, 31, v6
	v_lshlrev_b64 v[6:7], 2, v[6:7]
	v_lshl_add_u64 v[14:15], s[6:7], 0, v[6:7]
	v_lshl_add_u64 v[34:35], s[4:5], 0, v[6:7]
	v_lshlrev_b64 v[6:7], 2, v[22:23]
	v_lshl_add_u64 v[10:11], s[6:7], 0, v[6:7]
	v_lshl_add_u64 v[6:7], s[4:5], 0, v[6:7]
	global_load_dwordx2 v[10:11], v[10:11], off
	s_nop 0
	global_load_dwordx2 v[6:7], v[6:7], off
	s_waitcnt vmcnt(0)
	v_pk_fma_f32 v[6:7], v[28:29], v[6:7], v[10:11]
	s_nop 0
	v_pk_fma_f32 v[6:7], v[12:13], v[36:37], v[6:7]
	global_load_dwordx2 v[12:13], v[14:15], off
	s_nop 0
	global_load_dwordx2 v[14:15], v[34:35], off
	v_pk_fma_f32 v[6:7], v[32:33], v[16:17], v[6:7]
	s_waitcnt vmcnt(0)
	v_pk_fma_f32 v[12:13], v[20:21], v[14:15], v[12:13]
	v_mul_f32_e32 v0, 0xbdd2d3e7, v6
	v_fmaak_f32 v0, v6, v0, 0xc0135761
	v_mul_f32_e32 v0, v6, v0
	v_exp_f32_e32 v0, v0
	v_pk_fma_f32 v[4:5], v[4:5], v[30:31], v[12:13]
	v_add_f32_e32 v0, 1.0, v0
	v_rcp_f32_e32 v10, v0
	v_mul_f32_e32 v0, 0xbdd2d3e7, v7
	v_fmaak_f32 v0, v7, v0, 0xc0135761
	v_mul_f32_e32 v0, v7, v0
	v_exp_f32_e32 v0, v0
	v_pk_fma_f32 v[4:5], v[24:25], v[8:9], v[4:5]
	v_add_f32_e32 v0, 1.0, v0
	v_rcp_f32_e32 v11, v0
	s_nop 0
	v_pk_mul_f32 v[6:7], v[6:7], v[10:11]
	s_nop 0
	v_pk_mul_f32 v[8:9], v[4:5], v[6:7]
	v_cvt_pk_bf16_f32 v6, v2, v3
	v_mov_b64_e32 v[2:3], s[12:13]
	v_mad_i64_i32 v[2:3], s[4:5], v69, s57, v[2:3]
	v_cvt_pk_bf16_f32 v4, v26, v27
	v_cvt_pk_bf16_f32 v5, v38, v39
	v_cvt_pk_bf16_f32 v7, v8, v9
	v_lshl_add_u64 v[2:3], v[18:19], 1, v[2:3]
	global_store_dwordx4 v[2:3], v[4:7], off
	s_andn2_b64 exec, exec, s[14:15]
	s_cbranch_execz .LBB0_1238
